# xor-16/xor-32 lane reductions via v_permlane16/32_swap instead of ds_bpermute (68 sites: residual epilogues, prologue, final norm)
# baseline (speedup 1.0000x reference)
; __device__ __forceinline__ unsigned cvt_pk_bf16(float lo, float hi) { const f32x2 v = {lo, hi}; return __builtin_bit_cast(unsigned, __builtin_convertvector(v, bfx2_t)); }
; __device__ __forceinline__ float bflo(unsigned w) { return __uint_as_float(w << 16); }
; __device__ __forceinline__ float bfhi(unsigned w) { return __uint_as_float(w & 0xffff0000u); }
; __device__ __forceinline__ unsigned lo_pack4(float a, float b, float c, float d) { int p = __builtin_amdgcn_cvt_pk_fp8_f32(a * 512.0f, b * 512.0f, 0, false); return (unsigned)__builtin_amdgcn_cvt_pk_fp8_f32(c * 512.0f, d * 512.0f, p, true); }
; __device__ void prologue(const Params& P, LAS unsigned char* lds) {
;     ...
;         for (int row = blockIdx.x * 8 + wave; row < TT; row += G * 8) {
;             float ss = 0.f;
; #pragma unroll
;             for (int q = 0; q < 4; ++q) { const f32x4 v = *(const f32x4*)(x + (size_t)row * DM + q * 256 + lane * 4);
;                 ss += (v[0] * v[0] + v[1] * v[1]) + (v[2] * v[2] + v[3] * v[3]);
;                 u32x2 w; w.x = cvt_pk_bf16(v[0], v[1]); w.y = cvt_pk_bf16(v[2], v[3]); *(u32x2*)(hb + (size_t)row * DM + q * 256 + lane * 4) = w;
;                 *(unsigned*)(lo + (size_t)row * DM + q * 256 + lane * 4) = lo_pack4(v[0] - bflo(w.x), v[1] - bfhi(w.x), v[2] - bflo(w.y), v[3] - bfhi(w.y)); }
; #pragma unroll
;             for (int o = 32; o >= 1; o >>= 1) ss += __shfl_xor(ss, o);
;             if (lane < 16) ssp[(size_t)lane * TT + row] = (lane == 0) ? ss : 0.f;
.LBB0_10:
	s_waitcnt lgkmcnt(0)
	global_load_dwordx4 v[18:21], v[6:7], off offset:-3072
	global_load_dwordx4 v[22:25], v[6:7], off offset:-2048
	global_load_dwordx4 v[26:29], v[6:7], off offset:-1024
	global_load_dwordx4 v[30:33], v[6:7], off
	s_load_dwordx8 s[24:31], s[0:1], 0xc0
	s_waitcnt lgkmcnt(0)
	v_lshl_add_u64 v[34:35], s[30:31], 0, v[8:9]
	s_waitcnt vmcnt(3)
	v_mul_f32_e32 v17, v19, v19
	v_mul_f32_e32 v36, v21, v21
	v_fmac_f32_e32 v17, v18, v18
	v_fmac_f32_e32 v36, v20, v20
	v_add_f32_e32 v17, v17, v36
	v_cvt_pk_bf16_f32 v18, v18, v19
	v_cvt_pk_bf16_f32 v19, v20, v21
	global_store_dwordx2 v[34:35], v[18:19], off
	s_waitcnt vmcnt(3)
	v_mul_f32_e32 v38, v23, v23
	v_mul_f32_e32 v36, v25, v25
	v_fmac_f32_e32 v38, v22, v22
	v_fmac_f32_e32 v36, v24, v24
	v_add_f32_e32 v38, v38, v36
	v_add_f32_e32 v17, v17, v38
	v_cvt_pk_bf16_f32 v22, v22, v23
	v_cvt_pk_bf16_f32 v23, v24, v25
	global_store_dwordx2 v[34:35], v[22:23], off offset:512
	s_waitcnt vmcnt(3)
	v_mul_f32_e32 v38, v27, v27
	v_mul_f32_e32 v36, v29, v29
	v_fmac_f32_e32 v38, v26, v26
	v_fmac_f32_e32 v36, v28, v28
	v_add_f32_e32 v38, v38, v36
	v_add_f32_e32 v17, v17, v38
	v_cvt_pk_bf16_f32 v26, v26, v27
	v_cvt_pk_bf16_f32 v27, v28, v29
	global_store_dwordx2 v[34:35], v[26:27], off offset:1024
	s_waitcnt vmcnt(3)
	v_mul_f32_e32 v38, v31, v31
	v_mul_f32_e32 v36, v33, v33
	v_fmac_f32_e32 v38, v30, v30
	v_fmac_f32_e32 v36, v32, v32
	v_add_f32_e32 v38, v38, v36
	v_add_f32_e32 v17, v17, v38
	v_cvt_pk_bf16_f32 v30, v30, v31
	v_cvt_pk_bf16_f32 v31, v32, v33
	global_store_dwordx2 v[34:35], v[30:31], off offset:1536
	v_mov_b32_e32 v18, v17
	s_nop 1
	v_permlane32_swap_b32_e32 v17, v18
	s_waitcnt lgkmcnt(0)
	v_add_f32_e32 v17, v17, v18
	v_mov_b32_e32 v18, v17
	s_nop 1
	v_permlane16_swap_b32_e32 v17, v18
	s_waitcnt lgkmcnt(0)
	v_add_f32_e32 v17, v17, v18
	ds_bpermute_b32 v18, v12, v17
	s_waitcnt lgkmcnt(0)
	v_add_f32_e32 v17, v17, v18
	ds_bpermute_b32 v18, v13, v17
	s_waitcnt lgkmcnt(0)
	v_add_f32_e32 v17, v17, v18
	ds_bpermute_b32 v18, v14, v17
	s_waitcnt lgkmcnt(0)
	v_add_f32_e32 v17, v17, v18
	ds_bpermute_b32 v18, v15, v17
	s_and_saveexec_b64 s[8:9], vcc
	s_cbranch_execz .LBB0_9
	s_load_dwordx8 s[24:31], s[0:1], 0xc0
	s_waitcnt lgkmcnt(0)
	v_add_f32_e32 v17, v17, v18
	v_cndmask_b32_e64 v17, 0, v17, s[6:7]
	v_lshl_add_u64 v[18:19], s[30:31], 0, v[2:3]
	global_store_dword v[18:19], v17, off
	s_branch .LBB0_9

; __device__ __forceinline__ float bflo(unsigned w) { return __uint_as_float(w << 16); }
;     template <int NM> __device__ __forceinline__ void round(const AccT& acc, const Unit& u, int ai, int m0, int wr, int wc, int fr, int fq) const {
;     ...
;         for (int mm = 0; mm < NM; ++mm) {
;             const int rl = ai * 128 + wr * 64 + (m0 + mm) * 16 + fr;
;             const size_t off = (size_t)(u.pm * 256 + rl) * DM + u.pn * 256 + wc * 32 + 8 * fq;
; #pragma unroll
;             for (int bj = 0; bj < 2; ++bj) {
;                 hv[mm][bj] = *GP(const u32x4, hin + off + bj * 128); lv[mm][bj] = (u32x2){0u, 0u};
;                 if (MODE == 1) pv[mm][bj] = *GP(const u32x4, proj + off + bj * 128);
;             }
;         }
; #pragma unroll
;         for (int mm = 0; mm < NM; ++mm) {
;             const int m = m0 + mm;
;             const int rl = ai * 128 + wr * 64 + m * 16 + fr; const int row = u.pm * 256 + rl;
;             const size_t off = (size_t)row * DM + u.pn * 256 + wc * 32 + 8 * fq;
;             float r = 1.f; if (MODE == 1) r = rs[((u.pm >> 3) & 3) * 256 + rl];
;             float ss = 0.f;
; #pragma unroll
;             for (int bj = 0; bj < 2; ++bj) {
;                 f32x4 d0, d1;
;                 if (MODE == 0) { d0 = acc[ai][bj][m][0] * alpha; d1 = acc[ai][bj][m][1] * alpha; }
;                 else {
;                     const u32x4 p = pv[mm][bj];
;                     const f32x4 a0 = acc[ai][bj][m][0] * r, a1 = acc[ai][bj][m][1] * r;
;                     d0 = (f32x4){fsigmoid(a0[0]) * bflo(p.x), fsigmoid(a0[1]) * bfhi(p.x), fsigmoid(a0[2]) * bflo(p.y), fsigmoid(a0[3]) * bfhi(p.y)};
;                     d1 = (f32x4){fsigmoid(a1[0]) * bflo(p.z), fsigmoid(a1[1]) * bfhi(p.z), fsigmoid(a1[2]) * bflo(p.w), fsigmoid(a1[3]) * bfhi(p.w)};
;                 }
;                 const u32x4 H = hv[mm][bj]; const u32x2 L = lv[mm][bj];
;                 const f32x4 o0 = ((f32x4){bflo(H.x), bfhi(H.x), bflo(H.y), bfhi(H.y)} + lo_unpack4(L.x)) + d0;
;                 const f32x4 o1 = ((f32x4){bflo(H.z), bfhi(H.z), bflo(H.w), bfhi(H.w)} + lo_unpack4(L.y)) + d1;
;                 u32x4 w; w.x = cvt_pk_bf16(o0[0], o0[1]); w.y = cvt_pk_bf16(o0[2], o0[3]); w.z = cvt_pk_bf16(o1[0], o1[1]); w.w = cvt_pk_bf16(o1[2], o1[3]);
;                 u32x2 wl; wl.x = lo_pack4(o0[0] - bflo(w.x), o0[1] - bfhi(w.x), o0[2] - bflo(w.y), o0[3] - bfhi(w.y));
.LBB0_202:
	s_lshl_b32 s20, s62, 8
	s_lshl_b32 s52, s36, 8
	v_add_u32_e32 v194, s20, v203
	s_ashr_i32 s53, s52, 31
	s_lshl_b64 s[12:13], s[52:53], 1
	v_ashrrev_i32_e32 v195, 31, v194
	v_lshl_add_u64 v[148:149], v[130:131], 0, s[12:13]
	v_lshlrev_b64 v[216:217], 11, v[194:195]
	s_waitcnt lgkmcnt(0)
	v_lshl_add_u64 v[0:1], v[148:149], 0, v[216:217]
	global_load_dwordx4 v[212:215], v[0:1], off
	global_load_dwordx4 v[24:27], v[0:1], off offset:256
	v_or_b32_e32 v0, 16, v194
	v_ashrrev_i32_e32 v1, 31, v0
	v_lshlrev_b64 v[0:1], 11, v[0:1]
	v_lshl_add_u64 v[0:1], v[148:149], 0, v[0:1]
	global_load_dwordx4 v[20:23], v[0:1], off
	global_load_dwordx4 v[16:19], v[0:1], off offset:256
	v_or_b32_e32 v0, 32, v194
	v_ashrrev_i32_e32 v1, 31, v0
	v_lshlrev_b64 v[0:1], 11, v[0:1]
	v_lshl_add_u64 v[0:1], v[148:149], 0, v[0:1]
	global_load_dwordx4 v[12:15], v[0:1], off
	global_load_dwordx4 v[8:11], v[0:1], off offset:256
	v_or_b32_e32 v0, 48, v194
	v_ashrrev_i32_e32 v1, 31, v0
	v_lshlrev_b64 v[0:1], 11, v[0:1]
	v_lshl_add_u64 v[0:1], v[148:149], 0, v[0:1]
	global_load_dwordx4 v[4:7], v[0:1], off
	s_nop 0
	global_load_dwordx4 v[0:3], v[0:1], off offset:256
	v_and_b32_e32 v196, 64, v163
	v_xor_b32_e32 v168, 16, v163
	v_add_u32_e32 v196, 64, v196
	v_cmp_lt_i32_e32 vcc, v168, v196
	v_cvt_pk_f32_fp8_sdwa v[198:199], s63 src0_sel:WORD_1
	v_lshl_add_u64 v[216:217], s[14:15], 0, v[216:217]
	v_cndmask_b32_e32 v168, v163, v168, vcc
	v_lshlrev_b32_e32 v207, 2, v168
	v_xor_b32_e32 v168, 32, v163
	v_cmp_lt_i32_e32 vcc, v168, v196
	v_cvt_pk_f32_fp8_e32 v[196:197], 0
	v_lshl_add_u64 v[216:217], v[216:217], 0, s[12:13]
	v_cndmask_b32_e32 v168, v163, v168, vcc
	s_lshl_b32 s62, s78, 1
	v_lshlrev_b32_e32 v211, 2, v168
	v_lshl_add_u64 v[216:217], v[216:217], 0, s[62:63]
	v_lshlrev_b32_e32 v168, 1, v128
	v_lshl_add_u64 v[216:217], v[216:217], 0, v[168:169]
	s_waitcnt vmcnt(0)
	v_lshlrev_b32_e32 v218, 16, v212
	v_and_b32_e32 v219, 0xffff0000, v212
	v_lshlrev_b32_e32 v212, 16, v213
	v_and_b32_e32 v213, 0xffff0000, v213
	v_pk_fma_f32 v[212:213], v[198:199], s[34:35], v[212:213] op_sel_hi:[1,0,1]
	v_pk_fma_f32 v[218:219], v[196:197], s[34:35], v[218:219] op_sel_hi:[1,0,1]
	v_pk_add_f32 v[212:213], v[154:155], v[212:213]
	v_lshlrev_b32_e32 v154, 16, v214
	v_and_b32_e32 v155, 0xffff0000, v214
	v_lshlrev_b32_e32 v214, 16, v215
	v_and_b32_e32 v215, 0xffff0000, v215
	v_pk_fma_f32 v[154:155], v[196:197], s[34:35], v[154:155] op_sel_hi:[1,0,1]
	v_pk_fma_f32 v[214:215], v[198:199], s[34:35], v[214:215] op_sel_hi:[1,0,1]
	v_pk_add_f32 v[192:193], v[192:193], v[218:219]
	v_pk_add_f32 v[214:215], v[156:157], v[214:215]
	v_pk_add_f32 v[158:159], v[158:159], v[154:155]
	v_cvt_pk_bf16_f32 v154, v192, v193
	v_cvt_pk_bf16_f32 v155, v212, v213
	v_cvt_pk_bf16_f32 v156, v158, v159
	v_cvt_pk_bf16_f32 v157, v214, v215
	global_store_dwordx4 v[216:217], v[154:157], off
	s_nop 1
	v_mul_f32_e32 v154, v193, v193
	v_mul_f32_e32 v155, v213, v213
	v_fmac_f32_e32 v154, v192, v192
	v_fmac_f32_e32 v155, v212, v212
	v_add_f32_e32 v154, v154, v155
	v_mul_f32_e32 v155, v159, v159
	v_fmac_f32_e32 v155, v158, v158
	v_add_f32_e32 v154, v155, v154
	v_mul_f32_e32 v155, v215, v215
	v_fmac_f32_e32 v155, v214, v214
	v_add_f32_e32 v156, v155, v154
	v_lshlrev_b32_e32 v154, 16, v24
	v_and_b32_e32 v155, 0xffff0000, v24
	v_lshlrev_b32_e32 v24, 16, v25
	v_and_b32_e32 v25, 0xffff0000, v25
	v_pk_fma_f32 v[24:25], v[198:199], s[34:35], v[24:25] op_sel_hi:[1,0,1]
	v_pk_fma_f32 v[154:155], v[196:197], s[34:35], v[154:155] op_sel_hi:[1,0,1]
	v_pk_add_f32 v[150:151], v[150:151], v[24:25]
	v_lshlrev_b32_e32 v24, 16, v26
	v_and_b32_e32 v25, 0xffff0000, v26
	v_lshlrev_b32_e32 v26, 16, v27
	v_and_b32_e32 v27, 0xffff0000, v27
	v_pk_fma_f32 v[24:25], v[196:197], s[34:35], v[24:25] op_sel_hi:[1,0,1]
	v_pk_fma_f32 v[26:27], v[198:199], s[34:35], v[26:27] op_sel_hi:[1,0,1]
	v_pk_add_f32 v[152:153], v[152:153], v[154:155]
	v_pk_add_f32 v[126:127], v[126:127], v[26:27]
	v_pk_add_f32 v[124:125], v[124:125], v[24:25]
	v_cvt_pk_bf16_f32 v24, v152, v153
	v_cvt_pk_bf16_f32 v25, v150, v151
	v_cvt_pk_bf16_f32 v26, v124, v125
	v_cvt_pk_bf16_f32 v27, v126, v127
	global_store_dwordx4 v[216:217], v[24:27], off offset:256
	s_nop 1
	v_mul_f32_e32 v24, v153, v153
	v_mul_f32_e32 v25, v151, v151
	v_fmac_f32_e32 v24, v152, v152
	v_fmac_f32_e32 v25, v150, v150
	v_add_f32_e32 v24, v24, v25
	v_mul_f32_e32 v25, v125, v125
	v_fmac_f32_e32 v25, v124, v124
	v_add_f32_e32 v24, v25, v24
	v_mul_f32_e32 v25, v127, v127
	v_fmac_f32_e32 v25, v126, v126
	v_add_f32_e32 v24, v25, v24
	v_add_f32_e32 v24, v156, v24
	v_mov_b32_e32 v25, v24
	s_nop 1
	v_permlane16_swap_b32_e32 v24, v25
	s_waitcnt lgkmcnt(0)
	v_add_f32_e32 v24, v24, v25
	v_mov_b32_e32 v25, v24
	s_nop 1
	v_permlane32_swap_b32_e32 v24, v25
	s_and_saveexec_b64 s[12:13], s[42:43]
	s_cbranch_execz .LBB0_204
	s_lshl_b32 s21, s36, 2
	s_or_b32 s22, s21, s76
	s_ashr_i32 s23, s22, 31
	s_lshl_b64 s[22:23], s[22:23], 18
	s_add_u32 s22, s74, s22
	s_addc_u32 s23, s75, s23
	s_waitcnt lgkmcnt(0)
	v_add_f32_e32 v26, v24, v25
	v_lshl_add_u64 v[24:25], v[194:195], 2, s[22:23]
	global_store_dword v[24:25], v26, off
; __device__ __forceinline__ float bflo(unsigned w) { return __uint_as_float(w << 16); }
;     template <int NM> __device__ __forceinline__ void round(const AccT& acc, const Unit& u, int ai, int m0, int wr, int wc, int fr, int fq) const {
;     ...
;         for (int mm = 0; mm < NM; ++mm) {
;             const int m = m0 + mm;
;             const int rl = ai * 128 + wr * 64 + m * 16 + fr; const int row = u.pm * 256 + rl;
;             const size_t off = (size_t)row * DM + u.pn * 256 + wc * 32 + 8 * fq;
;             float r = 1.f; if (MODE == 1) r = rs[((u.pm >> 3) & 3) * 256 + rl];
;             float ss = 0.f;
; #pragma unroll
;             for (int bj = 0; bj < 2; ++bj) {
;                 f32x4 d0, d1;
;                 if (MODE == 0) { d0 = acc[ai][bj][m][0] * alpha; d1 = acc[ai][bj][m][1] * alpha; }
;                 else {
;                     const u32x4 p = pv[mm][bj];
;                     const f32x4 a0 = acc[ai][bj][m][0] * r, a1 = acc[ai][bj][m][1] * r;
;                     d0 = (f32x4){fsigmoid(a0[0]) * bflo(p.x), fsigmoid(a0[1]) * bfhi(p.x), fsigmoid(a0[2]) * bflo(p.y), fsigmoid(a0[3]) * bfhi(p.y)};
;                     d1 = (f32x4){fsigmoid(a1[0]) * bflo(p.z), fsigmoid(a1[1]) * bfhi(p.z), fsigmoid(a1[2]) * bflo(p.w), fsigmoid(a1[3]) * bfhi(p.w)};
;                 }
;                 const u32x4 H = hv[mm][bj]; const u32x2 L = lv[mm][bj];
;                 const f32x4 o0 = ((f32x4){bflo(H.x), bfhi(H.x), bflo(H.y), bfhi(H.y)} + lo_unpack4(L.x)) + d0;
;                 const f32x4 o1 = ((f32x4){bflo(H.z), bfhi(H.z), bflo(H.w), bfhi(H.w)} + lo_unpack4(L.y)) + d1;
;                 u32x4 w; w.x = cvt_pk_bf16(o0[0], o0[1]); w.y = cvt_pk_bf16(o0[2], o0[3]); w.z = cvt_pk_bf16(o1[0], o1[1]); w.w = cvt_pk_bf16(o1[2], o1[3]);
;                 u32x2 wl; wl.x = lo_pack4(o0[0] - bflo(w.x), o0[1] - bfhi(w.x), o0[2] - bflo(w.y), o0[3] - bfhi(w.y));
;                 wl.y = lo_pack4(o1[0] - bflo(w.z), o1[1] - bfhi(w.z), o1[2] - bflo(w.w), o1[3] - bfhi(w.w));
;                 *GP(u32x4, hout + off + bj * 128) = w; (void)wl;
;                 ss += (o0[0] * o0[0] + o0[1] * o0[1]) + (o0[2] * o0[2] + o0[3] * o0[3]) + (o1[0] * o1[0] + o1[1] * o1[1]) + (o1[2] * o1[2] + o1[3] * o1[3]);
;             }
;             ss += __shfl_xor(ss, 16); ss += __shfl_xor(ss, 32);
;             if (fq == 0) *GP(float, ssp + (size_t)(u.pn * 4 + wc) * TT + row) = ss;
.LBB0_204:
	s_or_b64 exec, exec, s[12:13]
	v_pk_mul_f32 v[124:125], v[198:199], s[34:35] op_sel_hi:[1,0]
	v_lshlrev_b32_e32 v150, 16, v20
	v_and_b32_e32 v151, 0xffff0000, v20
	v_lshlrev_b32_e32 v20, 16, v21
	v_and_b32_e32 v21, 0xffff0000, v21
	v_pk_mul_f32 v[126:127], v[196:197], s[34:35] op_sel_hi:[1,0]
	v_pk_add_f32 v[20:21], v[124:125], v[20:21]
	v_pk_add_f32 v[150:151], v[126:127], v[150:151]
	v_pk_add_f32 v[146:147], v[146:147], v[20:21]
	v_lshlrev_b32_e32 v20, 16, v22
	v_and_b32_e32 v21, 0xffff0000, v22
	v_pk_add_f32 v[144:145], v[144:145], v[150:151]
	v_pk_add_f32 v[20:21], v[126:127], v[20:21]
	v_lshlrev_b32_e32 v22, 16, v23
	v_and_b32_e32 v23, 0xffff0000, v23
	v_pk_add_f32 v[140:141], v[140:141], v[20:21]
	v_cvt_pk_bf16_f32 v20, v144, v145
	v_mul_f32_e32 v145, v145, v145
	v_pk_add_f32 v[22:23], v[124:125], v[22:23]
	v_fmac_f32_e32 v145, v144, v144
	v_mul_f32_e32 v144, v147, v147
	v_pk_add_f32 v[142:143], v[142:143], v[22:23]
	v_cvt_pk_bf16_f32 v22, v140, v141
	v_fmac_f32_e32 v144, v146, v146
	v_mul_f32_e32 v141, v141, v141
	v_add_f32_e32 v144, v145, v144
	v_fmac_f32_e32 v141, v140, v140
	v_add_f32_e32 v140, v141, v144
	v_mul_f32_e32 v141, v143, v143
	v_fmac_f32_e32 v141, v142, v142
	v_cvt_pk_bf16_f32 v23, v142, v143
	v_add_f32_e32 v142, v141, v140
	v_lshlrev_b32_e32 v140, 16, v16
	v_and_b32_e32 v141, 0xffff0000, v16
	v_lshlrev_b32_e32 v16, 16, v17
	v_and_b32_e32 v17, 0xffff0000, v17
	v_pk_add_f32 v[140:141], v[126:127], v[140:141]
	v_pk_add_f32 v[16:17], v[124:125], v[16:17]
	s_or_b32 s21, s20, 16
	v_pk_add_f32 v[138:139], v[138:139], v[16:17]
	v_pk_add_f32 v[16:17], v[136:137], v[140:141]
	v_lshlrev_b32_e32 v136, 16, v18
	v_and_b32_e32 v137, 0xffff0000, v18
	v_lshlrev_b32_e32 v18, 16, v19
	v_and_b32_e32 v19, 0xffff0000, v19
	v_pk_add_f32 v[18:19], v[124:125], v[18:19]
	v_pk_add_f32 v[136:137], v[126:127], v[136:137]
	v_pk_add_f32 v[134:135], v[134:135], v[18:19]
	v_mul_f32_e32 v18, v17, v17
	v_mul_f32_e32 v19, v139, v139
	v_pk_add_f32 v[132:133], v[132:133], v[136:137]
	v_fmac_f32_e32 v18, v16, v16
	v_fmac_f32_e32 v19, v138, v138
	v_add_f32_e32 v18, v18, v19
	v_mul_f32_e32 v19, v133, v133
	v_fmac_f32_e32 v19, v132, v132
	v_add_f32_e32 v18, v19, v18
	v_mul_f32_e32 v19, v135, v135
	v_fmac_f32_e32 v19, v134, v134
	v_add_f32_e32 v18, v19, v18
	v_add_u32_e32 v24, s21, v203
	v_add_f32_e32 v136, v142, v18
	s_waitcnt lgkmcnt(0)
	v_ashrrev_i32_e32 v25, 31, v24
	v_mov_b32_e32 v137, v136
	s_nop 1
	v_permlane16_swap_b32_e32 v136, v137
	v_lshlrev_b64 v[26:27], 11, v[24:25]
	v_lshl_add_u64 v[26:27], s[14:15], 0, v[26:27]
	v_lshl_add_u64 v[26:27], s[52:53], 1, v[26:27]
	v_lshl_add_u64 v[18:19], v[26:27], 0, s[62:63]
	v_lshl_add_u64 v[26:27], v[18:19], 0, v[168:169]
	v_cvt_pk_bf16_f32 v18, v16, v17
	s_waitcnt lgkmcnt(0)
	v_add_f32_e32 v16, v136, v137
	v_mov_b32_e32 v17, v16
	s_nop 1
	v_permlane32_swap_b32_e32 v16, v17
	v_cvt_pk_bf16_f32 v21, v146, v147
	global_store_dwordx4 v[26:27], v[20:23], off
	v_cvt_pk_bf16_f32 v19, v138, v139
	s_nop 0
	v_cvt_pk_bf16_f32 v20, v132, v133
	v_cvt_pk_bf16_f32 v21, v134, v135
	global_store_dwordx4 v[26:27], v[18:21], off offset:256
	s_and_saveexec_b64 s[12:13], s[42:43]
	s_cbranch_execz .LBB0_206
	s_lshl_b32 s22, s36, 2
	s_or_b32 s22, s22, s76
	s_ashr_i32 s23, s22, 31
	s_lshl_b64 s[22:23], s[22:23], 18
	s_add_u32 s22, s74, s22
	s_addc_u32 s23, s75, s23
	s_waitcnt lgkmcnt(0)
	v_add_f32_e32 v18, v16, v17
	v_lshl_add_u64 v[16:17], v[24:25], 2, s[22:23]
	global_store_dword v[16:17], v18, off
.LBB0_206:
	s_or_b64 exec, exec, s[12:13]
	v_lshlrev_b32_e32 v20, 16, v12
	v_and_b32_e32 v21, 0xffff0000, v12
	v_lshlrev_b32_e32 v12, 16, v13
	v_and_b32_e32 v13, 0xffff0000, v13
	v_pk_add_f32 v[12:13], v[124:125], v[12:13]
	v_pk_add_f32 v[20:21], v[126:127], v[20:21]
	v_pk_add_f32 v[22:23], v[122:123], v[12:13]
	v_lshlrev_b32_e32 v12, 16, v14
	v_and_b32_e32 v13, 0xffff0000, v14
	v_pk_add_f32 v[20:21], v[120:121], v[20:21]
	v_pk_add_f32 v[12:13], v[126:127], v[12:13]
	v_lshlrev_b32_e32 v14, 16, v15
	v_pk_add_f32 v[26:27], v[116:117], v[12:13]
	v_cvt_pk_bf16_f32 v12, v20, v21
	v_mul_f32_e32 v21, v21, v21
	v_fmac_f32_e32 v21, v20, v20
	v_mul_f32_e32 v20, v23, v23
	v_and_b32_e32 v15, 0xffff0000, v15
	v_fmac_f32_e32 v20, v22, v22
	v_pk_add_f32 v[14:15], v[124:125], v[14:15]
	v_add_f32_e32 v20, v21, v20
	v_mul_f32_e32 v21, v27, v27
	v_pk_add_f32 v[24:25], v[118:119], v[14:15]
	v_fmac_f32_e32 v21, v26, v26
	v_add_f32_e32 v20, v21, v20
	v_mul_f32_e32 v21, v25, v25
	v_fmac_f32_e32 v21, v24, v24
	v_cvt_pk_bf16_f32 v14, v26, v27
	v_add_f32_e32 v26, v21, v20
	v_lshlrev_b32_e32 v20, 16, v8
	v_and_b32_e32 v21, 0xffff0000, v8
	v_lshlrev_b32_e32 v8, 16, v9
	v_and_b32_e32 v9, 0xffff0000, v9
	v_pk_add_f32 v[20:21], v[126:127], v[20:21]
	v_pk_add_f32 v[8:9], v[124:125], v[8:9]
	v_cvt_pk_bf16_f32 v13, v22, v23
	v_pk_add_f32 v[22:23], v[114:115], v[8:9]
	v_pk_add_f32 v[8:9], v[112:113], v[20:21]
	v_lshlrev_b32_e32 v20, 16, v10
	v_and_b32_e32 v21, 0xffff0000, v10
	v_lshlrev_b32_e32 v10, 16, v11
	v_and_b32_e32 v11, 0xffff0000, v11
	v_pk_add_f32 v[10:11], v[124:125], v[10:11]
	v_cvt_pk_bf16_f32 v15, v24, v25
	v_pk_add_f32 v[20:21], v[126:127], v[20:21]
	v_pk_add_f32 v[24:25], v[110:111], v[10:11]
	v_mul_f32_e32 v10, v9, v9
	v_mul_f32_e32 v11, v23, v23
	v_pk_add_f32 v[20:21], v[108:109], v[20:21]
	v_fmac_f32_e32 v10, v8, v8
	v_fmac_f32_e32 v11, v22, v22
	v_add_f32_e32 v10, v10, v11
	v_mul_f32_e32 v11, v21, v21
	v_fmac_f32_e32 v11, v20, v20
	v_add_f32_e32 v10, v11, v10
	v_mul_f32_e32 v11, v25, v25
	v_fmac_f32_e32 v11, v24, v24
	s_or_b32 s22, s20, 32
	v_add_f32_e32 v10, v11, v10
	v_add_u32_e32 v16, s22, v203
	v_add_f32_e32 v26, v26, v10
	s_waitcnt lgkmcnt(0)
	v_ashrrev_i32_e32 v17, 31, v16
	v_mov_b32_e32 v27, v26
	s_nop 1
	v_permlane16_swap_b32_e32 v26, v27
	v_lshlrev_b64 v[18:19], 11, v[16:17]
	v_lshl_add_u64 v[18:19], s[14:15], 0, v[18:19]
	v_lshl_add_u64 v[18:19], s[52:53], 1, v[18:19]
	v_lshl_add_u64 v[10:11], v[18:19], 0, s[62:63]
	v_lshl_add_u64 v[18:19], v[10:11], 0, v[168:169]
	v_cvt_pk_bf16_f32 v10, v8, v9
	s_waitcnt lgkmcnt(0)
	v_add_f32_e32 v8, v26, v27
	v_mov_b32_e32 v9, v8
	s_nop 1
	v_permlane32_swap_b32_e32 v8, v9
	global_store_dwordx4 v[18:19], v[12:15], off
	v_cvt_pk_bf16_f32 v11, v22, v23
	s_nop 0
	v_cvt_pk_bf16_f32 v12, v20, v21
	v_cvt_pk_bf16_f32 v13, v24, v25
	global_store_dwordx4 v[18:19], v[10:13], off offset:256
	s_and_saveexec_b64 s[12:13], s[42:43]
	s_cbranch_execz .LBB0_208
	s_lshl_b32 s23, s36, 2
	s_or_b32 s24, s23, s76
	s_ashr_i32 s25, s24, 31
	s_lshl_b64 s[24:25], s[24:25], 18
	s_add_u32 s24, s74, s24
	s_addc_u32 s25, s75, s25
	s_waitcnt lgkmcnt(0)
	v_add_f32_e32 v10, v8, v9
	v_lshl_add_u64 v[8:9], v[16:17], 2, s[24:25]
	global_store_dword v[8:9], v10, off
; __device__ __forceinline__ float bflo(unsigned w) { return __uint_as_float(w << 16); }
;     template <int NM> __device__ __forceinline__ void round(const AccT& acc, const Unit& u, int ai, int m0, int wr, int wc, int fr, int fq) const {
;     ...
;         for (int mm = 0; mm < NM; ++mm) {
;             const int rl = ai * 128 + wr * 64 + (m0 + mm) * 16 + fr;
;             const size_t off = (size_t)(u.pm * 256 + rl) * DM + u.pn * 256 + wc * 32 + 8 * fq;
; #pragma unroll
;             for (int bj = 0; bj < 2; ++bj) {
;                 hv[mm][bj] = *GP(const u32x4, hin + off + bj * 128); lv[mm][bj] = (u32x2){0u, 0u};
;                 if (MODE == 1) pv[mm][bj] = *GP(const u32x4, proj + off + bj * 128);
;             }
;         }
; #pragma unroll
;         for (int mm = 0; mm < NM; ++mm) {
;             const int m = m0 + mm;
;             const int rl = ai * 128 + wr * 64 + m * 16 + fr; const int row = u.pm * 256 + rl;
;             const size_t off = (size_t)row * DM + u.pn * 256 + wc * 32 + 8 * fq;
;             float r = 1.f; if (MODE == 1) r = rs[((u.pm >> 3) & 3) * 256 + rl];
;             float ss = 0.f;
; #pragma unroll
;             for (int bj = 0; bj < 2; ++bj) {
;                 f32x4 d0, d1;
;                 if (MODE == 0) { d0 = acc[ai][bj][m][0] * alpha; d1 = acc[ai][bj][m][1] * alpha; }
;                 else {
;                     const u32x4 p = pv[mm][bj];
;                     const f32x4 a0 = acc[ai][bj][m][0] * r, a1 = acc[ai][bj][m][1] * r;
;                     d0 = (f32x4){fsigmoid(a0[0]) * bflo(p.x), fsigmoid(a0[1]) * bfhi(p.x), fsigmoid(a0[2]) * bflo(p.y), fsigmoid(a0[3]) * bfhi(p.y)};
;                     d1 = (f32x4){fsigmoid(a1[0]) * bflo(p.z), fsigmoid(a1[1]) * bfhi(p.z), fsigmoid(a1[2]) * bflo(p.w), fsigmoid(a1[3]) * bfhi(p.w)};
;                 }
;                 const u32x4 H = hv[mm][bj]; const u32x2 L = lv[mm][bj];
;                 const f32x4 o0 = ((f32x4){bflo(H.x), bfhi(H.x), bflo(H.y), bfhi(H.y)} + lo_unpack4(L.x)) + d0;
;                 const f32x4 o1 = ((f32x4){bflo(H.z), bfhi(H.z), bflo(H.w), bfhi(H.w)} + lo_unpack4(L.y)) + d1;
;                 u32x4 w; w.x = cvt_pk_bf16(o0[0], o0[1]); w.y = cvt_pk_bf16(o0[2], o0[3]); w.z = cvt_pk_bf16(o1[0], o1[1]); w.w = cvt_pk_bf16(o1[2], o1[3]);
;                 u32x2 wl; wl.x = lo_pack4(o0[0] - bflo(w.x), o0[1] - bfhi(w.x), o0[2] - bflo(w.y), o0[3] - bfhi(w.y));
.LBB0_208:
	s_or_b64 exec, exec, s[12:13]
	v_lshlrev_b32_e32 v12, 16, v4
	v_and_b32_e32 v13, 0xffff0000, v4
	v_lshlrev_b32_e32 v4, 16, v5
	v_and_b32_e32 v5, 0xffff0000, v5
	v_pk_add_f32 v[4:5], v[124:125], v[4:5]
	v_pk_add_f32 v[12:13], v[126:127], v[12:13]
	v_pk_add_f32 v[14:15], v[106:107], v[4:5]
	v_lshlrev_b32_e32 v4, 16, v6
	v_and_b32_e32 v5, 0xffff0000, v6
	v_pk_add_f32 v[12:13], v[104:105], v[12:13]
	v_pk_add_f32 v[4:5], v[126:127], v[4:5]
	v_lshlrev_b32_e32 v6, 16, v7
	v_pk_add_f32 v[18:19], v[100:101], v[4:5]
	v_cvt_pk_bf16_f32 v4, v12, v13
	v_mul_f32_e32 v13, v13, v13
	v_fmac_f32_e32 v13, v12, v12
	v_mul_f32_e32 v12, v15, v15
	v_and_b32_e32 v7, 0xffff0000, v7
	v_fmac_f32_e32 v12, v14, v14
	v_pk_add_f32 v[6:7], v[124:125], v[6:7]
	v_add_f32_e32 v12, v13, v12
	v_mul_f32_e32 v13, v19, v19
	v_pk_add_f32 v[16:17], v[102:103], v[6:7]
	v_fmac_f32_e32 v13, v18, v18
	v_add_f32_e32 v12, v13, v12
	v_mul_f32_e32 v13, v17, v17
	v_fmac_f32_e32 v13, v16, v16
	v_cvt_pk_bf16_f32 v6, v18, v19
	v_add_f32_e32 v18, v13, v12
	v_lshlrev_b32_e32 v12, 16, v0
	v_and_b32_e32 v13, 0xffff0000, v0
	v_lshlrev_b32_e32 v0, 16, v1
	v_and_b32_e32 v1, 0xffff0000, v1
	v_pk_add_f32 v[12:13], v[126:127], v[12:13]
	v_pk_add_f32 v[0:1], v[124:125], v[0:1]
	v_cvt_pk_bf16_f32 v5, v14, v15
	v_pk_add_f32 v[14:15], v[98:99], v[0:1]
	v_pk_add_f32 v[0:1], v[96:97], v[12:13]
	v_lshlrev_b32_e32 v12, 16, v2
	v_and_b32_e32 v13, 0xffff0000, v2
	v_lshlrev_b32_e32 v2, 16, v3
	v_and_b32_e32 v3, 0xffff0000, v3
	v_pk_add_f32 v[2:3], v[124:125], v[2:3]
	v_cvt_pk_bf16_f32 v7, v16, v17
	v_pk_add_f32 v[12:13], v[126:127], v[12:13]
	v_pk_add_f32 v[16:17], v[94:95], v[2:3]
	v_mul_f32_e32 v2, v1, v1
	v_mul_f32_e32 v3, v15, v15
	v_pk_add_f32 v[12:13], v[92:93], v[12:13]
	v_fmac_f32_e32 v2, v0, v0
	v_fmac_f32_e32 v3, v14, v14
	v_add_f32_e32 v2, v2, v3
	v_mul_f32_e32 v3, v13, v13
	v_fmac_f32_e32 v3, v12, v12
	v_add_f32_e32 v2, v3, v2
	v_mul_f32_e32 v3, v17, v17
	v_fmac_f32_e32 v3, v16, v16
	s_or_b32 s23, s20, 48
	v_add_f32_e32 v2, v3, v2
	v_add_u32_e32 v8, s23, v203
	v_add_f32_e32 v18, v18, v2
	s_waitcnt lgkmcnt(0)
	v_ashrrev_i32_e32 v9, 31, v8
	v_mov_b32_e32 v19, v18
	s_nop 1
	v_permlane16_swap_b32_e32 v18, v19
	v_lshlrev_b64 v[10:11], 11, v[8:9]
	v_lshl_add_u64 v[10:11], s[14:15], 0, v[10:11]
	v_lshl_add_u64 v[10:11], s[52:53], 1, v[10:11]
	v_lshl_add_u64 v[2:3], v[10:11], 0, s[62:63]
	v_lshl_add_u64 v[10:11], v[2:3], 0, v[168:169]
	v_cvt_pk_bf16_f32 v2, v0, v1
	s_waitcnt lgkmcnt(0)
	v_add_f32_e32 v0, v18, v19
	v_mov_b32_e32 v1, v0
	s_nop 1
	v_permlane32_swap_b32_e32 v0, v1
	global_store_dwordx4 v[10:11], v[4:7], off
	v_cvt_pk_bf16_f32 v3, v14, v15
	s_nop 0
	v_cvt_pk_bf16_f32 v4, v12, v13
	v_cvt_pk_bf16_f32 v5, v16, v17
	global_store_dwordx4 v[10:11], v[2:5], off offset:256
	s_and_saveexec_b64 s[12:13], s[42:43]
	s_cbranch_execz .LBB0_210
	s_lshl_b32 s24, s36, 2
	s_or_b32 s24, s24, s76
	s_ashr_i32 s25, s24, 31
	s_lshl_b64 s[24:25], s[24:25], 18
	s_add_u32 s24, s74, s24
	s_addc_u32 s25, s75, s25
	s_waitcnt lgkmcnt(0)
	v_add_f32_e32 v2, v0, v1
	v_lshl_add_u64 v[0:1], v[8:9], 2, s[24:25]
	global_store_dword v[0:1], v2, off
.LBB0_210:
	s_or_b64 exec, exec, s[12:13]
	v_add_u32_e32 v92, s20, v205
	v_ashrrev_i32_e32 v93, 31, v92
	v_lshlrev_b64 v[98:99], 11, v[92:93]
	s_waitcnt lgkmcnt(0)
	v_lshl_add_u64 v[0:1], v[148:149], 0, v[98:99]
	global_load_dwordx4 v[94:97], v[0:1], off
	global_load_dwordx4 v[24:27], v[0:1], off offset:256
	v_or_b32_e32 v0, 16, v92
	v_ashrrev_i32_e32 v1, 31, v0
	v_lshlrev_b64 v[0:1], 11, v[0:1]
	v_lshl_add_u64 v[0:1], v[148:149], 0, v[0:1]
	global_load_dwordx4 v[20:23], v[0:1], off
	global_load_dwordx4 v[16:19], v[0:1], off offset:256
	v_or_b32_e32 v0, 32, v92
	v_ashrrev_i32_e32 v1, 31, v0
	v_lshlrev_b64 v[0:1], 11, v[0:1]
	v_lshl_add_u64 v[0:1], v[148:149], 0, v[0:1]
	global_load_dwordx4 v[12:15], v[0:1], off
	global_load_dwordx4 v[8:11], v[0:1], off offset:256
	v_or_b32_e32 v0, 48, v92
	v_ashrrev_i32_e32 v1, 31, v0
	v_lshlrev_b64 v[0:1], 11, v[0:1]
	v_lshl_add_u64 v[0:1], v[148:149], 0, v[0:1]
	global_load_dwordx4 v[4:7], v[0:1], off
	s_nop 0
	global_load_dwordx4 v[0:3], v[0:1], off offset:256
	v_lshl_add_u64 v[98:99], s[14:15], 0, v[98:99]
	v_lshl_add_u64 v[98:99], s[52:53], 1, v[98:99]
	v_lshl_add_u64 v[98:99], v[98:99], 0, s[62:63]
	v_lshl_add_u64 v[98:99], v[98:99], 0, v[168:169]
	s_waitcnt vmcnt(7)
	v_lshlrev_b32_e32 v100, 16, v94
	v_and_b32_e32 v101, 0xffff0000, v94
	v_lshlrev_b32_e32 v94, 16, v95
	v_and_b32_e32 v95, 0xffff0000, v95
	v_pk_add_f32 v[94:95], v[124:125], v[94:95]
	v_pk_add_f32 v[100:101], v[126:127], v[100:101]
	v_pk_add_f32 v[94:95], v[86:87], v[94:95]
	v_lshlrev_b32_e32 v86, 16, v96
	v_and_b32_e32 v87, 0xffff0000, v96
	v_lshlrev_b32_e32 v96, 16, v97
	v_and_b32_e32 v97, 0xffff0000, v97
	v_pk_add_f32 v[86:87], v[126:127], v[86:87]
	v_pk_add_f32 v[96:97], v[124:125], v[96:97]
	v_pk_add_f32 v[90:91], v[90:91], v[100:101]
	v_pk_add_f32 v[96:97], v[84:85], v[96:97]
	v_pk_add_f32 v[88:89], v[88:89], v[86:87]
	v_cvt_pk_bf16_f32 v84, v90, v91
	v_cvt_pk_bf16_f32 v85, v94, v95
	v_cvt_pk_bf16_f32 v86, v88, v89
	v_cvt_pk_bf16_f32 v87, v96, v97
	global_store_dwordx4 v[98:99], v[84:87], off
	s_nop 1
	v_mul_f32_e32 v84, v91, v91
	v_mul_f32_e32 v85, v95, v95
	v_fmac_f32_e32 v84, v90, v90
	v_fmac_f32_e32 v85, v94, v94
	v_add_f32_e32 v84, v84, v85
	v_mul_f32_e32 v85, v89, v89
	v_fmac_f32_e32 v85, v88, v88
	v_add_f32_e32 v84, v85, v84
	v_mul_f32_e32 v85, v97, v97
	v_fmac_f32_e32 v85, v96, v96
	v_add_f32_e32 v86, v85, v84
	s_waitcnt vmcnt(7)
	v_lshlrev_b32_e32 v84, 16, v24
	v_and_b32_e32 v85, 0xffff0000, v24
	v_lshlrev_b32_e32 v24, 16, v25
	v_and_b32_e32 v25, 0xffff0000, v25
	v_pk_add_f32 v[24:25], v[124:125], v[24:25]
	v_pk_add_f32 v[84:85], v[126:127], v[84:85]
	v_pk_add_f32 v[80:81], v[80:81], v[24:25]
	v_lshlrev_b32_e32 v24, 16, v26
	v_and_b32_e32 v25, 0xffff0000, v26
	v_lshlrev_b32_e32 v26, 16, v27
	v_and_b32_e32 v27, 0xffff0000, v27
	v_pk_add_f32 v[24:25], v[126:127], v[24:25]
	v_pk_add_f32 v[26:27], v[124:125], v[26:27]
	v_pk_add_f32 v[82:83], v[82:83], v[84:85]
	v_pk_add_f32 v[78:79], v[78:79], v[26:27]
	v_pk_add_f32 v[76:77], v[76:77], v[24:25]
	v_cvt_pk_bf16_f32 v24, v82, v83
	v_cvt_pk_bf16_f32 v25, v80, v81
	v_cvt_pk_bf16_f32 v26, v76, v77
	v_cvt_pk_bf16_f32 v27, v78, v79
	global_store_dwordx4 v[98:99], v[24:27], off offset:256
	s_nop 1
	v_mul_f32_e32 v24, v83, v83
	v_mul_f32_e32 v25, v81, v81
	v_fmac_f32_e32 v24, v82, v82
	v_fmac_f32_e32 v25, v80, v80
	v_add_f32_e32 v24, v24, v25
	v_mul_f32_e32 v25, v77, v77
	v_fmac_f32_e32 v25, v76, v76
	v_add_f32_e32 v24, v25, v24
	v_mul_f32_e32 v25, v79, v79
	v_fmac_f32_e32 v25, v78, v78
	v_add_f32_e32 v24, v25, v24
	v_add_f32_e32 v24, v86, v24
	v_mov_b32_e32 v25, v24
	s_nop 1
	v_permlane16_swap_b32_e32 v24, v25
	s_waitcnt lgkmcnt(0)
	v_add_f32_e32 v24, v24, v25
	v_mov_b32_e32 v25, v24
	s_nop 1
	v_permlane32_swap_b32_e32 v24, v25
	s_and_saveexec_b64 s[12:13], s[42:43]
	s_cbranch_execz .LBB0_212
; __device__ __forceinline__ float bflo(unsigned w) { return __uint_as_float(w << 16); }
;     template <int NM> __device__ __forceinline__ void round(const AccT& acc, const Unit& u, int ai, int m0, int wr, int wc, int fr, int fq) const {
;     ...
;         for (int mm = 0; mm < NM; ++mm) {
;             const int m = m0 + mm;
;             const int rl = ai * 128 + wr * 64 + m * 16 + fr; const int row = u.pm * 256 + rl;
;             const size_t off = (size_t)row * DM + u.pn * 256 + wc * 32 + 8 * fq;
;             float r = 1.f; if (MODE == 1) r = rs[((u.pm >> 3) & 3) * 256 + rl];
;             float ss = 0.f;
; #pragma unroll
;             for (int bj = 0; bj < 2; ++bj) {
;                 f32x4 d0, d1;
;                 if (MODE == 0) { d0 = acc[ai][bj][m][0] * alpha; d1 = acc[ai][bj][m][1] * alpha; }
;                 else {
;                     const u32x4 p = pv[mm][bj];
;                     const f32x4 a0 = acc[ai][bj][m][0] * r, a1 = acc[ai][bj][m][1] * r;
;                     d0 = (f32x4){fsigmoid(a0[0]) * bflo(p.x), fsigmoid(a0[1]) * bfhi(p.x), fsigmoid(a0[2]) * bflo(p.y), fsigmoid(a0[3]) * bfhi(p.y)};
;                     d1 = (f32x4){fsigmoid(a1[0]) * bflo(p.z), fsigmoid(a1[1]) * bfhi(p.z), fsigmoid(a1[2]) * bflo(p.w), fsigmoid(a1[3]) * bfhi(p.w)};
;                 }
;                 const u32x4 H = hv[mm][bj]; const u32x2 L = lv[mm][bj];
;                 const f32x4 o0 = ((f32x4){bflo(H.x), bfhi(H.x), bflo(H.y), bfhi(H.y)} + lo_unpack4(L.x)) + d0;
;                 const f32x4 o1 = ((f32x4){bflo(H.z), bfhi(H.z), bflo(H.w), bfhi(H.w)} + lo_unpack4(L.y)) + d1;
;                 u32x4 w; w.x = cvt_pk_bf16(o0[0], o0[1]); w.y = cvt_pk_bf16(o0[2], o0[3]); w.z = cvt_pk_bf16(o1[0], o1[1]); w.w = cvt_pk_bf16(o1[2], o1[3]);
;                 u32x2 wl; wl.x = lo_pack4(o0[0] - bflo(w.x), o0[1] - bfhi(w.x), o0[2] - bflo(w.y), o0[3] - bfhi(w.y));
;                 wl.y = lo_pack4(o1[0] - bflo(w.z), o1[1] - bfhi(w.z), o1[2] - bflo(w.w), o1[3] - bfhi(w.w));
;                 *GP(u32x4, hout + off + bj * 128) = w; (void)wl;
;                 ss += (o0[0] * o0[0] + o0[1] * o0[1]) + (o0[2] * o0[2] + o0[3] * o0[3]) + (o1[0] * o1[0] + o1[1] * o1[1]) + (o1[2] * o1[2] + o1[3] * o1[3]);
;             }
;             ss += __shfl_xor(ss, 16); ss += __shfl_xor(ss, 32);
;             if (fq == 0) *GP(float, ssp + (size_t)(u.pn * 4 + wc) * TT + row) = ss;
	s_lshl_b32 s20, s36, 2
	s_or_b32 s24, s20, s76
	s_ashr_i32 s25, s24, 31
	s_lshl_b64 s[24:25], s[24:25], 18
	s_add_u32 s24, s74, s24
	s_addc_u32 s25, s75, s25
	s_waitcnt lgkmcnt(0)
	v_add_f32_e32 v26, v24, v25
	v_lshl_add_u64 v[24:25], v[92:93], 2, s[24:25]
	global_store_dword v[24:25], v26, off
.LBB0_212:
	s_or_b64 exec, exec, s[12:13]
	s_waitcnt vmcnt(7)
	v_lshlrev_b32_e32 v76, 16, v20
	v_and_b32_e32 v77, 0xffff0000, v20
	v_lshlrev_b32_e32 v20, 16, v21
	v_and_b32_e32 v21, 0xffff0000, v21
	v_pk_add_f32 v[20:21], v[124:125], v[20:21]
	v_pk_add_f32 v[76:77], v[126:127], v[76:77]
	v_pk_add_f32 v[74:75], v[74:75], v[20:21]
	v_lshlrev_b32_e32 v20, 16, v22
	v_and_b32_e32 v21, 0xffff0000, v22
	v_pk_add_f32 v[72:73], v[72:73], v[76:77]
	v_pk_add_f32 v[20:21], v[126:127], v[20:21]
	v_lshlrev_b32_e32 v22, 16, v23
	v_and_b32_e32 v23, 0xffff0000, v23
	v_pk_add_f32 v[68:69], v[68:69], v[20:21]
	v_cvt_pk_bf16_f32 v20, v72, v73
	v_mul_f32_e32 v73, v73, v73
	v_pk_add_f32 v[22:23], v[124:125], v[22:23]
	v_fmac_f32_e32 v73, v72, v72
	v_mul_f32_e32 v72, v75, v75
	v_pk_add_f32 v[70:71], v[70:71], v[22:23]
	v_cvt_pk_bf16_f32 v22, v68, v69
	v_fmac_f32_e32 v72, v74, v74
	v_mul_f32_e32 v69, v69, v69
	v_add_f32_e32 v72, v73, v72
	v_fmac_f32_e32 v69, v68, v68
	v_add_f32_e32 v68, v69, v72
	v_mul_f32_e32 v69, v71, v71
	v_fmac_f32_e32 v69, v70, v70
	v_cvt_pk_bf16_f32 v23, v70, v71
	v_add_f32_e32 v70, v69, v68
	s_waitcnt vmcnt(6)
	v_lshlrev_b32_e32 v68, 16, v16
	v_and_b32_e32 v69, 0xffff0000, v16
	v_lshlrev_b32_e32 v16, 16, v17
	v_and_b32_e32 v17, 0xffff0000, v17
	v_pk_add_f32 v[68:69], v[126:127], v[68:69]
	v_pk_add_f32 v[16:17], v[124:125], v[16:17]
	v_add_u32_e32 v24, s21, v205
	v_pk_add_f32 v[66:67], v[66:67], v[16:17]
	v_pk_add_f32 v[16:17], v[64:65], v[68:69]
	v_lshlrev_b32_e32 v64, 16, v18
	v_and_b32_e32 v65, 0xffff0000, v18
	v_lshlrev_b32_e32 v18, 16, v19
	v_and_b32_e32 v19, 0xffff0000, v19
	v_pk_add_f32 v[18:19], v[124:125], v[18:19]
	v_pk_add_f32 v[64:65], v[126:127], v[64:65]
	v_pk_add_f32 v[62:63], v[62:63], v[18:19]
	v_mul_f32_e32 v18, v17, v17
	v_mul_f32_e32 v19, v67, v67
	v_pk_add_f32 v[60:61], v[60:61], v[64:65]
	v_fmac_f32_e32 v18, v16, v16
	v_fmac_f32_e32 v19, v66, v66
	v_add_f32_e32 v18, v18, v19
	v_mul_f32_e32 v19, v61, v61
	v_fmac_f32_e32 v19, v60, v60
	v_add_f32_e32 v18, v19, v18
	v_mul_f32_e32 v19, v63, v63
	v_fmac_f32_e32 v19, v62, v62
	v_add_f32_e32 v18, v19, v18
	v_add_f32_e32 v64, v70, v18
	s_waitcnt lgkmcnt(0)
	v_ashrrev_i32_e32 v25, 31, v24
	v_mov_b32_e32 v65, v64
	s_nop 1
	v_permlane16_swap_b32_e32 v64, v65
	v_lshlrev_b64 v[26:27], 11, v[24:25]
	v_lshl_add_u64 v[26:27], s[14:15], 0, v[26:27]
	v_lshl_add_u64 v[26:27], s[52:53], 1, v[26:27]
	v_lshl_add_u64 v[18:19], v[26:27], 0, s[62:63]
	v_lshl_add_u64 v[26:27], v[18:19], 0, v[168:169]
	v_cvt_pk_bf16_f32 v18, v16, v17
	s_waitcnt lgkmcnt(0)
	v_add_f32_e32 v16, v64, v65
	v_mov_b32_e32 v17, v16
	s_nop 1
	v_permlane32_swap_b32_e32 v16, v17
	v_cvt_pk_bf16_f32 v21, v74, v75
	global_store_dwordx4 v[26:27], v[20:23], off
	v_cvt_pk_bf16_f32 v19, v66, v67
	s_nop 0
	v_cvt_pk_bf16_f32 v20, v60, v61
	v_cvt_pk_bf16_f32 v21, v62, v63
	global_store_dwordx4 v[26:27], v[18:21], off offset:256
	s_and_saveexec_b64 s[12:13], s[42:43]
	s_cbranch_execz .LBB0_214
	s_lshl_b32 s20, s36, 2
	s_or_b32 s20, s20, s76
	s_ashr_i32 s21, s20, 31
	s_lshl_b64 s[20:21], s[20:21], 18
	s_add_u32 s20, s74, s20
	s_addc_u32 s21, s75, s21
	s_waitcnt lgkmcnt(0)
	v_add_f32_e32 v18, v16, v17
	v_lshl_add_u64 v[16:17], v[24:25], 2, s[20:21]
	global_store_dword v[16:17], v18, off
; __device__ __forceinline__ float bflo(unsigned w) { return __uint_as_float(w << 16); }
;     template <int NM> __device__ __forceinline__ void round(const AccT& acc, const Unit& u, int ai, int m0, int wr, int wc, int fr, int fq) const {
;     ...
;         for (int mm = 0; mm < NM; ++mm) {
;             const int m = m0 + mm;
;             const int rl = ai * 128 + wr * 64 + m * 16 + fr; const int row = u.pm * 256 + rl;
;             const size_t off = (size_t)row * DM + u.pn * 256 + wc * 32 + 8 * fq;
;             float r = 1.f; if (MODE == 1) r = rs[((u.pm >> 3) & 3) * 256 + rl];
;             float ss = 0.f;
; #pragma unroll
;             for (int bj = 0; bj < 2; ++bj) {
;                 f32x4 d0, d1;
;                 if (MODE == 0) { d0 = acc[ai][bj][m][0] * alpha; d1 = acc[ai][bj][m][1] * alpha; }
;                 else {
;                     const u32x4 p = pv[mm][bj];
;                     const f32x4 a0 = acc[ai][bj][m][0] * r, a1 = acc[ai][bj][m][1] * r;
;                     d0 = (f32x4){fsigmoid(a0[0]) * bflo(p.x), fsigmoid(a0[1]) * bfhi(p.x), fsigmoid(a0[2]) * bflo(p.y), fsigmoid(a0[3]) * bfhi(p.y)};
;                     d1 = (f32x4){fsigmoid(a1[0]) * bflo(p.z), fsigmoid(a1[1]) * bfhi(p.z), fsigmoid(a1[2]) * bflo(p.w), fsigmoid(a1[3]) * bfhi(p.w)};
;                 }
;                 const u32x4 H = hv[mm][bj]; const u32x2 L = lv[mm][bj];
;                 const f32x4 o0 = ((f32x4){bflo(H.x), bfhi(H.x), bflo(H.y), bfhi(H.y)} + lo_unpack4(L.x)) + d0;
;                 const f32x4 o1 = ((f32x4){bflo(H.z), bfhi(H.z), bflo(H.w), bfhi(H.w)} + lo_unpack4(L.y)) + d1;
;                 u32x4 w; w.x = cvt_pk_bf16(o0[0], o0[1]); w.y = cvt_pk_bf16(o0[2], o0[3]); w.z = cvt_pk_bf16(o1[0], o1[1]); w.w = cvt_pk_bf16(o1[2], o1[3]);
;                 u32x2 wl; wl.x = lo_pack4(o0[0] - bflo(w.x), o0[1] - bfhi(w.x), o0[2] - bflo(w.y), o0[3] - bfhi(w.y));
;                 wl.y = lo_pack4(o1[0] - bflo(w.z), o1[1] - bfhi(w.z), o1[2] - bflo(w.w), o1[3] - bfhi(w.w));
;                 *GP(u32x4, hout + off + bj * 128) = w; (void)wl;
;                 ss += (o0[0] * o0[0] + o0[1] * o0[1]) + (o0[2] * o0[2] + o0[3] * o0[3]) + (o1[0] * o1[0] + o1[1] * o1[1]) + (o1[2] * o1[2] + o1[3] * o1[3]);
;             }
;             ss += __shfl_xor(ss, 16); ss += __shfl_xor(ss, 32);
;             if (fq == 0) *GP(float, ssp + (size_t)(u.pn * 4 + wc) * TT + row) = ss;
.LBB0_214:
	s_or_b64 exec, exec, s[12:13]
	s_waitcnt vmcnt(7)
	v_lshlrev_b32_e32 v20, 16, v12
	v_and_b32_e32 v21, 0xffff0000, v12
	v_lshlrev_b32_e32 v12, 16, v13
	v_and_b32_e32 v13, 0xffff0000, v13
	v_pk_add_f32 v[12:13], v[124:125], v[12:13]
	v_pk_add_f32 v[20:21], v[126:127], v[20:21]
	v_pk_add_f32 v[22:23], v[58:59], v[12:13]
	v_lshlrev_b32_e32 v12, 16, v14
	v_and_b32_e32 v13, 0xffff0000, v14
	v_pk_add_f32 v[20:21], v[56:57], v[20:21]
	v_pk_add_f32 v[12:13], v[126:127], v[12:13]
	v_lshlrev_b32_e32 v14, 16, v15
	v_pk_add_f32 v[26:27], v[52:53], v[12:13]
	v_cvt_pk_bf16_f32 v12, v20, v21
	v_mul_f32_e32 v21, v21, v21
	v_fmac_f32_e32 v21, v20, v20
	v_mul_f32_e32 v20, v23, v23
	v_and_b32_e32 v15, 0xffff0000, v15
	v_fmac_f32_e32 v20, v22, v22
	v_pk_add_f32 v[14:15], v[124:125], v[14:15]
	v_add_f32_e32 v20, v21, v20
	v_mul_f32_e32 v21, v27, v27
	v_pk_add_f32 v[24:25], v[54:55], v[14:15]
	v_fmac_f32_e32 v21, v26, v26
	v_add_f32_e32 v20, v21, v20
	v_mul_f32_e32 v21, v25, v25
	v_fmac_f32_e32 v21, v24, v24
	v_cvt_pk_bf16_f32 v14, v26, v27
	v_add_f32_e32 v26, v21, v20
	s_waitcnt vmcnt(6)
	v_lshlrev_b32_e32 v20, 16, v8
	v_and_b32_e32 v21, 0xffff0000, v8
	v_lshlrev_b32_e32 v8, 16, v9
	v_and_b32_e32 v9, 0xffff0000, v9
	v_pk_add_f32 v[20:21], v[126:127], v[20:21]
	v_pk_add_f32 v[8:9], v[124:125], v[8:9]
	v_cvt_pk_bf16_f32 v13, v22, v23
	v_pk_add_f32 v[22:23], v[50:51], v[8:9]
	v_pk_add_f32 v[8:9], v[48:49], v[20:21]
	v_lshlrev_b32_e32 v20, 16, v10
	v_and_b32_e32 v21, 0xffff0000, v10
	v_lshlrev_b32_e32 v10, 16, v11
	v_and_b32_e32 v11, 0xffff0000, v11
	v_pk_add_f32 v[10:11], v[124:125], v[10:11]
	v_cvt_pk_bf16_f32 v15, v24, v25
	v_pk_add_f32 v[20:21], v[126:127], v[20:21]
	v_pk_add_f32 v[24:25], v[46:47], v[10:11]
	v_mul_f32_e32 v10, v9, v9
	v_mul_f32_e32 v11, v23, v23
	v_pk_add_f32 v[20:21], v[44:45], v[20:21]
	v_fmac_f32_e32 v10, v8, v8
	v_fmac_f32_e32 v11, v22, v22
	v_add_f32_e32 v10, v10, v11
	v_mul_f32_e32 v11, v21, v21
	v_fmac_f32_e32 v11, v20, v20
	v_add_f32_e32 v10, v11, v10
	v_mul_f32_e32 v11, v25, v25
	v_fmac_f32_e32 v11, v24, v24
	v_add_f32_e32 v10, v11, v10
	v_add_u32_e32 v16, s22, v205
	v_add_f32_e32 v26, v26, v10
	s_waitcnt lgkmcnt(0)
	v_ashrrev_i32_e32 v17, 31, v16
	v_mov_b32_e32 v27, v26
	s_nop 1
	v_permlane16_swap_b32_e32 v26, v27
	v_lshlrev_b64 v[18:19], 11, v[16:17]
	v_lshl_add_u64 v[18:19], s[14:15], 0, v[18:19]
	v_lshl_add_u64 v[18:19], s[52:53], 1, v[18:19]
	v_lshl_add_u64 v[10:11], v[18:19], 0, s[62:63]
	v_lshl_add_u64 v[18:19], v[10:11], 0, v[168:169]
	v_cvt_pk_bf16_f32 v10, v8, v9
	s_waitcnt lgkmcnt(0)
	v_add_f32_e32 v8, v26, v27
	v_mov_b32_e32 v9, v8
	s_nop 1
	v_permlane32_swap_b32_e32 v8, v9
	global_store_dwordx4 v[18:19], v[12:15], off
	v_cvt_pk_bf16_f32 v11, v22, v23
	s_nop 0
	v_cvt_pk_bf16_f32 v12, v20, v21
	v_cvt_pk_bf16_f32 v13, v24, v25
	global_store_dwordx4 v[18:19], v[10:13], off offset:256
	s_and_saveexec_b64 s[12:13], s[42:43]
	s_cbranch_execz .LBB0_216
	s_lshl_b32 s20, s36, 2
	s_or_b32 s20, s20, s76
	s_ashr_i32 s21, s20, 31
	s_lshl_b64 s[20:21], s[20:21], 18
	s_add_u32 s20, s74, s20
	s_addc_u32 s21, s75, s21
	s_waitcnt lgkmcnt(0)
	v_add_f32_e32 v10, v8, v9
	v_lshl_add_u64 v[8:9], v[16:17], 2, s[20:21]
	global_store_dword v[8:9], v10, off
.LBB0_216:
	s_or_b64 exec, exec, s[12:13]
	s_waitcnt vmcnt(7)
	v_lshlrev_b32_e32 v12, 16, v4
	v_and_b32_e32 v13, 0xffff0000, v4
	v_lshlrev_b32_e32 v4, 16, v5
	v_and_b32_e32 v5, 0xffff0000, v5
	v_pk_add_f32 v[4:5], v[124:125], v[4:5]
	v_pk_add_f32 v[12:13], v[126:127], v[12:13]
	v_pk_add_f32 v[14:15], v[42:43], v[4:5]
	v_lshlrev_b32_e32 v4, 16, v6
	v_and_b32_e32 v5, 0xffff0000, v6
	v_pk_add_f32 v[12:13], v[40:41], v[12:13]
	v_pk_add_f32 v[4:5], v[126:127], v[4:5]
	v_lshlrev_b32_e32 v6, 16, v7
	v_pk_add_f32 v[18:19], v[36:37], v[4:5]
	v_cvt_pk_bf16_f32 v4, v12, v13
	v_mul_f32_e32 v13, v13, v13
	v_fmac_f32_e32 v13, v12, v12
	v_mul_f32_e32 v12, v15, v15
	v_and_b32_e32 v7, 0xffff0000, v7
	v_fmac_f32_e32 v12, v14, v14
	v_pk_add_f32 v[6:7], v[124:125], v[6:7]
	v_add_f32_e32 v12, v13, v12
	v_mul_f32_e32 v13, v19, v19
	v_pk_add_f32 v[16:17], v[38:39], v[6:7]
	v_fmac_f32_e32 v13, v18, v18
	v_add_f32_e32 v12, v13, v12
	v_mul_f32_e32 v13, v17, v17
	v_fmac_f32_e32 v13, v16, v16
	v_cvt_pk_bf16_f32 v6, v18, v19
	v_add_f32_e32 v18, v13, v12
	s_waitcnt vmcnt(6)
	v_lshlrev_b32_e32 v12, 16, v0
	v_and_b32_e32 v13, 0xffff0000, v0
	v_lshlrev_b32_e32 v0, 16, v1
	v_and_b32_e32 v1, 0xffff0000, v1
	v_pk_add_f32 v[12:13], v[126:127], v[12:13]
	v_pk_add_f32 v[0:1], v[124:125], v[0:1]
	v_cvt_pk_bf16_f32 v5, v14, v15
	v_pk_add_f32 v[14:15], v[34:35], v[0:1]
	v_pk_add_f32 v[0:1], v[32:33], v[12:13]
	v_lshlrev_b32_e32 v12, 16, v2
	v_and_b32_e32 v13, 0xffff0000, v2
	v_lshlrev_b32_e32 v2, 16, v3
	v_and_b32_e32 v3, 0xffff0000, v3
	v_pk_add_f32 v[2:3], v[124:125], v[2:3]
	v_cvt_pk_bf16_f32 v7, v16, v17
	v_pk_add_f32 v[12:13], v[126:127], v[12:13]
	v_pk_add_f32 v[16:17], v[30:31], v[2:3]
	v_mul_f32_e32 v2, v1, v1
	v_mul_f32_e32 v3, v15, v15
	v_pk_add_f32 v[12:13], v[28:29], v[12:13]
	v_fmac_f32_e32 v2, v0, v0
	v_fmac_f32_e32 v3, v14, v14
	v_add_f32_e32 v2, v2, v3
	v_mul_f32_e32 v3, v13, v13
	v_fmac_f32_e32 v3, v12, v12
	v_add_f32_e32 v2, v3, v2
	v_mul_f32_e32 v3, v17, v17
	v_fmac_f32_e32 v3, v16, v16
	v_add_f32_e32 v2, v3, v2
	v_add_u32_e32 v8, s23, v205
	v_add_f32_e32 v18, v18, v2
	s_waitcnt lgkmcnt(0)
	v_ashrrev_i32_e32 v9, 31, v8
	v_mov_b32_e32 v19, v18
	s_nop 1
	v_permlane16_swap_b32_e32 v18, v19
	v_lshlrev_b64 v[10:11], 11, v[8:9]
	v_lshl_add_u64 v[10:11], s[14:15], 0, v[10:11]
	v_lshl_add_u64 v[10:11], s[52:53], 1, v[10:11]
	v_lshl_add_u64 v[2:3], v[10:11], 0, s[62:63]
	v_lshl_add_u64 v[10:11], v[2:3], 0, v[168:169]
	v_cvt_pk_bf16_f32 v2, v0, v1
	s_waitcnt lgkmcnt(0)
	v_add_f32_e32 v0, v18, v19
	v_mov_b32_e32 v1, v0
	s_nop 1
	v_permlane32_swap_b32_e32 v0, v1
	global_store_dwordx4 v[10:11], v[4:7], off
	v_cvt_pk_bf16_f32 v3, v14, v15
	s_nop 0
	v_cvt_pk_bf16_f32 v4, v12, v13
	v_cvt_pk_bf16_f32 v5, v16, v17
	global_store_dwordx4 v[10:11], v[2:5], off offset:256
	s_and_saveexec_b64 s[12:13], s[42:43]
	s_cbranch_execz .LBB0_186
	s_lshl_b32 s20, s36, 2
	s_or_b32 s20, s20, s76
	s_ashr_i32 s21, s20, 31
	s_lshl_b64 s[20:21], s[20:21], 18
	s_add_u32 s20, s74, s20
	s_addc_u32 s21, s75, s21
	s_waitcnt lgkmcnt(0)
	v_add_f32_e32 v2, v0, v1
	v_lshl_add_u64 v[0:1], v[8:9], 2, s[20:21]
	global_store_dword v[0:1], v2, off
	s_branch .LBB0_186

; __device__ __forceinline__ float bflo(unsigned w) { return __uint_as_float(w << 16); }
;     template <int NM> __device__ __forceinline__ void round(const AccT& acc, const Unit& u, int ai, int m0, int wr, int wc, int fr, int fq) const {
;     ...
;         for (int mm = 0; mm < NM; ++mm) {
;             const int rl = ai * 128 + wr * 64 + (m0 + mm) * 16 + fr;
;             const size_t off = (size_t)(u.pm * 256 + rl) * DM + u.pn * 256 + wc * 32 + 8 * fq;
; #pragma unroll
;             for (int bj = 0; bj < 2; ++bj) {
;                 hv[mm][bj] = *GP(const u32x4, hin + off + bj * 128); lv[mm][bj] = (u32x2){0u, 0u};
;                 if (MODE == 1) pv[mm][bj] = *GP(const u32x4, proj + off + bj * 128);
;             }
;         }
; #pragma unroll
;         for (int mm = 0; mm < NM; ++mm) {
;             const int m = m0 + mm;
;             const int rl = ai * 128 + wr * 64 + m * 16 + fr; const int row = u.pm * 256 + rl;
;             const size_t off = (size_t)row * DM + u.pn * 256 + wc * 32 + 8 * fq;
;             float r = 1.f; if (MODE == 1) r = rs[((u.pm >> 3) & 3) * 256 + rl];
;             float ss = 0.f;
; #pragma unroll
;             for (int bj = 0; bj < 2; ++bj) {
;                 f32x4 d0, d1;
;                 if (MODE == 0) { d0 = acc[ai][bj][m][0] * alpha; d1 = acc[ai][bj][m][1] * alpha; }
;                 else {
;                     const u32x4 p = pv[mm][bj];
;                     const f32x4 a0 = acc[ai][bj][m][0] * r, a1 = acc[ai][bj][m][1] * r;
;                     d0 = (f32x4){fsigmoid(a0[0]) * bflo(p.x), fsigmoid(a0[1]) * bfhi(p.x), fsigmoid(a0[2]) * bflo(p.y), fsigmoid(a0[3]) * bfhi(p.y)};
;                     d1 = (f32x4){fsigmoid(a1[0]) * bflo(p.z), fsigmoid(a1[1]) * bfhi(p.z), fsigmoid(a1[2]) * bflo(p.w), fsigmoid(a1[3]) * bfhi(p.w)};
;                 }
;                 const u32x4 H = hv[mm][bj]; const u32x2 L = lv[mm][bj];
;                 const f32x4 o0 = ((f32x4){bflo(H.x), bfhi(H.x), bflo(H.y), bfhi(H.y)} + lo_unpack4(L.x)) + d0;
;                 const f32x4 o1 = ((f32x4){bflo(H.z), bfhi(H.z), bflo(H.w), bfhi(H.w)} + lo_unpack4(L.y)) + d1;
;                 u32x4 w; w.x = cvt_pk_bf16(o0[0], o0[1]); w.y = cvt_pk_bf16(o0[2], o0[3]); w.z = cvt_pk_bf16(o1[0], o1[1]); w.w = cvt_pk_bf16(o1[2], o1[3]);
;                 u32x2 wl; wl.x = lo_pack4(o0[0] - bflo(w.x), o0[1] - bfhi(w.x), o0[2] - bflo(w.y), o0[3] - bfhi(w.y));
.LBB0_270:
	s_lshl_b32 s20, s62, 8
	s_lshl_b32 s52, s36, 8
	v_add_u32_e32 v194, s20, v203
	s_ashr_i32 s53, s52, 31
	s_lshl_b64 s[12:13], s[52:53], 1
	v_ashrrev_i32_e32 v195, 31, v194
	v_lshl_add_u64 v[192:193], v[158:159], 0, s[12:13]
	v_lshlrev_b64 v[216:217], 11, v[194:195]
	v_lshl_add_u64 v[128:129], v[192:193], 0, v[216:217]
	global_load_dwordx4 v[212:215], v[128:129], off
	global_load_dwordx4 v[152:155], v[128:129], off offset:256
	v_or_b32_e32 v128, 16, v194
	v_ashrrev_i32_e32 v129, 31, v128
	v_lshlrev_b64 v[128:129], 11, v[128:129]
	v_lshl_add_u64 v[128:129], v[192:193], 0, v[128:129]
	global_load_dwordx4 v[148:151], v[128:129], off
	global_load_dwordx4 v[144:147], v[128:129], off offset:256
	v_or_b32_e32 v128, 32, v194
	v_ashrrev_i32_e32 v129, 31, v128
	v_lshlrev_b64 v[128:129], 11, v[128:129]
	v_lshl_add_u64 v[128:129], v[192:193], 0, v[128:129]
	global_load_dwordx4 v[140:143], v[128:129], off
	global_load_dwordx4 v[136:139], v[128:129], off offset:256
	v_or_b32_e32 v128, 48, v194
	v_ashrrev_i32_e32 v129, 31, v128
	v_lshlrev_b64 v[128:129], 11, v[128:129]
	v_lshl_add_u64 v[128:129], v[192:193], 0, v[128:129]
	global_load_dwordx4 v[132:135], v[128:129], off
	s_nop 0
	global_load_dwordx4 v[128:131], v[128:129], off offset:256
	v_and_b32_e32 v196, 64, v163
	v_xor_b32_e32 v168, 16, v163
	v_add_u32_e32 v196, 64, v196
	v_cmp_lt_i32_e32 vcc, v168, v196
	v_cvt_pk_f32_fp8_sdwa v[198:199], s63 src0_sel:WORD_1
	v_lshl_add_u64 v[216:217], s[14:15], 0, v[216:217]
	v_cndmask_b32_e32 v168, v163, v168, vcc
	v_lshlrev_b32_e32 v207, 2, v168
	v_xor_b32_e32 v168, 32, v163
	v_cmp_lt_i32_e32 vcc, v168, v196
	v_cvt_pk_f32_fp8_e32 v[196:197], 0
	v_lshl_add_u64 v[216:217], v[216:217], 0, s[12:13]
	v_cndmask_b32_e32 v168, v163, v168, vcc
	s_lshl_b32 s62, s78, 1
	v_lshlrev_b32_e32 v211, 2, v168
	v_lshl_add_u64 v[216:217], v[216:217], 0, s[62:63]
	v_lshlrev_b32_e32 v168, 1, v156
	v_lshl_add_u64 v[216:217], v[216:217], 0, v[168:169]
	s_waitcnt vmcnt(0)
	v_lshlrev_b32_e32 v218, 16, v212
	v_and_b32_e32 v219, 0xffff0000, v212
	v_lshlrev_b32_e32 v212, 16, v213
	v_and_b32_e32 v213, 0xffff0000, v213
	v_pk_fma_f32 v[212:213], v[198:199], s[34:35], v[212:213] op_sel_hi:[1,0,1]
	v_pk_fma_f32 v[218:219], v[196:197], s[34:35], v[218:219] op_sel_hi:[1,0,1]
	v_pk_add_f32 v[126:127], v[126:127], v[212:213]
	v_lshlrev_b32_e32 v212, 16, v214
	v_and_b32_e32 v213, 0xffff0000, v214
	v_lshlrev_b32_e32 v214, 16, v215
	v_and_b32_e32 v215, 0xffff0000, v215
	v_pk_fma_f32 v[212:213], v[196:197], s[34:35], v[212:213] op_sel_hi:[1,0,1]
	v_pk_fma_f32 v[214:215], v[198:199], s[34:35], v[214:215] op_sel_hi:[1,0,1]
	v_pk_add_f32 v[124:125], v[124:125], v[218:219]
	v_pk_add_f32 v[214:215], v[122:123], v[214:215]
	v_pk_add_f32 v[212:213], v[120:121], v[212:213]
	v_cvt_pk_bf16_f32 v120, v124, v125
	v_cvt_pk_bf16_f32 v121, v126, v127
	v_cvt_pk_bf16_f32 v122, v212, v213
	v_cvt_pk_bf16_f32 v123, v214, v215
	global_store_dwordx4 v[216:217], v[120:123], off
	s_nop 1
	v_mul_f32_e32 v120, v125, v125
	v_mul_f32_e32 v121, v127, v127
	v_fmac_f32_e32 v120, v124, v124
	v_fmac_f32_e32 v121, v126, v126
	v_add_f32_e32 v120, v120, v121
	v_mul_f32_e32 v121, v213, v213
	v_fmac_f32_e32 v121, v212, v212
	v_add_f32_e32 v120, v121, v120
	v_mul_f32_e32 v121, v215, v215
	v_fmac_f32_e32 v121, v214, v214
	v_add_f32_e32 v124, v121, v120
	v_lshlrev_b32_e32 v120, 16, v152
	v_and_b32_e32 v121, 0xffff0000, v152
	v_lshlrev_b32_e32 v122, 16, v153
	v_and_b32_e32 v123, 0xffff0000, v153
	v_pk_fma_f32 v[120:121], v[196:197], s[34:35], v[120:121] op_sel_hi:[1,0,1]
	v_pk_fma_f32 v[122:123], v[198:199], s[34:35], v[122:123] op_sel_hi:[1,0,1]
	v_pk_add_f32 v[116:117], v[116:117], v[120:121]
	v_pk_add_f32 v[118:119], v[118:119], v[122:123]
	v_lshlrev_b32_e32 v120, 16, v154
	v_and_b32_e32 v121, 0xffff0000, v154
	v_lshlrev_b32_e32 v122, 16, v155
	v_and_b32_e32 v123, 0xffff0000, v155
	v_pk_fma_f32 v[120:121], v[196:197], s[34:35], v[120:121] op_sel_hi:[1,0,1]
	v_pk_fma_f32 v[122:123], v[198:199], s[34:35], v[122:123] op_sel_hi:[1,0,1]
	v_pk_add_f32 v[120:121], v[112:113], v[120:121]
	v_pk_add_f32 v[122:123], v[114:115], v[122:123]
	v_cvt_pk_bf16_f32 v112, v116, v117
	v_cvt_pk_bf16_f32 v113, v118, v119
	v_cvt_pk_bf16_f32 v114, v120, v121
	v_cvt_pk_bf16_f32 v115, v122, v123
	global_store_dwordx4 v[216:217], v[112:115], off offset:256
	s_nop 1
	v_mul_f32_e32 v112, v117, v117
	v_mul_f32_e32 v113, v119, v119
	v_fmac_f32_e32 v112, v116, v116
	v_fmac_f32_e32 v113, v118, v118
	v_add_f32_e32 v112, v112, v113
	v_mul_f32_e32 v113, v121, v121
	v_fmac_f32_e32 v113, v120, v120
	v_add_f32_e32 v112, v113, v112
	v_mul_f32_e32 v113, v123, v123
	v_fmac_f32_e32 v113, v122, v122
	v_add_f32_e32 v112, v113, v112
	v_add_f32_e32 v112, v124, v112
	v_mov_b32_e32 v113, v112
	s_nop 1
	v_permlane16_swap_b32_e32 v112, v113
	s_waitcnt lgkmcnt(0)
	v_add_f32_e32 v112, v112, v113
	v_mov_b32_e32 v113, v112
	s_nop 1
	v_permlane32_swap_b32_e32 v112, v113
	s_and_saveexec_b64 s[12:13], s[42:43]
	s_cbranch_execz .LBB0_272
	s_lshl_b32 s21, s36, 2
	s_or_b32 s22, s21, s76
	s_ashr_i32 s23, s22, 31
	s_lshl_b64 s[22:23], s[22:23], 18
	s_add_u32 s22, s74, s22
	s_addc_u32 s23, s75, s23
	s_waitcnt lgkmcnt(0)
	v_add_f32_e32 v114, v112, v113
	v_lshl_add_u64 v[112:113], v[194:195], 2, s[22:23]
	global_store_dword v[112:113], v114, off
; __device__ __forceinline__ float bflo(unsigned w) { return __uint_as_float(w << 16); }
;     template <int NM> __device__ __forceinline__ void round(const AccT& acc, const Unit& u, int ai, int m0, int wr, int wc, int fr, int fq) const {
;     ...
;         for (int mm = 0; mm < NM; ++mm) {
;             const int m = m0 + mm;
;             const int rl = ai * 128 + wr * 64 + m * 16 + fr; const int row = u.pm * 256 + rl;
;             const size_t off = (size_t)row * DM + u.pn * 256 + wc * 32 + 8 * fq;
;             float r = 1.f; if (MODE == 1) r = rs[((u.pm >> 3) & 3) * 256 + rl];
;             float ss = 0.f;
; #pragma unroll
;             for (int bj = 0; bj < 2; ++bj) {
;                 f32x4 d0, d1;
;                 if (MODE == 0) { d0 = acc[ai][bj][m][0] * alpha; d1 = acc[ai][bj][m][1] * alpha; }
;                 else {
;                     const u32x4 p = pv[mm][bj];
;                     const f32x4 a0 = acc[ai][bj][m][0] * r, a1 = acc[ai][bj][m][1] * r;
;                     d0 = (f32x4){fsigmoid(a0[0]) * bflo(p.x), fsigmoid(a0[1]) * bfhi(p.x), fsigmoid(a0[2]) * bflo(p.y), fsigmoid(a0[3]) * bfhi(p.y)};
;                     d1 = (f32x4){fsigmoid(a1[0]) * bflo(p.z), fsigmoid(a1[1]) * bfhi(p.z), fsigmoid(a1[2]) * bflo(p.w), fsigmoid(a1[3]) * bfhi(p.w)};
;                 }
;                 const u32x4 H = hv[mm][bj]; const u32x2 L = lv[mm][bj];
;                 const f32x4 o0 = ((f32x4){bflo(H.x), bfhi(H.x), bflo(H.y), bfhi(H.y)} + lo_unpack4(L.x)) + d0;
;                 const f32x4 o1 = ((f32x4){bflo(H.z), bfhi(H.z), bflo(H.w), bfhi(H.w)} + lo_unpack4(L.y)) + d1;
;                 u32x4 w; w.x = cvt_pk_bf16(o0[0], o0[1]); w.y = cvt_pk_bf16(o0[2], o0[3]); w.z = cvt_pk_bf16(o1[0], o1[1]); w.w = cvt_pk_bf16(o1[2], o1[3]);
;                 u32x2 wl; wl.x = lo_pack4(o0[0] - bflo(w.x), o0[1] - bfhi(w.x), o0[2] - bflo(w.y), o0[3] - bfhi(w.y));
;                 wl.y = lo_pack4(o1[0] - bflo(w.z), o1[1] - bfhi(w.z), o1[2] - bflo(w.w), o1[3] - bfhi(w.w));
;                 *GP(u32x4, hout + off + bj * 128) = w; (void)wl;
;                 ss += (o0[0] * o0[0] + o0[1] * o0[1]) + (o0[2] * o0[2] + o0[3] * o0[3]) + (o1[0] * o1[0] + o1[1] * o1[1]) + (o1[2] * o1[2] + o1[3] * o1[3]);
;             }
;             ss += __shfl_xor(ss, 16); ss += __shfl_xor(ss, 32);
;             if (fq == 0) *GP(float, ssp + (size_t)(u.pn * 4 + wc) * TT + row) = ss;
.LBB0_272:
	s_or_b64 exec, exec, s[12:13]
	v_pk_mul_f32 v[114:115], v[196:197], s[34:35] op_sel_hi:[1,0]
	v_lshlrev_b32_e32 v120, 16, v148
	v_and_b32_e32 v121, 0xffff0000, v148
	v_pk_add_f32 v[120:121], v[114:115], v[120:121]
	s_waitcnt lgkmcnt(0)
	v_pk_mul_f32 v[112:113], v[198:199], s[34:35] op_sel_hi:[1,0]
	v_lshlrev_b32_e32 v122, 16, v149
	v_and_b32_e32 v123, 0xffff0000, v149
	v_pk_add_f32 v[108:109], v[108:109], v[120:121]
	v_lshlrev_b32_e32 v120, 16, v150
	v_and_b32_e32 v121, 0xffff0000, v150
	v_pk_add_f32 v[122:123], v[112:113], v[122:123]
	v_pk_add_f32 v[120:121], v[114:115], v[120:121]
	v_pk_add_f32 v[110:111], v[110:111], v[122:123]
	v_pk_add_f32 v[120:121], v[104:105], v[120:121]
	v_cvt_pk_bf16_f32 v104, v108, v109
	v_mul_f32_e32 v109, v109, v109
	v_fmac_f32_e32 v109, v108, v108
	v_mul_f32_e32 v108, v111, v111
	v_lshlrev_b32_e32 v122, 16, v151
	v_and_b32_e32 v123, 0xffff0000, v151
	v_fmac_f32_e32 v108, v110, v110
	v_pk_add_f32 v[122:123], v[112:113], v[122:123]
	v_add_f32_e32 v108, v109, v108
	v_mul_f32_e32 v109, v121, v121
	v_pk_add_f32 v[122:123], v[106:107], v[122:123]
	v_fmac_f32_e32 v109, v120, v120
	v_add_f32_e32 v108, v109, v108
	v_mul_f32_e32 v109, v123, v123
	v_fmac_f32_e32 v109, v122, v122
	v_cvt_pk_bf16_f32 v106, v120, v121
	v_add_f32_e32 v120, v109, v108
	v_lshlrev_b32_e32 v108, 16, v144
	v_and_b32_e32 v109, 0xffff0000, v144
	v_cvt_pk_bf16_f32 v105, v110, v111
	v_lshlrev_b32_e32 v110, 16, v145
	v_and_b32_e32 v111, 0xffff0000, v145
	v_pk_add_f32 v[108:109], v[114:115], v[108:109]
	v_pk_add_f32 v[110:111], v[112:113], v[110:111]
	v_pk_add_f32 v[100:101], v[100:101], v[108:109]
	v_lshlrev_b32_e32 v108, 16, v146
	v_and_b32_e32 v109, 0xffff0000, v146
	v_pk_add_f32 v[102:103], v[102:103], v[110:111]
	v_pk_add_f32 v[108:109], v[114:115], v[108:109]
	v_lshlrev_b32_e32 v110, 16, v147
	v_pk_add_f32 v[108:109], v[96:97], v[108:109]
	v_mul_f32_e32 v96, v101, v101
	v_mul_f32_e32 v97, v103, v103
	v_and_b32_e32 v111, 0xffff0000, v147
	v_fmac_f32_e32 v96, v100, v100
	v_fmac_f32_e32 v97, v102, v102
	v_pk_add_f32 v[110:111], v[112:113], v[110:111]
	v_add_f32_e32 v96, v96, v97
	v_mul_f32_e32 v97, v109, v109
	v_pk_add_f32 v[110:111], v[98:99], v[110:111]
	v_fmac_f32_e32 v97, v108, v108
	v_add_f32_e32 v96, v97, v96
	v_mul_f32_e32 v97, v111, v111
	v_fmac_f32_e32 v97, v110, v110
	s_or_b32 s21, s20, 16
	v_add_f32_e32 v96, v97, v96
	v_add_u32_e32 v116, s21, v203
	v_add_f32_e32 v99, v120, v96
	v_ashrrev_i32_e32 v117, 31, v116
	v_mov_b32_e32 v120, v99
	s_nop 1
	v_permlane16_swap_b32_e32 v99, v120
	v_lshlrev_b64 v[118:119], 11, v[116:117]
	v_lshl_add_u64 v[118:119], s[14:15], 0, v[118:119]
	v_lshl_add_u64 v[118:119], s[52:53], 1, v[118:119]
	v_lshl_add_u64 v[96:97], v[118:119], 0, s[62:63]
	v_lshl_add_u64 v[118:119], v[96:97], 0, v[168:169]
	s_waitcnt lgkmcnt(0)
	v_add_f32_e32 v96, v99, v120
	v_mov_b32_e32 v97, v96
	s_nop 1
	v_permlane32_swap_b32_e32 v96, v97
	v_cvt_pk_bf16_f32 v107, v122, v123
	v_cvt_pk_bf16_f32 v98, v100, v101
	v_cvt_pk_bf16_f32 v99, v102, v103
	v_cvt_pk_bf16_f32 v100, v108, v109
	v_cvt_pk_bf16_f32 v101, v110, v111
	global_store_dwordx4 v[118:119], v[104:107], off
	global_store_dwordx4 v[118:119], v[98:101], off offset:256
	s_and_saveexec_b64 s[12:13], s[42:43]
	s_cbranch_execz .LBB0_274
	s_lshl_b32 s22, s36, 2
	s_or_b32 s22, s22, s76
	s_ashr_i32 s23, s22, 31
	s_lshl_b64 s[22:23], s[22:23], 18
	s_add_u32 s22, s74, s22
	s_addc_u32 s23, s75, s23
	s_waitcnt lgkmcnt(0)
	v_add_f32_e32 v98, v96, v97
	v_lshl_add_u64 v[96:97], v[116:117], 2, s[22:23]
	global_store_dword v[96:97], v98, off
.LBB0_274:
	s_or_b64 exec, exec, s[12:13]
	v_lshlrev_b32_e32 v100, 16, v140
	v_and_b32_e32 v101, 0xffff0000, v140
	v_pk_add_f32 v[100:101], v[114:115], v[100:101]
	v_lshlrev_b32_e32 v102, 16, v141
	v_and_b32_e32 v103, 0xffff0000, v141
	v_pk_add_f32 v[92:93], v[92:93], v[100:101]
	v_lshlrev_b32_e32 v100, 16, v142
	v_and_b32_e32 v101, 0xffff0000, v142
	v_pk_add_f32 v[102:103], v[112:113], v[102:103]
	v_pk_add_f32 v[100:101], v[114:115], v[100:101]
	v_pk_add_f32 v[94:95], v[94:95], v[102:103]
	v_pk_add_f32 v[100:101], v[88:89], v[100:101]
	v_cvt_pk_bf16_f32 v88, v92, v93
	v_mul_f32_e32 v93, v93, v93
	v_fmac_f32_e32 v93, v92, v92
	v_mul_f32_e32 v92, v95, v95
	v_lshlrev_b32_e32 v102, 16, v143
	v_and_b32_e32 v103, 0xffff0000, v143
	v_fmac_f32_e32 v92, v94, v94
	v_pk_add_f32 v[102:103], v[112:113], v[102:103]
	v_add_f32_e32 v92, v93, v92
	v_mul_f32_e32 v93, v101, v101
	v_pk_add_f32 v[102:103], v[90:91], v[102:103]
	v_fmac_f32_e32 v93, v100, v100
	v_add_f32_e32 v92, v93, v92
	v_mul_f32_e32 v93, v103, v103
	v_fmac_f32_e32 v93, v102, v102
	v_cvt_pk_bf16_f32 v90, v100, v101
	v_add_f32_e32 v100, v93, v92
	v_lshlrev_b32_e32 v92, 16, v136
	v_and_b32_e32 v93, 0xffff0000, v136
	v_cvt_pk_bf16_f32 v89, v94, v95
	v_lshlrev_b32_e32 v94, 16, v137
	v_and_b32_e32 v95, 0xffff0000, v137
	v_pk_add_f32 v[92:93], v[114:115], v[92:93]
	v_pk_add_f32 v[94:95], v[112:113], v[94:95]
	v_pk_add_f32 v[84:85], v[84:85], v[92:93]
	v_lshlrev_b32_e32 v92, 16, v138
	v_and_b32_e32 v93, 0xffff0000, v138
	v_pk_add_f32 v[86:87], v[86:87], v[94:95]
	v_pk_add_f32 v[92:93], v[114:115], v[92:93]
	v_lshlrev_b32_e32 v94, 16, v139
	v_pk_add_f32 v[92:93], v[80:81], v[92:93]
	v_mul_f32_e32 v80, v85, v85
	v_mul_f32_e32 v81, v87, v87
	v_and_b32_e32 v95, 0xffff0000, v139
	v_fmac_f32_e32 v80, v84, v84
	v_fmac_f32_e32 v81, v86, v86
	v_pk_add_f32 v[94:95], v[112:113], v[94:95]
	v_add_f32_e32 v80, v80, v81
	v_mul_f32_e32 v81, v93, v93
	v_pk_add_f32 v[94:95], v[82:83], v[94:95]
	v_fmac_f32_e32 v81, v92, v92
	v_add_f32_e32 v80, v81, v80
	v_mul_f32_e32 v81, v95, v95
	v_fmac_f32_e32 v81, v94, v94
	s_or_b32 s22, s20, 32
	v_add_f32_e32 v80, v81, v80
	v_add_u32_e32 v96, s22, v203
	v_add_f32_e32 v83, v100, v80
	s_waitcnt lgkmcnt(0)
	v_ashrrev_i32_e32 v97, 31, v96
	v_mov_b32_e32 v100, v83
	s_nop 1
	v_permlane16_swap_b32_e32 v83, v100
	v_lshlrev_b64 v[98:99], 11, v[96:97]
	v_lshl_add_u64 v[98:99], s[14:15], 0, v[98:99]
	v_lshl_add_u64 v[98:99], s[52:53], 1, v[98:99]
	v_lshl_add_u64 v[80:81], v[98:99], 0, s[62:63]
	v_lshl_add_u64 v[98:99], v[80:81], 0, v[168:169]
	s_waitcnt lgkmcnt(0)
	v_add_f32_e32 v80, v83, v100
	v_mov_b32_e32 v81, v80
	s_nop 1
	v_permlane32_swap_b32_e32 v80, v81
	v_cvt_pk_bf16_f32 v91, v102, v103
	v_cvt_pk_bf16_f32 v82, v84, v85
	v_cvt_pk_bf16_f32 v83, v86, v87
	v_cvt_pk_bf16_f32 v84, v92, v93
	v_cvt_pk_bf16_f32 v85, v94, v95
	global_store_dwordx4 v[98:99], v[88:91], off
	global_store_dwordx4 v[98:99], v[82:85], off offset:256
	s_and_saveexec_b64 s[12:13], s[42:43]
	s_cbranch_execz .LBB0_276
	s_lshl_b32 s23, s36, 2
	s_or_b32 s24, s23, s76
	s_ashr_i32 s25, s24, 31
	s_lshl_b64 s[24:25], s[24:25], 18
	s_add_u32 s24, s74, s24
	s_addc_u32 s25, s75, s25
	s_waitcnt lgkmcnt(0)
	v_add_f32_e32 v82, v80, v81
	v_lshl_add_u64 v[80:81], v[96:97], 2, s[24:25]
	global_store_dword v[80:81], v82, off
; __device__ __forceinline__ float bflo(unsigned w) { return __uint_as_float(w << 16); }
;     template <int NM> __device__ __forceinline__ void round(const AccT& acc, const Unit& u, int ai, int m0, int wr, int wc, int fr, int fq) const {
;     ...
;         for (int mm = 0; mm < NM; ++mm) {
;             const int rl = ai * 128 + wr * 64 + (m0 + mm) * 16 + fr;
;             const size_t off = (size_t)(u.pm * 256 + rl) * DM + u.pn * 256 + wc * 32 + 8 * fq;
; #pragma unroll
;             for (int bj = 0; bj < 2; ++bj) {
;                 hv[mm][bj] = *GP(const u32x4, hin + off + bj * 128); lv[mm][bj] = (u32x2){0u, 0u};
;                 if (MODE == 1) pv[mm][bj] = *GP(const u32x4, proj + off + bj * 128);
;             }
;         }
; #pragma unroll
;         for (int mm = 0; mm < NM; ++mm) {
;             const int m = m0 + mm;
;             const int rl = ai * 128 + wr * 64 + m * 16 + fr; const int row = u.pm * 256 + rl;
;             const size_t off = (size_t)row * DM + u.pn * 256 + wc * 32 + 8 * fq;
;             float r = 1.f; if (MODE == 1) r = rs[((u.pm >> 3) & 3) * 256 + rl];
;             float ss = 0.f;
; #pragma unroll
;             for (int bj = 0; bj < 2; ++bj) {
;                 f32x4 d0, d1;
;                 if (MODE == 0) { d0 = acc[ai][bj][m][0] * alpha; d1 = acc[ai][bj][m][1] * alpha; }
;                 else {
;                     const u32x4 p = pv[mm][bj];
;                     const f32x4 a0 = acc[ai][bj][m][0] * r, a1 = acc[ai][bj][m][1] * r;
;                     d0 = (f32x4){fsigmoid(a0[0]) * bflo(p.x), fsigmoid(a0[1]) * bfhi(p.x), fsigmoid(a0[2]) * bflo(p.y), fsigmoid(a0[3]) * bfhi(p.y)};
;                     d1 = (f32x4){fsigmoid(a1[0]) * bflo(p.z), fsigmoid(a1[1]) * bfhi(p.z), fsigmoid(a1[2]) * bflo(p.w), fsigmoid(a1[3]) * bfhi(p.w)};
;                 }
;                 const u32x4 H = hv[mm][bj]; const u32x2 L = lv[mm][bj];
;                 const f32x4 o0 = ((f32x4){bflo(H.x), bfhi(H.x), bflo(H.y), bfhi(H.y)} + lo_unpack4(L.x)) + d0;
;                 const f32x4 o1 = ((f32x4){bflo(H.z), bfhi(H.z), bflo(H.w), bfhi(H.w)} + lo_unpack4(L.y)) + d1;
;                 u32x4 w; w.x = cvt_pk_bf16(o0[0], o0[1]); w.y = cvt_pk_bf16(o0[2], o0[3]); w.z = cvt_pk_bf16(o1[0], o1[1]); w.w = cvt_pk_bf16(o1[2], o1[3]);
;                 u32x2 wl; wl.x = lo_pack4(o0[0] - bflo(w.x), o0[1] - bfhi(w.x), o0[2] - bflo(w.y), o0[3] - bfhi(w.y));
.LBB0_276:
	s_or_b64 exec, exec, s[12:13]
	v_lshlrev_b32_e32 v84, 16, v132
	v_and_b32_e32 v85, 0xffff0000, v132
	v_pk_add_f32 v[84:85], v[114:115], v[84:85]
	v_lshlrev_b32_e32 v86, 16, v133
	v_and_b32_e32 v87, 0xffff0000, v133
	v_pk_add_f32 v[76:77], v[76:77], v[84:85]
	v_lshlrev_b32_e32 v84, 16, v134
	v_and_b32_e32 v85, 0xffff0000, v134
	v_pk_add_f32 v[86:87], v[112:113], v[86:87]
	v_pk_add_f32 v[84:85], v[114:115], v[84:85]
	v_pk_add_f32 v[78:79], v[78:79], v[86:87]
	v_pk_add_f32 v[84:85], v[72:73], v[84:85]
	v_cvt_pk_bf16_f32 v72, v76, v77
	v_mul_f32_e32 v77, v77, v77
	v_fmac_f32_e32 v77, v76, v76
	v_mul_f32_e32 v76, v79, v79
	v_lshlrev_b32_e32 v86, 16, v135
	v_and_b32_e32 v87, 0xffff0000, v135
	v_fmac_f32_e32 v76, v78, v78
	v_pk_add_f32 v[86:87], v[112:113], v[86:87]
	v_add_f32_e32 v76, v77, v76
	v_mul_f32_e32 v77, v85, v85
	v_pk_add_f32 v[86:87], v[74:75], v[86:87]
	v_fmac_f32_e32 v77, v84, v84
	v_add_f32_e32 v76, v77, v76
	v_mul_f32_e32 v77, v87, v87
	v_fmac_f32_e32 v77, v86, v86
	v_cvt_pk_bf16_f32 v74, v84, v85
	v_add_f32_e32 v84, v77, v76
	v_lshlrev_b32_e32 v76, 16, v128
	v_and_b32_e32 v77, 0xffff0000, v128
	v_cvt_pk_bf16_f32 v73, v78, v79
	v_lshlrev_b32_e32 v78, 16, v129
	v_and_b32_e32 v79, 0xffff0000, v129
	v_pk_add_f32 v[76:77], v[114:115], v[76:77]
	v_pk_add_f32 v[78:79], v[112:113], v[78:79]
	v_pk_add_f32 v[68:69], v[68:69], v[76:77]
	v_lshlrev_b32_e32 v76, 16, v130
	v_and_b32_e32 v77, 0xffff0000, v130
	v_pk_add_f32 v[70:71], v[70:71], v[78:79]
	v_pk_add_f32 v[76:77], v[114:115], v[76:77]
	v_lshlrev_b32_e32 v78, 16, v131
	v_pk_add_f32 v[76:77], v[64:65], v[76:77]
	v_mul_f32_e32 v64, v69, v69
	v_mul_f32_e32 v65, v71, v71
	v_and_b32_e32 v79, 0xffff0000, v131
	v_fmac_f32_e32 v64, v68, v68
	v_fmac_f32_e32 v65, v70, v70
	v_pk_add_f32 v[78:79], v[112:113], v[78:79]
	v_add_f32_e32 v64, v64, v65
	v_mul_f32_e32 v65, v77, v77
	v_pk_add_f32 v[78:79], v[66:67], v[78:79]
	v_fmac_f32_e32 v65, v76, v76
	v_add_f32_e32 v64, v65, v64
	v_mul_f32_e32 v65, v79, v79
	v_fmac_f32_e32 v65, v78, v78
	s_or_b32 s23, s20, 48
	v_add_f32_e32 v64, v65, v64
	v_add_u32_e32 v80, s23, v203
	v_add_f32_e32 v67, v84, v64
	s_waitcnt lgkmcnt(0)
	v_ashrrev_i32_e32 v81, 31, v80
	v_mov_b32_e32 v84, v67
	s_nop 1
	v_permlane16_swap_b32_e32 v67, v84
	v_lshlrev_b64 v[82:83], 11, v[80:81]
	v_lshl_add_u64 v[82:83], s[14:15], 0, v[82:83]
	v_lshl_add_u64 v[82:83], s[52:53], 1, v[82:83]
	v_lshl_add_u64 v[64:65], v[82:83], 0, s[62:63]
	v_lshl_add_u64 v[82:83], v[64:65], 0, v[168:169]
	s_waitcnt lgkmcnt(0)
	v_add_f32_e32 v64, v67, v84
	v_mov_b32_e32 v65, v64
	s_nop 1
	v_permlane32_swap_b32_e32 v64, v65
	v_cvt_pk_bf16_f32 v75, v86, v87
	v_cvt_pk_bf16_f32 v66, v68, v69
	v_cvt_pk_bf16_f32 v67, v70, v71
	v_cvt_pk_bf16_f32 v68, v76, v77
	v_cvt_pk_bf16_f32 v69, v78, v79
	global_store_dwordx4 v[82:83], v[72:75], off
	global_store_dwordx4 v[82:83], v[66:69], off offset:256
	s_and_saveexec_b64 s[12:13], s[42:43]
	s_cbranch_execz .LBB0_278
	s_lshl_b32 s24, s36, 2
	s_or_b32 s24, s24, s76
	s_ashr_i32 s25, s24, 31
	s_lshl_b64 s[24:25], s[24:25], 18
	s_add_u32 s24, s74, s24
	s_addc_u32 s25, s75, s25
	s_waitcnt lgkmcnt(0)
	v_add_f32_e32 v66, v64, v65
	v_lshl_add_u64 v[64:65], v[80:81], 2, s[24:25]
	global_store_dword v[64:65], v66, off
.LBB0_278:
	s_or_b64 exec, exec, s[12:13]
	v_add_u32_e32 v92, s20, v205
	v_ashrrev_i32_e32 v93, 31, v92
	v_lshlrev_b64 v[98:99], 11, v[92:93]
	s_waitcnt lgkmcnt(0)
	v_lshl_add_u64 v[64:65], v[192:193], 0, v[98:99]
	global_load_dwordx4 v[94:97], v[64:65], off
	global_load_dwordx4 v[88:91], v[64:65], off offset:256
	v_or_b32_e32 v64, 16, v92
	v_ashrrev_i32_e32 v65, 31, v64
	v_lshlrev_b64 v[64:65], 11, v[64:65]
	v_lshl_add_u64 v[64:65], v[192:193], 0, v[64:65]
	global_load_dwordx4 v[84:87], v[64:65], off
	global_load_dwordx4 v[80:83], v[64:65], off offset:256
	v_or_b32_e32 v64, 32, v92
	v_ashrrev_i32_e32 v65, 31, v64
	v_lshlrev_b64 v[64:65], 11, v[64:65]
	v_lshl_add_u64 v[64:65], v[192:193], 0, v[64:65]
	global_load_dwordx4 v[76:79], v[64:65], off
	global_load_dwordx4 v[72:75], v[64:65], off offset:256
	v_or_b32_e32 v64, 48, v92
	v_ashrrev_i32_e32 v65, 31, v64
	v_lshlrev_b64 v[64:65], 11, v[64:65]
	v_lshl_add_u64 v[64:65], v[192:193], 0, v[64:65]
	global_load_dwordx4 v[68:71], v[64:65], off
	s_nop 0
	global_load_dwordx4 v[64:67], v[64:65], off offset:256
	v_lshl_add_u64 v[98:99], s[14:15], 0, v[98:99]
	v_lshl_add_u64 v[98:99], s[52:53], 1, v[98:99]
	v_lshl_add_u64 v[98:99], v[98:99], 0, s[62:63]
	v_lshl_add_u64 v[98:99], v[98:99], 0, v[168:169]
	s_waitcnt vmcnt(7)
	v_lshlrev_b32_e32 v100, 16, v94
	v_and_b32_e32 v101, 0xffff0000, v94
	v_lshlrev_b32_e32 v94, 16, v95
	v_and_b32_e32 v95, 0xffff0000, v95
	v_pk_add_f32 v[94:95], v[112:113], v[94:95]
	v_pk_add_f32 v[100:101], v[114:115], v[100:101]
	v_pk_add_f32 v[62:63], v[62:63], v[94:95]
	v_lshlrev_b32_e32 v94, 16, v96
	v_and_b32_e32 v95, 0xffff0000, v96
	v_lshlrev_b32_e32 v96, 16, v97
	v_and_b32_e32 v97, 0xffff0000, v97
	v_pk_add_f32 v[94:95], v[114:115], v[94:95]
	v_pk_add_f32 v[96:97], v[112:113], v[96:97]
	v_pk_add_f32 v[60:61], v[60:61], v[100:101]
	v_pk_add_f32 v[96:97], v[58:59], v[96:97]
	v_pk_add_f32 v[94:95], v[56:57], v[94:95]
	v_cvt_pk_bf16_f32 v56, v60, v61
	v_cvt_pk_bf16_f32 v57, v62, v63
	v_cvt_pk_bf16_f32 v58, v94, v95
	v_cvt_pk_bf16_f32 v59, v96, v97
	global_store_dwordx4 v[98:99], v[56:59], off
	s_nop 1
	v_mul_f32_e32 v56, v61, v61
	v_mul_f32_e32 v57, v63, v63
	v_fmac_f32_e32 v56, v60, v60
	v_fmac_f32_e32 v57, v62, v62
	v_add_f32_e32 v56, v56, v57
	v_mul_f32_e32 v57, v95, v95
	v_fmac_f32_e32 v57, v94, v94
	v_add_f32_e32 v56, v57, v56
	v_mul_f32_e32 v57, v97, v97
	v_fmac_f32_e32 v57, v96, v96
	v_add_f32_e32 v60, v57, v56
	s_waitcnt vmcnt(7)
; __device__ __forceinline__ float bflo(unsigned w) { return __uint_as_float(w << 16); }
;     template <int NM> __device__ __forceinline__ void round(const AccT& acc, const Unit& u, int ai, int m0, int wr, int wc, int fr, int fq) const {
;     ...
;         for (int mm = 0; mm < NM; ++mm) {
;             const int m = m0 + mm;
;             const int rl = ai * 128 + wr * 64 + m * 16 + fr; const int row = u.pm * 256 + rl;
;             const size_t off = (size_t)row * DM + u.pn * 256 + wc * 32 + 8 * fq;
;             float r = 1.f; if (MODE == 1) r = rs[((u.pm >> 3) & 3) * 256 + rl];
;             float ss = 0.f;
; #pragma unroll
;             for (int bj = 0; bj < 2; ++bj) {
;                 f32x4 d0, d1;
;                 if (MODE == 0) { d0 = acc[ai][bj][m][0] * alpha; d1 = acc[ai][bj][m][1] * alpha; }
;                 else {
;                     const u32x4 p = pv[mm][bj];
;                     const f32x4 a0 = acc[ai][bj][m][0] * r, a1 = acc[ai][bj][m][1] * r;
;                     d0 = (f32x4){fsigmoid(a0[0]) * bflo(p.x), fsigmoid(a0[1]) * bfhi(p.x), fsigmoid(a0[2]) * bflo(p.y), fsigmoid(a0[3]) * bfhi(p.y)};
;                     d1 = (f32x4){fsigmoid(a1[0]) * bflo(p.z), fsigmoid(a1[1]) * bfhi(p.z), fsigmoid(a1[2]) * bflo(p.w), fsigmoid(a1[3]) * bfhi(p.w)};
;                 }
;                 const u32x4 H = hv[mm][bj]; const u32x2 L = lv[mm][bj];
;                 const f32x4 o0 = ((f32x4){bflo(H.x), bfhi(H.x), bflo(H.y), bfhi(H.y)} + lo_unpack4(L.x)) + d0;
;                 const f32x4 o1 = ((f32x4){bflo(H.z), bfhi(H.z), bflo(H.w), bfhi(H.w)} + lo_unpack4(L.y)) + d1;
;                 u32x4 w; w.x = cvt_pk_bf16(o0[0], o0[1]); w.y = cvt_pk_bf16(o0[2], o0[3]); w.z = cvt_pk_bf16(o1[0], o1[1]); w.w = cvt_pk_bf16(o1[2], o1[3]);
;                 u32x2 wl; wl.x = lo_pack4(o0[0] - bflo(w.x), o0[1] - bfhi(w.x), o0[2] - bflo(w.y), o0[3] - bfhi(w.y));
;                 wl.y = lo_pack4(o1[0] - bflo(w.z), o1[1] - bfhi(w.z), o1[2] - bflo(w.w), o1[3] - bfhi(w.w));
;                 *GP(u32x4, hout + off + bj * 128) = w; (void)wl;
;                 ss += (o0[0] * o0[0] + o0[1] * o0[1]) + (o0[2] * o0[2] + o0[3] * o0[3]) + (o1[0] * o1[0] + o1[1] * o1[1]) + (o1[2] * o1[2] + o1[3] * o1[3]);
;             }
;             ss += __shfl_xor(ss, 16); ss += __shfl_xor(ss, 32);
;             if (fq == 0) *GP(float, ssp + (size_t)(u.pn * 4 + wc) * TT + row) = ss;
	v_lshlrev_b32_e32 v56, 16, v88
	v_and_b32_e32 v57, 0xffff0000, v88
	v_lshlrev_b32_e32 v58, 16, v89
	v_and_b32_e32 v59, 0xffff0000, v89
	v_pk_add_f32 v[56:57], v[114:115], v[56:57]
	v_pk_add_f32 v[58:59], v[112:113], v[58:59]
	v_pk_add_f32 v[52:53], v[52:53], v[56:57]
	v_pk_add_f32 v[54:55], v[54:55], v[58:59]
	v_lshlrev_b32_e32 v56, 16, v90
	v_and_b32_e32 v57, 0xffff0000, v90
	v_lshlrev_b32_e32 v58, 16, v91
	v_and_b32_e32 v59, 0xffff0000, v91
	v_pk_add_f32 v[56:57], v[114:115], v[56:57]
	v_pk_add_f32 v[58:59], v[112:113], v[58:59]
	v_pk_add_f32 v[56:57], v[48:49], v[56:57]
	v_pk_add_f32 v[58:59], v[50:51], v[58:59]
	v_cvt_pk_bf16_f32 v48, v52, v53
	v_cvt_pk_bf16_f32 v49, v54, v55
	v_cvt_pk_bf16_f32 v50, v56, v57
	v_cvt_pk_bf16_f32 v51, v58, v59
	global_store_dwordx4 v[98:99], v[48:51], off offset:256
	s_nop 1
	v_mul_f32_e32 v48, v53, v53
	v_mul_f32_e32 v49, v55, v55
	v_fmac_f32_e32 v48, v52, v52
	v_fmac_f32_e32 v49, v54, v54
	v_add_f32_e32 v48, v48, v49
	v_mul_f32_e32 v49, v57, v57
	v_fmac_f32_e32 v49, v56, v56
	v_add_f32_e32 v48, v49, v48
	v_mul_f32_e32 v49, v59, v59
	v_fmac_f32_e32 v49, v58, v58
	v_add_f32_e32 v48, v49, v48
	v_add_f32_e32 v48, v60, v48
	v_mov_b32_e32 v49, v48
	s_nop 1
	v_permlane16_swap_b32_e32 v48, v49
	s_waitcnt lgkmcnt(0)
	v_add_f32_e32 v48, v48, v49
	v_mov_b32_e32 v49, v48
	s_nop 1
	v_permlane32_swap_b32_e32 v48, v49
	s_and_saveexec_b64 s[12:13], s[42:43]
	s_cbranch_execz .LBB0_280
	s_lshl_b32 s20, s36, 2
	s_or_b32 s24, s20, s76
	s_ashr_i32 s25, s24, 31
	s_lshl_b64 s[24:25], s[24:25], 18
	s_add_u32 s24, s74, s24
	s_addc_u32 s25, s75, s25
	s_waitcnt lgkmcnt(0)
	v_add_f32_e32 v50, v48, v49
	v_lshl_add_u64 v[48:49], v[92:93], 2, s[24:25]
	global_store_dword v[48:49], v50, off
.LBB0_280:
	s_or_b64 exec, exec, s[12:13]
	s_waitcnt vmcnt(7)
	v_lshlrev_b32_e32 v52, 16, v84
	v_and_b32_e32 v53, 0xffff0000, v84
	v_pk_add_f32 v[52:53], v[114:115], v[52:53]
	v_lshlrev_b32_e32 v54, 16, v85
	v_and_b32_e32 v55, 0xffff0000, v85
	v_pk_add_f32 v[44:45], v[44:45], v[52:53]
	v_lshlrev_b32_e32 v52, 16, v86
	v_and_b32_e32 v53, 0xffff0000, v86
	v_pk_add_f32 v[54:55], v[112:113], v[54:55]
	v_pk_add_f32 v[52:53], v[114:115], v[52:53]
	v_pk_add_f32 v[46:47], v[46:47], v[54:55]
	v_pk_add_f32 v[52:53], v[40:41], v[52:53]
	v_cvt_pk_bf16_f32 v40, v44, v45
	v_mul_f32_e32 v45, v45, v45
	v_fmac_f32_e32 v45, v44, v44
	v_mul_f32_e32 v44, v47, v47
	v_lshlrev_b32_e32 v54, 16, v87
	v_and_b32_e32 v55, 0xffff0000, v87
	v_fmac_f32_e32 v44, v46, v46
	v_pk_add_f32 v[54:55], v[112:113], v[54:55]
	v_add_f32_e32 v44, v45, v44
	v_mul_f32_e32 v45, v53, v53
	v_pk_add_f32 v[54:55], v[42:43], v[54:55]
	v_fmac_f32_e32 v45, v52, v52
	v_add_f32_e32 v44, v45, v44
	v_mul_f32_e32 v45, v55, v55
	v_fmac_f32_e32 v45, v54, v54
	v_cvt_pk_bf16_f32 v42, v52, v53
	v_add_f32_e32 v52, v45, v44
	s_waitcnt vmcnt(6)
	v_lshlrev_b32_e32 v44, 16, v80
	v_and_b32_e32 v45, 0xffff0000, v80
	v_cvt_pk_bf16_f32 v41, v46, v47
	v_lshlrev_b32_e32 v46, 16, v81
	v_and_b32_e32 v47, 0xffff0000, v81
	v_pk_add_f32 v[44:45], v[114:115], v[44:45]
	v_pk_add_f32 v[46:47], v[112:113], v[46:47]
	v_pk_add_f32 v[36:37], v[36:37], v[44:45]
	v_lshlrev_b32_e32 v44, 16, v82
	v_and_b32_e32 v45, 0xffff0000, v82
	v_pk_add_f32 v[38:39], v[38:39], v[46:47]
	v_pk_add_f32 v[44:45], v[114:115], v[44:45]
	v_lshlrev_b32_e32 v46, 16, v83
	v_pk_add_f32 v[44:45], v[32:33], v[44:45]
	v_mul_f32_e32 v32, v37, v37
	v_mul_f32_e32 v33, v39, v39
	v_and_b32_e32 v47, 0xffff0000, v83
	v_fmac_f32_e32 v32, v36, v36
	v_fmac_f32_e32 v33, v38, v38
	v_pk_add_f32 v[46:47], v[112:113], v[46:47]
	v_add_f32_e32 v32, v32, v33
	v_mul_f32_e32 v33, v45, v45
	v_pk_add_f32 v[46:47], v[34:35], v[46:47]
	v_fmac_f32_e32 v33, v44, v44
	v_add_f32_e32 v32, v33, v32
	v_mul_f32_e32 v33, v47, v47
	v_fmac_f32_e32 v33, v46, v46
	v_add_f32_e32 v32, v33, v32
	v_add_u32_e32 v48, s21, v205
	v_add_f32_e32 v35, v52, v32
	s_waitcnt lgkmcnt(0)
	v_ashrrev_i32_e32 v49, 31, v48
	v_mov_b32_e32 v52, v35
	s_nop 1
	v_permlane16_swap_b32_e32 v35, v52
	v_lshlrev_b64 v[50:51], 11, v[48:49]
	v_lshl_add_u64 v[50:51], s[14:15], 0, v[50:51]
	v_lshl_add_u64 v[50:51], s[52:53], 1, v[50:51]
	v_lshl_add_u64 v[32:33], v[50:51], 0, s[62:63]
	v_lshl_add_u64 v[50:51], v[32:33], 0, v[168:169]
	s_waitcnt lgkmcnt(0)
	v_add_f32_e32 v32, v35, v52
	v_mov_b32_e32 v33, v32
	s_nop 1
	v_permlane32_swap_b32_e32 v32, v33
	v_cvt_pk_bf16_f32 v43, v54, v55
	v_cvt_pk_bf16_f32 v34, v36, v37
	v_cvt_pk_bf16_f32 v35, v38, v39
	v_cvt_pk_bf16_f32 v36, v44, v45
	v_cvt_pk_bf16_f32 v37, v46, v47
	global_store_dwordx4 v[50:51], v[40:43], off
	global_store_dwordx4 v[50:51], v[34:37], off offset:256
	s_and_saveexec_b64 s[12:13], s[42:43]
	s_cbranch_execz .LBB0_282
	s_lshl_b32 s20, s36, 2
	s_or_b32 s20, s20, s76
	s_ashr_i32 s21, s20, 31
	s_lshl_b64 s[20:21], s[20:21], 18
	s_add_u32 s20, s74, s20
	s_addc_u32 s21, s75, s21
	s_waitcnt lgkmcnt(0)
	v_add_f32_e32 v34, v32, v33
	v_lshl_add_u64 v[32:33], v[48:49], 2, s[20:21]
	global_store_dword v[32:33], v34, off
; __device__ __forceinline__ float bflo(unsigned w) { return __uint_as_float(w << 16); }
;     template <int NM> __device__ __forceinline__ void round(const AccT& acc, const Unit& u, int ai, int m0, int wr, int wc, int fr, int fq) const {
;     ...
;         for (int mm = 0; mm < NM; ++mm) {
;             const int m = m0 + mm;
;             const int rl = ai * 128 + wr * 64 + m * 16 + fr; const int row = u.pm * 256 + rl;
;             const size_t off = (size_t)row * DM + u.pn * 256 + wc * 32 + 8 * fq;
;             float r = 1.f; if (MODE == 1) r = rs[((u.pm >> 3) & 3) * 256 + rl];
;             float ss = 0.f;
; #pragma unroll
;             for (int bj = 0; bj < 2; ++bj) {
;                 f32x4 d0, d1;
;                 if (MODE == 0) { d0 = acc[ai][bj][m][0] * alpha; d1 = acc[ai][bj][m][1] * alpha; }
;                 else {
;                     const u32x4 p = pv[mm][bj];
;                     const f32x4 a0 = acc[ai][bj][m][0] * r, a1 = acc[ai][bj][m][1] * r;
;                     d0 = (f32x4){fsigmoid(a0[0]) * bflo(p.x), fsigmoid(a0[1]) * bfhi(p.x), fsigmoid(a0[2]) * bflo(p.y), fsigmoid(a0[3]) * bfhi(p.y)};
;                     d1 = (f32x4){fsigmoid(a1[0]) * bflo(p.z), fsigmoid(a1[1]) * bfhi(p.z), fsigmoid(a1[2]) * bflo(p.w), fsigmoid(a1[3]) * bfhi(p.w)};
;                 }
;                 const u32x4 H = hv[mm][bj]; const u32x2 L = lv[mm][bj];
;                 const f32x4 o0 = ((f32x4){bflo(H.x), bfhi(H.x), bflo(H.y), bfhi(H.y)} + lo_unpack4(L.x)) + d0;
;                 const f32x4 o1 = ((f32x4){bflo(H.z), bfhi(H.z), bflo(H.w), bfhi(H.w)} + lo_unpack4(L.y)) + d1;
;                 u32x4 w; w.x = cvt_pk_bf16(o0[0], o0[1]); w.y = cvt_pk_bf16(o0[2], o0[3]); w.z = cvt_pk_bf16(o1[0], o1[1]); w.w = cvt_pk_bf16(o1[2], o1[3]);
;                 u32x2 wl; wl.x = lo_pack4(o0[0] - bflo(w.x), o0[1] - bfhi(w.x), o0[2] - bflo(w.y), o0[3] - bfhi(w.y));
;                 wl.y = lo_pack4(o1[0] - bflo(w.z), o1[1] - bfhi(w.z), o1[2] - bflo(w.w), o1[3] - bfhi(w.w));
;                 *GP(u32x4, hout + off + bj * 128) = w; (void)wl;
;                 ss += (o0[0] * o0[0] + o0[1] * o0[1]) + (o0[2] * o0[2] + o0[3] * o0[3]) + (o1[0] * o1[0] + o1[1] * o1[1]) + (o1[2] * o1[2] + o1[3] * o1[3]);
;             }
;             ss += __shfl_xor(ss, 16); ss += __shfl_xor(ss, 32);
;             if (fq == 0) *GP(float, ssp + (size_t)(u.pn * 4 + wc) * TT + row) = ss;
.LBB0_282:
	s_or_b64 exec, exec, s[12:13]
	s_waitcnt vmcnt(7)
	v_lshlrev_b32_e32 v36, 16, v76
	v_and_b32_e32 v37, 0xffff0000, v76
	v_pk_add_f32 v[36:37], v[114:115], v[36:37]
	v_lshlrev_b32_e32 v38, 16, v77
	v_and_b32_e32 v39, 0xffff0000, v77
	v_pk_add_f32 v[28:29], v[28:29], v[36:37]
	v_lshlrev_b32_e32 v36, 16, v78
	v_and_b32_e32 v37, 0xffff0000, v78
	v_pk_add_f32 v[38:39], v[112:113], v[38:39]
	v_pk_add_f32 v[36:37], v[114:115], v[36:37]
	v_pk_add_f32 v[30:31], v[30:31], v[38:39]
	v_pk_add_f32 v[36:37], v[24:25], v[36:37]
	v_cvt_pk_bf16_f32 v24, v28, v29
	v_mul_f32_e32 v29, v29, v29
	v_fmac_f32_e32 v29, v28, v28
	v_mul_f32_e32 v28, v31, v31
	v_lshlrev_b32_e32 v38, 16, v79
	v_and_b32_e32 v39, 0xffff0000, v79
	v_fmac_f32_e32 v28, v30, v30
	v_pk_add_f32 v[38:39], v[112:113], v[38:39]
	v_add_f32_e32 v28, v29, v28
	v_mul_f32_e32 v29, v37, v37
	v_pk_add_f32 v[38:39], v[26:27], v[38:39]
	v_fmac_f32_e32 v29, v36, v36
	v_add_f32_e32 v28, v29, v28
	v_mul_f32_e32 v29, v39, v39
	v_fmac_f32_e32 v29, v38, v38
	v_cvt_pk_bf16_f32 v26, v36, v37
	v_add_f32_e32 v36, v29, v28
	s_waitcnt vmcnt(6)
	v_lshlrev_b32_e32 v28, 16, v72
	v_and_b32_e32 v29, 0xffff0000, v72
	v_cvt_pk_bf16_f32 v25, v30, v31
	v_lshlrev_b32_e32 v30, 16, v73
	v_and_b32_e32 v31, 0xffff0000, v73
	v_pk_add_f32 v[28:29], v[114:115], v[28:29]
	v_pk_add_f32 v[30:31], v[112:113], v[30:31]
	v_pk_add_f32 v[20:21], v[20:21], v[28:29]
	v_lshlrev_b32_e32 v28, 16, v74
	v_and_b32_e32 v29, 0xffff0000, v74
	v_pk_add_f32 v[22:23], v[22:23], v[30:31]
	v_pk_add_f32 v[28:29], v[114:115], v[28:29]
	v_lshlrev_b32_e32 v30, 16, v75
	v_pk_add_f32 v[28:29], v[16:17], v[28:29]
	v_mul_f32_e32 v16, v21, v21
	v_mul_f32_e32 v17, v23, v23
	v_and_b32_e32 v31, 0xffff0000, v75
	v_fmac_f32_e32 v16, v20, v20
	v_fmac_f32_e32 v17, v22, v22
	v_pk_add_f32 v[30:31], v[112:113], v[30:31]
	v_add_f32_e32 v16, v16, v17
	v_mul_f32_e32 v17, v29, v29
	v_pk_add_f32 v[30:31], v[18:19], v[30:31]
	v_fmac_f32_e32 v17, v28, v28
	v_add_f32_e32 v16, v17, v16
	v_mul_f32_e32 v17, v31, v31
	v_fmac_f32_e32 v17, v30, v30
	v_add_f32_e32 v16, v17, v16
	v_add_u32_e32 v32, s22, v205
	v_add_f32_e32 v19, v36, v16
	s_waitcnt lgkmcnt(0)
	v_ashrrev_i32_e32 v33, 31, v32
	v_mov_b32_e32 v36, v19
	s_nop 1
	v_permlane16_swap_b32_e32 v19, v36
	v_lshlrev_b64 v[34:35], 11, v[32:33]
	v_lshl_add_u64 v[34:35], s[14:15], 0, v[34:35]
	v_lshl_add_u64 v[34:35], s[52:53], 1, v[34:35]
	v_lshl_add_u64 v[16:17], v[34:35], 0, s[62:63]
	v_lshl_add_u64 v[34:35], v[16:17], 0, v[168:169]
	s_waitcnt lgkmcnt(0)
	v_add_f32_e32 v16, v19, v36
	v_mov_b32_e32 v17, v16
	s_nop 1
	v_permlane32_swap_b32_e32 v16, v17
	v_cvt_pk_bf16_f32 v27, v38, v39
	v_cvt_pk_bf16_f32 v18, v20, v21
	v_cvt_pk_bf16_f32 v19, v22, v23
	v_cvt_pk_bf16_f32 v20, v28, v29
	v_cvt_pk_bf16_f32 v21, v30, v31
	global_store_dwordx4 v[34:35], v[24:27], off
	global_store_dwordx4 v[34:35], v[18:21], off offset:256
	s_and_saveexec_b64 s[12:13], s[42:43]
	s_cbranch_execz .LBB0_284
	s_lshl_b32 s20, s36, 2
	s_or_b32 s20, s20, s76
	s_ashr_i32 s21, s20, 31
	s_lshl_b64 s[20:21], s[20:21], 18
	s_add_u32 s20, s74, s20
	s_addc_u32 s21, s75, s21
	s_waitcnt lgkmcnt(0)
	v_add_f32_e32 v18, v16, v17
	v_lshl_add_u64 v[16:17], v[32:33], 2, s[20:21]
	global_store_dword v[16:17], v18, off
.LBB0_284:
	s_or_b64 exec, exec, s[12:13]
	s_waitcnt vmcnt(7)
	v_lshlrev_b32_e32 v20, 16, v68
	v_and_b32_e32 v21, 0xffff0000, v68
	v_pk_add_f32 v[20:21], v[114:115], v[20:21]
	v_lshlrev_b32_e32 v22, 16, v69
	v_and_b32_e32 v23, 0xffff0000, v69
	v_pk_add_f32 v[12:13], v[12:13], v[20:21]
	v_lshlrev_b32_e32 v20, 16, v70
	v_and_b32_e32 v21, 0xffff0000, v70
	v_pk_add_f32 v[22:23], v[112:113], v[22:23]
	v_pk_add_f32 v[20:21], v[114:115], v[20:21]
	v_pk_add_f32 v[14:15], v[14:15], v[22:23]
	v_pk_add_f32 v[20:21], v[8:9], v[20:21]
	v_cvt_pk_bf16_f32 v8, v12, v13
	v_mul_f32_e32 v13, v13, v13
	v_fmac_f32_e32 v13, v12, v12
	v_mul_f32_e32 v12, v15, v15
	v_lshlrev_b32_e32 v22, 16, v71
	v_and_b32_e32 v23, 0xffff0000, v71
	v_fmac_f32_e32 v12, v14, v14
	v_pk_add_f32 v[22:23], v[112:113], v[22:23]
	v_add_f32_e32 v12, v13, v12
	v_mul_f32_e32 v13, v21, v21
	v_pk_add_f32 v[22:23], v[10:11], v[22:23]
	v_fmac_f32_e32 v13, v20, v20
	v_add_f32_e32 v12, v13, v12
	v_mul_f32_e32 v13, v23, v23
	v_fmac_f32_e32 v13, v22, v22
	v_cvt_pk_bf16_f32 v10, v20, v21
	v_add_f32_e32 v20, v13, v12
	s_waitcnt vmcnt(6)
	v_lshlrev_b32_e32 v12, 16, v64
	v_and_b32_e32 v13, 0xffff0000, v64
	v_cvt_pk_bf16_f32 v9, v14, v15
	v_lshlrev_b32_e32 v14, 16, v65
	v_and_b32_e32 v15, 0xffff0000, v65
	v_pk_add_f32 v[12:13], v[114:115], v[12:13]
	v_pk_add_f32 v[14:15], v[112:113], v[14:15]
	v_pk_add_f32 v[4:5], v[4:5], v[12:13]
	v_lshlrev_b32_e32 v12, 16, v66
	v_and_b32_e32 v13, 0xffff0000, v66
	v_pk_add_f32 v[6:7], v[6:7], v[14:15]
	v_pk_add_f32 v[12:13], v[114:115], v[12:13]
	v_lshlrev_b32_e32 v14, 16, v67
	v_pk_add_f32 v[12:13], v[0:1], v[12:13]
	v_mul_f32_e32 v0, v5, v5
	v_mul_f32_e32 v1, v7, v7
	v_and_b32_e32 v15, 0xffff0000, v67
	v_fmac_f32_e32 v0, v4, v4
	v_fmac_f32_e32 v1, v6, v6
	v_pk_add_f32 v[14:15], v[112:113], v[14:15]
	v_add_f32_e32 v0, v0, v1
	v_mul_f32_e32 v1, v13, v13
	v_pk_add_f32 v[14:15], v[2:3], v[14:15]
	v_fmac_f32_e32 v1, v12, v12
	v_add_f32_e32 v0, v1, v0
	v_mul_f32_e32 v1, v15, v15
	v_fmac_f32_e32 v1, v14, v14
	v_add_f32_e32 v0, v1, v0
	v_add_u32_e32 v16, s23, v205
	v_add_f32_e32 v3, v20, v0
	s_waitcnt lgkmcnt(0)
	v_ashrrev_i32_e32 v17, 31, v16
	v_mov_b32_e32 v20, v3
	s_nop 1
	v_permlane16_swap_b32_e32 v3, v20
	v_lshlrev_b64 v[18:19], 11, v[16:17]
	v_lshl_add_u64 v[18:19], s[14:15], 0, v[18:19]
	v_lshl_add_u64 v[18:19], s[52:53], 1, v[18:19]
	v_lshl_add_u64 v[0:1], v[18:19], 0, s[62:63]
	v_lshl_add_u64 v[18:19], v[0:1], 0, v[168:169]
	s_waitcnt lgkmcnt(0)
	v_add_f32_e32 v0, v3, v20
	v_mov_b32_e32 v1, v0
	s_nop 1
	v_permlane32_swap_b32_e32 v0, v1
	v_cvt_pk_bf16_f32 v11, v22, v23
	v_cvt_pk_bf16_f32 v2, v4, v5
	v_cvt_pk_bf16_f32 v3, v6, v7
	v_cvt_pk_bf16_f32 v4, v12, v13
	v_cvt_pk_bf16_f32 v5, v14, v15
	global_store_dwordx4 v[18:19], v[8:11], off
	global_store_dwordx4 v[18:19], v[2:5], off offset:256
	s_and_saveexec_b64 s[12:13], s[42:43]
	s_cbranch_execz .LBB0_255
	s_lshl_b32 s20, s36, 2
	s_or_b32 s20, s20, s76
	s_ashr_i32 s21, s20, 31
	s_lshl_b64 s[20:21], s[20:21], 18
	s_add_u32 s20, s74, s20
	s_addc_u32 s21, s75, s21
	s_waitcnt lgkmcnt(0)
	v_add_f32_e32 v2, v0, v1
	v_lshl_add_u64 v[0:1], v[16:17], 2, s[20:21]
	global_store_dword v[0:1], v2, off
	s_branch .LBB0_255

; __device__ __forceinline__ float bflo(unsigned w) { return __uint_as_float(w << 16); }
;     template <int NM> __device__ __forceinline__ void round(const AccT& acc, const Unit& u, int ai, int m0, int wr, int wc, int fr, int fq) const {
;     ...
;         for (int mm = 0; mm < NM; ++mm) {
;             const int rl = ai * 128 + wr * 64 + (m0 + mm) * 16 + fr;
;             const size_t off = (size_t)(u.pm * 256 + rl) * DM + u.pn * 256 + wc * 32 + 8 * fq;
; #pragma unroll
;             for (int bj = 0; bj < 2; ++bj) {
;                 hv[mm][bj] = *GP(const u32x4, hin + off + bj * 128); lv[mm][bj] = (u32x2){0u, 0u};
;                 if (MODE == 1) pv[mm][bj] = *GP(const u32x4, proj + off + bj * 128);
;             }
;         }
; #pragma unroll
;         for (int mm = 0; mm < NM; ++mm) {
;             const int m = m0 + mm;
;             const int rl = ai * 128 + wr * 64 + m * 16 + fr; const int row = u.pm * 256 + rl;
;             const size_t off = (size_t)row * DM + u.pn * 256 + wc * 32 + 8 * fq;
;             float r = 1.f; if (MODE == 1) r = rs[((u.pm >> 3) & 3) * 256 + rl];
;             float ss = 0.f;
; #pragma unroll
;             for (int bj = 0; bj < 2; ++bj) {
;                 f32x4 d0, d1;
;                 if (MODE == 0) { d0 = acc[ai][bj][m][0] * alpha; d1 = acc[ai][bj][m][1] * alpha; }
;                 else {
;                     const u32x4 p = pv[mm][bj];
;                     const f32x4 a0 = acc[ai][bj][m][0] * r, a1 = acc[ai][bj][m][1] * r;
;                     d0 = (f32x4){fsigmoid(a0[0]) * bflo(p.x), fsigmoid(a0[1]) * bfhi(p.x), fsigmoid(a0[2]) * bflo(p.y), fsigmoid(a0[3]) * bfhi(p.y)};
;                     d1 = (f32x4){fsigmoid(a1[0]) * bflo(p.z), fsigmoid(a1[1]) * bfhi(p.z), fsigmoid(a1[2]) * bflo(p.w), fsigmoid(a1[3]) * bfhi(p.w)};
;                 }
;                 const u32x4 H = hv[mm][bj]; const u32x2 L = lv[mm][bj];
;                 const f32x4 o0 = ((f32x4){bflo(H.x), bfhi(H.x), bflo(H.y), bfhi(H.y)} + lo_unpack4(L.x)) + d0;
;                 const f32x4 o1 = ((f32x4){bflo(H.z), bfhi(H.z), bflo(H.w), bfhi(H.w)} + lo_unpack4(L.y)) + d1;
;                 u32x4 w; w.x = cvt_pk_bf16(o0[0], o0[1]); w.y = cvt_pk_bf16(o0[2], o0[3]); w.z = cvt_pk_bf16(o1[0], o1[1]); w.w = cvt_pk_bf16(o1[2], o1[3]);
;                 u32x2 wl; wl.x = lo_pack4(o0[0] - bflo(w.x), o0[1] - bfhi(w.x), o0[2] - bflo(w.y), o0[3] - bfhi(w.y));
.LBB0_530:
	s_lshl_b32 s20, s62, 8
	s_lshl_b32 s48, s37, 8
	v_add_u32_e32 v194, s20, v203
	s_ashr_i32 s49, s48, 31
	s_lshl_b64 s[12:13], s[48:49], 1
	v_ashrrev_i32_e32 v195, 31, v194
	v_lshl_add_u64 v[148:149], v[130:131], 0, s[12:13]
	v_lshlrev_b64 v[216:217], 11, v[194:195]
	s_waitcnt lgkmcnt(0)
	v_lshl_add_u64 v[0:1], v[148:149], 0, v[216:217]
	global_load_dwordx4 v[212:215], v[0:1], off
	global_load_dwordx4 v[24:27], v[0:1], off offset:256
	v_or_b32_e32 v0, 16, v194
	v_ashrrev_i32_e32 v1, 31, v0
	v_lshlrev_b64 v[0:1], 11, v[0:1]
	v_lshl_add_u64 v[0:1], v[148:149], 0, v[0:1]
	global_load_dwordx4 v[20:23], v[0:1], off
	global_load_dwordx4 v[16:19], v[0:1], off offset:256
	v_or_b32_e32 v0, 32, v194
	v_ashrrev_i32_e32 v1, 31, v0
	v_lshlrev_b64 v[0:1], 11, v[0:1]
	v_lshl_add_u64 v[0:1], v[148:149], 0, v[0:1]
	global_load_dwordx4 v[12:15], v[0:1], off
	global_load_dwordx4 v[8:11], v[0:1], off offset:256
	v_or_b32_e32 v0, 48, v194
	v_ashrrev_i32_e32 v1, 31, v0
	v_lshlrev_b64 v[0:1], 11, v[0:1]
	v_lshl_add_u64 v[0:1], v[148:149], 0, v[0:1]
	global_load_dwordx4 v[4:7], v[0:1], off
	s_nop 0
	global_load_dwordx4 v[0:3], v[0:1], off offset:256
	v_and_b32_e32 v196, 64, v163
	v_xor_b32_e32 v168, 16, v163
	v_add_u32_e32 v196, 64, v196
	v_cmp_lt_i32_e32 vcc, v168, v196
	v_cvt_pk_f32_fp8_sdwa v[198:199], s63 src0_sel:WORD_1
	v_lshl_add_u64 v[216:217], s[18:19], 0, v[216:217]
	v_cndmask_b32_e32 v168, v163, v168, vcc
	v_lshlrev_b32_e32 v207, 2, v168
	v_xor_b32_e32 v168, 32, v163
	v_cmp_lt_i32_e32 vcc, v168, v196
	v_cvt_pk_f32_fp8_e32 v[196:197], 0
	v_lshl_add_u64 v[216:217], v[216:217], 0, s[12:13]
	v_cndmask_b32_e32 v168, v163, v168, vcc
	s_lshl_b32 s62, s77, 1
	v_lshlrev_b32_e32 v211, 2, v168
	v_lshl_add_u64 v[216:217], v[216:217], 0, s[62:63]
	v_lshlrev_b32_e32 v168, 1, v128
	v_lshl_add_u64 v[216:217], v[216:217], 0, v[168:169]
	s_waitcnt vmcnt(0)
	v_lshlrev_b32_e32 v218, 16, v212
	v_and_b32_e32 v219, 0xffff0000, v212
	v_lshlrev_b32_e32 v212, 16, v213
	v_and_b32_e32 v213, 0xffff0000, v213
	v_pk_fma_f32 v[212:213], v[198:199], s[34:35], v[212:213] op_sel_hi:[1,0,1]
	v_pk_fma_f32 v[218:219], v[196:197], s[34:35], v[218:219] op_sel_hi:[1,0,1]
	v_pk_add_f32 v[212:213], v[154:155], v[212:213]
	v_lshlrev_b32_e32 v154, 16, v214
	v_and_b32_e32 v155, 0xffff0000, v214
	v_lshlrev_b32_e32 v214, 16, v215
	v_and_b32_e32 v215, 0xffff0000, v215
	v_pk_fma_f32 v[154:155], v[196:197], s[34:35], v[154:155] op_sel_hi:[1,0,1]
	v_pk_fma_f32 v[214:215], v[198:199], s[34:35], v[214:215] op_sel_hi:[1,0,1]
	v_pk_add_f32 v[192:193], v[192:193], v[218:219]
	v_pk_add_f32 v[214:215], v[156:157], v[214:215]
	v_pk_add_f32 v[158:159], v[158:159], v[154:155]
	v_cvt_pk_bf16_f32 v154, v192, v193
	v_cvt_pk_bf16_f32 v155, v212, v213
	v_cvt_pk_bf16_f32 v156, v158, v159
	v_cvt_pk_bf16_f32 v157, v214, v215
	global_store_dwordx4 v[216:217], v[154:157], off
	s_nop 1
	v_mul_f32_e32 v154, v193, v193
	v_mul_f32_e32 v155, v213, v213
	v_fmac_f32_e32 v154, v192, v192
	v_fmac_f32_e32 v155, v212, v212
	v_add_f32_e32 v154, v154, v155
	v_mul_f32_e32 v155, v159, v159
	v_fmac_f32_e32 v155, v158, v158
	v_add_f32_e32 v154, v155, v154
	v_mul_f32_e32 v155, v215, v215
	v_fmac_f32_e32 v155, v214, v214
	v_add_f32_e32 v156, v155, v154
	v_lshlrev_b32_e32 v154, 16, v24
	v_and_b32_e32 v155, 0xffff0000, v24
	v_lshlrev_b32_e32 v24, 16, v25
	v_and_b32_e32 v25, 0xffff0000, v25
	v_pk_fma_f32 v[24:25], v[198:199], s[34:35], v[24:25] op_sel_hi:[1,0,1]
	v_pk_fma_f32 v[154:155], v[196:197], s[34:35], v[154:155] op_sel_hi:[1,0,1]
	v_pk_add_f32 v[150:151], v[150:151], v[24:25]
	v_lshlrev_b32_e32 v24, 16, v26
	v_and_b32_e32 v25, 0xffff0000, v26
	v_lshlrev_b32_e32 v26, 16, v27
	v_and_b32_e32 v27, 0xffff0000, v27
	v_pk_fma_f32 v[24:25], v[196:197], s[34:35], v[24:25] op_sel_hi:[1,0,1]
	v_pk_fma_f32 v[26:27], v[198:199], s[34:35], v[26:27] op_sel_hi:[1,0,1]
	v_pk_add_f32 v[152:153], v[152:153], v[154:155]
	v_pk_add_f32 v[126:127], v[126:127], v[26:27]
	v_pk_add_f32 v[124:125], v[124:125], v[24:25]
	v_cvt_pk_bf16_f32 v24, v152, v153
	v_cvt_pk_bf16_f32 v25, v150, v151
	v_cvt_pk_bf16_f32 v26, v124, v125
	v_cvt_pk_bf16_f32 v27, v126, v127
	global_store_dwordx4 v[216:217], v[24:27], off offset:256
	s_nop 1
	v_mul_f32_e32 v24, v153, v153
	v_mul_f32_e32 v25, v151, v151
	v_fmac_f32_e32 v24, v152, v152
	v_fmac_f32_e32 v25, v150, v150
	v_add_f32_e32 v24, v24, v25
	v_mul_f32_e32 v25, v125, v125
	v_fmac_f32_e32 v25, v124, v124
	v_add_f32_e32 v24, v25, v24
	v_mul_f32_e32 v25, v127, v127
	v_fmac_f32_e32 v25, v126, v126
	v_add_f32_e32 v24, v25, v24
	v_add_f32_e32 v24, v156, v24
	v_mov_b32_e32 v25, v24
	s_nop 1
	v_permlane16_swap_b32_e32 v24, v25
	s_waitcnt lgkmcnt(0)
	v_add_f32_e32 v24, v24, v25
	v_mov_b32_e32 v25, v24
	s_nop 1
	v_permlane32_swap_b32_e32 v24, v25
	s_and_saveexec_b64 s[12:13], s[42:43]
	s_cbranch_execz .LBB0_532
	s_lshl_b32 s21, s37, 2
	s_or_b32 s22, s21, s75
	s_ashr_i32 s23, s22, 31
	s_lshl_b64 s[22:23], s[22:23], 18
	s_add_u32 s22, s73, s22
	s_addc_u32 s23, s74, s23
	s_waitcnt lgkmcnt(0)
	v_add_f32_e32 v26, v24, v25
	v_lshl_add_u64 v[24:25], v[194:195], 2, s[22:23]
	global_store_dword v[24:25], v26, off
; __device__ __forceinline__ float bflo(unsigned w) { return __uint_as_float(w << 16); }
;     template <int NM> __device__ __forceinline__ void round(const AccT& acc, const Unit& u, int ai, int m0, int wr, int wc, int fr, int fq) const {
;     ...
;         for (int mm = 0; mm < NM; ++mm) {
;             const int m = m0 + mm;
;             const int rl = ai * 128 + wr * 64 + m * 16 + fr; const int row = u.pm * 256 + rl;
;             const size_t off = (size_t)row * DM + u.pn * 256 + wc * 32 + 8 * fq;
;             float r = 1.f; if (MODE == 1) r = rs[((u.pm >> 3) & 3) * 256 + rl];
;             float ss = 0.f;
; #pragma unroll
;             for (int bj = 0; bj < 2; ++bj) {
;                 f32x4 d0, d1;
;                 if (MODE == 0) { d0 = acc[ai][bj][m][0] * alpha; d1 = acc[ai][bj][m][1] * alpha; }
;                 else {
;                     const u32x4 p = pv[mm][bj];
;                     const f32x4 a0 = acc[ai][bj][m][0] * r, a1 = acc[ai][bj][m][1] * r;
;                     d0 = (f32x4){fsigmoid(a0[0]) * bflo(p.x), fsigmoid(a0[1]) * bfhi(p.x), fsigmoid(a0[2]) * bflo(p.y), fsigmoid(a0[3]) * bfhi(p.y)};
;                     d1 = (f32x4){fsigmoid(a1[0]) * bflo(p.z), fsigmoid(a1[1]) * bfhi(p.z), fsigmoid(a1[2]) * bflo(p.w), fsigmoid(a1[3]) * bfhi(p.w)};
;                 }
;                 const u32x4 H = hv[mm][bj]; const u32x2 L = lv[mm][bj];
;                 const f32x4 o0 = ((f32x4){bflo(H.x), bfhi(H.x), bflo(H.y), bfhi(H.y)} + lo_unpack4(L.x)) + d0;
;                 const f32x4 o1 = ((f32x4){bflo(H.z), bfhi(H.z), bflo(H.w), bfhi(H.w)} + lo_unpack4(L.y)) + d1;
;                 u32x4 w; w.x = cvt_pk_bf16(o0[0], o0[1]); w.y = cvt_pk_bf16(o0[2], o0[3]); w.z = cvt_pk_bf16(o1[0], o1[1]); w.w = cvt_pk_bf16(o1[2], o1[3]);
;                 u32x2 wl; wl.x = lo_pack4(o0[0] - bflo(w.x), o0[1] - bfhi(w.x), o0[2] - bflo(w.y), o0[3] - bfhi(w.y));
;                 wl.y = lo_pack4(o1[0] - bflo(w.z), o1[1] - bfhi(w.z), o1[2] - bflo(w.w), o1[3] - bfhi(w.w));
;                 *GP(u32x4, hout + off + bj * 128) = w; (void)wl;
;                 ss += (o0[0] * o0[0] + o0[1] * o0[1]) + (o0[2] * o0[2] + o0[3] * o0[3]) + (o1[0] * o1[0] + o1[1] * o1[1]) + (o1[2] * o1[2] + o1[3] * o1[3]);
;             }
;             ss += __shfl_xor(ss, 16); ss += __shfl_xor(ss, 32);
;             if (fq == 0) *GP(float, ssp + (size_t)(u.pn * 4 + wc) * TT + row) = ss;
.LBB0_532:
	s_or_b64 exec, exec, s[12:13]
	v_pk_mul_f32 v[124:125], v[198:199], s[34:35] op_sel_hi:[1,0]
	v_lshlrev_b32_e32 v150, 16, v20
	v_and_b32_e32 v151, 0xffff0000, v20
	v_lshlrev_b32_e32 v20, 16, v21
	v_and_b32_e32 v21, 0xffff0000, v21
	v_pk_mul_f32 v[126:127], v[196:197], s[34:35] op_sel_hi:[1,0]
	v_pk_add_f32 v[20:21], v[124:125], v[20:21]
	v_pk_add_f32 v[150:151], v[126:127], v[150:151]
	v_pk_add_f32 v[146:147], v[146:147], v[20:21]
	v_lshlrev_b32_e32 v20, 16, v22
	v_and_b32_e32 v21, 0xffff0000, v22
	v_pk_add_f32 v[144:145], v[144:145], v[150:151]
	v_pk_add_f32 v[20:21], v[126:127], v[20:21]
	v_lshlrev_b32_e32 v22, 16, v23
	v_and_b32_e32 v23, 0xffff0000, v23
	v_pk_add_f32 v[140:141], v[140:141], v[20:21]
	v_cvt_pk_bf16_f32 v20, v144, v145
	v_mul_f32_e32 v145, v145, v145
	v_pk_add_f32 v[22:23], v[124:125], v[22:23]
	v_fmac_f32_e32 v145, v144, v144
	v_mul_f32_e32 v144, v147, v147
	v_pk_add_f32 v[142:143], v[142:143], v[22:23]
	v_cvt_pk_bf16_f32 v22, v140, v141
	v_fmac_f32_e32 v144, v146, v146
	v_mul_f32_e32 v141, v141, v141
	v_add_f32_e32 v144, v145, v144
	v_fmac_f32_e32 v141, v140, v140
	v_add_f32_e32 v140, v141, v144
	v_mul_f32_e32 v141, v143, v143
	v_fmac_f32_e32 v141, v142, v142
	v_cvt_pk_bf16_f32 v23, v142, v143
	v_add_f32_e32 v142, v141, v140
	v_lshlrev_b32_e32 v140, 16, v16
	v_and_b32_e32 v141, 0xffff0000, v16
	v_lshlrev_b32_e32 v16, 16, v17
	v_and_b32_e32 v17, 0xffff0000, v17
	v_pk_add_f32 v[140:141], v[126:127], v[140:141]
	v_pk_add_f32 v[16:17], v[124:125], v[16:17]
	s_or_b32 s21, s20, 16
	v_pk_add_f32 v[138:139], v[138:139], v[16:17]
	v_pk_add_f32 v[16:17], v[136:137], v[140:141]
	v_lshlrev_b32_e32 v136, 16, v18
	v_and_b32_e32 v137, 0xffff0000, v18
	v_lshlrev_b32_e32 v18, 16, v19
	v_and_b32_e32 v19, 0xffff0000, v19
	v_pk_add_f32 v[18:19], v[124:125], v[18:19]
	v_pk_add_f32 v[136:137], v[126:127], v[136:137]
	v_pk_add_f32 v[134:135], v[134:135], v[18:19]
	v_mul_f32_e32 v18, v17, v17
	v_mul_f32_e32 v19, v139, v139
	v_pk_add_f32 v[132:133], v[132:133], v[136:137]
	v_fmac_f32_e32 v18, v16, v16
	v_fmac_f32_e32 v19, v138, v138
	v_add_f32_e32 v18, v18, v19
	v_mul_f32_e32 v19, v133, v133
	v_fmac_f32_e32 v19, v132, v132
	v_add_f32_e32 v18, v19, v18
	v_mul_f32_e32 v19, v135, v135
	v_fmac_f32_e32 v19, v134, v134
	v_add_f32_e32 v18, v19, v18
	v_add_u32_e32 v24, s21, v203
	v_add_f32_e32 v136, v142, v18
	s_waitcnt lgkmcnt(0)
	v_ashrrev_i32_e32 v25, 31, v24
	v_mov_b32_e32 v137, v136
	s_nop 1
	v_permlane16_swap_b32_e32 v136, v137
	v_lshlrev_b64 v[26:27], 11, v[24:25]
	v_lshl_add_u64 v[26:27], s[18:19], 0, v[26:27]
	v_lshl_add_u64 v[26:27], s[48:49], 1, v[26:27]
	v_lshl_add_u64 v[18:19], v[26:27], 0, s[62:63]
	v_lshl_add_u64 v[26:27], v[18:19], 0, v[168:169]
	v_cvt_pk_bf16_f32 v18, v16, v17
	s_waitcnt lgkmcnt(0)
	v_add_f32_e32 v16, v136, v137
	v_mov_b32_e32 v17, v16
	s_nop 1
	v_permlane32_swap_b32_e32 v16, v17
	v_cvt_pk_bf16_f32 v21, v146, v147
	global_store_dwordx4 v[26:27], v[20:23], off
	v_cvt_pk_bf16_f32 v19, v138, v139
	s_nop 0
	v_cvt_pk_bf16_f32 v20, v132, v133
	v_cvt_pk_bf16_f32 v21, v134, v135
	global_store_dwordx4 v[26:27], v[18:21], off offset:256
	s_and_saveexec_b64 s[12:13], s[42:43]
	s_cbranch_execz .LBB0_534
	s_lshl_b32 s22, s37, 2
	s_or_b32 s22, s22, s75
	s_ashr_i32 s23, s22, 31
	s_lshl_b64 s[22:23], s[22:23], 18
	s_add_u32 s22, s73, s22
	s_addc_u32 s23, s74, s23
	s_waitcnt lgkmcnt(0)
	v_add_f32_e32 v18, v16, v17
	v_lshl_add_u64 v[16:17], v[24:25], 2, s[22:23]
	global_store_dword v[16:17], v18, off
.LBB0_534:
	s_or_b64 exec, exec, s[12:13]
	v_lshlrev_b32_e32 v20, 16, v12
	v_and_b32_e32 v21, 0xffff0000, v12
	v_lshlrev_b32_e32 v12, 16, v13
	v_and_b32_e32 v13, 0xffff0000, v13
	v_pk_add_f32 v[12:13], v[124:125], v[12:13]
	v_pk_add_f32 v[20:21], v[126:127], v[20:21]
	v_pk_add_f32 v[22:23], v[122:123], v[12:13]
	v_lshlrev_b32_e32 v12, 16, v14
	v_and_b32_e32 v13, 0xffff0000, v14
	v_pk_add_f32 v[20:21], v[120:121], v[20:21]
	v_pk_add_f32 v[12:13], v[126:127], v[12:13]
	v_lshlrev_b32_e32 v14, 16, v15
	v_pk_add_f32 v[26:27], v[116:117], v[12:13]
	v_cvt_pk_bf16_f32 v12, v20, v21
	v_mul_f32_e32 v21, v21, v21
	v_fmac_f32_e32 v21, v20, v20
	v_mul_f32_e32 v20, v23, v23
	v_and_b32_e32 v15, 0xffff0000, v15
	v_fmac_f32_e32 v20, v22, v22
	v_pk_add_f32 v[14:15], v[124:125], v[14:15]
	v_add_f32_e32 v20, v21, v20
	v_mul_f32_e32 v21, v27, v27
	v_pk_add_f32 v[24:25], v[118:119], v[14:15]
	v_fmac_f32_e32 v21, v26, v26
	v_add_f32_e32 v20, v21, v20
	v_mul_f32_e32 v21, v25, v25
	v_fmac_f32_e32 v21, v24, v24
	v_cvt_pk_bf16_f32 v14, v26, v27
	v_add_f32_e32 v26, v21, v20
	v_lshlrev_b32_e32 v20, 16, v8
	v_and_b32_e32 v21, 0xffff0000, v8
	v_lshlrev_b32_e32 v8, 16, v9
	v_and_b32_e32 v9, 0xffff0000, v9
	v_pk_add_f32 v[20:21], v[126:127], v[20:21]
	v_pk_add_f32 v[8:9], v[124:125], v[8:9]
	v_cvt_pk_bf16_f32 v13, v22, v23
	v_pk_add_f32 v[22:23], v[114:115], v[8:9]
	v_pk_add_f32 v[8:9], v[112:113], v[20:21]
	v_lshlrev_b32_e32 v20, 16, v10
	v_and_b32_e32 v21, 0xffff0000, v10
	v_lshlrev_b32_e32 v10, 16, v11
	v_and_b32_e32 v11, 0xffff0000, v11
	v_pk_add_f32 v[10:11], v[124:125], v[10:11]
	v_cvt_pk_bf16_f32 v15, v24, v25
	v_pk_add_f32 v[20:21], v[126:127], v[20:21]
	v_pk_add_f32 v[24:25], v[110:111], v[10:11]
	v_mul_f32_e32 v10, v9, v9
	v_mul_f32_e32 v11, v23, v23
	v_pk_add_f32 v[20:21], v[108:109], v[20:21]
	v_fmac_f32_e32 v10, v8, v8
	v_fmac_f32_e32 v11, v22, v22
	v_add_f32_e32 v10, v10, v11
	v_mul_f32_e32 v11, v21, v21
	v_fmac_f32_e32 v11, v20, v20
	v_add_f32_e32 v10, v11, v10
	v_mul_f32_e32 v11, v25, v25
	v_fmac_f32_e32 v11, v24, v24
	s_or_b32 s22, s20, 32
	v_add_f32_e32 v10, v11, v10
	v_add_u32_e32 v16, s22, v203
	v_add_f32_e32 v26, v26, v10
	s_waitcnt lgkmcnt(0)
	v_ashrrev_i32_e32 v17, 31, v16
	v_mov_b32_e32 v27, v26
	s_nop 1
	v_permlane16_swap_b32_e32 v26, v27
	v_lshlrev_b64 v[18:19], 11, v[16:17]
	v_lshl_add_u64 v[18:19], s[18:19], 0, v[18:19]
	v_lshl_add_u64 v[18:19], s[48:49], 1, v[18:19]
	v_lshl_add_u64 v[10:11], v[18:19], 0, s[62:63]
	v_lshl_add_u64 v[18:19], v[10:11], 0, v[168:169]
	v_cvt_pk_bf16_f32 v10, v8, v9
	s_waitcnt lgkmcnt(0)
	v_add_f32_e32 v8, v26, v27
	v_mov_b32_e32 v9, v8
	s_nop 1
	v_permlane32_swap_b32_e32 v8, v9
	global_store_dwordx4 v[18:19], v[12:15], off
	v_cvt_pk_bf16_f32 v11, v22, v23
	s_nop 0
	v_cvt_pk_bf16_f32 v12, v20, v21
	v_cvt_pk_bf16_f32 v13, v24, v25
	global_store_dwordx4 v[18:19], v[10:13], off offset:256
	s_and_saveexec_b64 s[12:13], s[42:43]
	s_cbranch_execz .LBB0_536
	s_lshl_b32 s23, s37, 2
	s_or_b32 s24, s23, s75
	s_ashr_i32 s25, s24, 31
	s_lshl_b64 s[24:25], s[24:25], 18
	s_add_u32 s24, s73, s24
	s_addc_u32 s25, s74, s25
	s_waitcnt lgkmcnt(0)
	v_add_f32_e32 v10, v8, v9
	v_lshl_add_u64 v[8:9], v[16:17], 2, s[24:25]
	global_store_dword v[8:9], v10, off
;     template <int NM> __device__ __forceinline__ void round(const AccT& acc, const Unit& u, int ai, int m0, int wr, int wc, int fr, int fq) const {
;         u32x4 hv[NM][2], pv[NM][2]; u32x2 lv[NM][2];
; #pragma unroll
;         for (int mm = 0; mm < NM; ++mm) {
;             const int rl = ai * 128 + wr * 64 + (m0 + mm) * 16 + fr;
;             const size_t off = (size_t)(u.pm * 256 + rl) * DM + u.pn * 256 + wc * 32 + 8 * fq;
; #pragma unroll
;             for (int bj = 0; bj < 2; ++bj) {
;                 hv[mm][bj] = *GP(const u32x4, hin + off + bj * 128); lv[mm][bj] = (u32x2){0u, 0u};
;                 if (MODE == 1) pv[mm][bj] = *GP(const u32x4, proj + off + bj * 128);
;             }
;         }
; #pragma unroll
;         for (int mm = 0; mm < NM; ++mm) {
;             const int m = m0 + mm;
;             const int rl = ai * 128 + wr * 64 + m * 16 + fr; const int row = u.pm * 256 + rl;
;             const size_t off = (size_t)row * DM + u.pn * 256 + wc * 32 + 8 * fq;
;             float r = 1.f; if (MODE == 1) r = rs[((u.pm >> 3) & 3) * 256 + rl];
;             float ss = 0.f;
; #pragma unroll
;             for (int bj = 0; bj < 2; ++bj) {
;                 f32x4 d0, d1;
;                 if (MODE == 0) { d0 = acc[ai][bj][m][0] * alpha; d1 = acc[ai][bj][m][1] * alpha; }
;                 else {
;                     const u32x4 p = pv[mm][bj];
;                     const f32x4 a0 = acc[ai][bj][m][0] * r, a1 = acc[ai][bj][m][1] * r;
;                     d0 = (f32x4){fsigmoid(a0[0]) * bflo(p.x), fsigmoid(a0[1]) * bfhi(p.x), fsigmoid(a0[2]) * bflo(p.y), fsigmoid(a0[3]) * bfhi(p.y)};
;                     d1 = (f32x4){fsigmoid(a1[0]) * bflo(p.z), fsigmoid(a1[1]) * bfhi(p.z), fsigmoid(a1[2]) * bflo(p.w), fsigmoid(a1[3]) * bfhi(p.w)};
;                 }
;                 const u32x4 H = hv[mm][bj]; const u32x2 L = lv[mm][bj];
;                 const f32x4 o0 = ((f32x4){bflo(H.x), bfhi(H.x), bflo(H.y), bfhi(H.y)} + lo_unpack4(L.x)) + d0;
;                 const f32x4 o1 = ((f32x4){bflo(H.z), bfhi(H.z), bflo(H.w), bfhi(H.w)} + lo_unpack4(L.y)) + d1;
;                 u32x4 w; w.x = cvt_pk_bf16(o0[0], o0[1]); w.y = cvt_pk_bf16(o0[2], o0[3]); w.z = cvt_pk_bf16(o1[0], o1[1]); w.w = cvt_pk_bf16(o1[2], o1[3]);
;                 u32x2 wl; wl.x = lo_pack4(o0[0] - bflo(w.x), o0[1] - bfhi(w.x), o0[2] - bflo(w.y), o0[3] - bfhi(w.y));
.LBB0_536:
	s_or_b64 exec, exec, s[12:13]
	v_lshlrev_b32_e32 v12, 16, v4
	v_and_b32_e32 v13, 0xffff0000, v4
	v_lshlrev_b32_e32 v4, 16, v5
	v_and_b32_e32 v5, 0xffff0000, v5
	v_pk_add_f32 v[4:5], v[124:125], v[4:5]
	v_pk_add_f32 v[12:13], v[126:127], v[12:13]
	v_pk_add_f32 v[14:15], v[106:107], v[4:5]
	v_lshlrev_b32_e32 v4, 16, v6
	v_and_b32_e32 v5, 0xffff0000, v6
	v_pk_add_f32 v[12:13], v[104:105], v[12:13]
	v_pk_add_f32 v[4:5], v[126:127], v[4:5]
	v_lshlrev_b32_e32 v6, 16, v7
	v_pk_add_f32 v[18:19], v[100:101], v[4:5]
	v_cvt_pk_bf16_f32 v4, v12, v13
	v_mul_f32_e32 v13, v13, v13
	v_fmac_f32_e32 v13, v12, v12
	v_mul_f32_e32 v12, v15, v15
	v_and_b32_e32 v7, 0xffff0000, v7
	v_fmac_f32_e32 v12, v14, v14
	v_pk_add_f32 v[6:7], v[124:125], v[6:7]
	v_add_f32_e32 v12, v13, v12
	v_mul_f32_e32 v13, v19, v19
	v_pk_add_f32 v[16:17], v[102:103], v[6:7]
	v_fmac_f32_e32 v13, v18, v18
	v_add_f32_e32 v12, v13, v12
	v_mul_f32_e32 v13, v17, v17
	v_fmac_f32_e32 v13, v16, v16
	v_cvt_pk_bf16_f32 v6, v18, v19
	v_add_f32_e32 v18, v13, v12
	v_lshlrev_b32_e32 v12, 16, v0
	v_and_b32_e32 v13, 0xffff0000, v0
	v_lshlrev_b32_e32 v0, 16, v1
	v_and_b32_e32 v1, 0xffff0000, v1
	v_pk_add_f32 v[12:13], v[126:127], v[12:13]
	v_pk_add_f32 v[0:1], v[124:125], v[0:1]
	v_cvt_pk_bf16_f32 v5, v14, v15
	v_pk_add_f32 v[14:15], v[98:99], v[0:1]
	v_pk_add_f32 v[0:1], v[96:97], v[12:13]
	v_lshlrev_b32_e32 v12, 16, v2
	v_and_b32_e32 v13, 0xffff0000, v2
	v_lshlrev_b32_e32 v2, 16, v3
	v_and_b32_e32 v3, 0xffff0000, v3
	v_pk_add_f32 v[2:3], v[124:125], v[2:3]
	v_cvt_pk_bf16_f32 v7, v16, v17
	v_pk_add_f32 v[12:13], v[126:127], v[12:13]
	v_pk_add_f32 v[16:17], v[94:95], v[2:3]
	v_mul_f32_e32 v2, v1, v1
	v_mul_f32_e32 v3, v15, v15
	v_pk_add_f32 v[12:13], v[92:93], v[12:13]
	v_fmac_f32_e32 v2, v0, v0
	v_fmac_f32_e32 v3, v14, v14
	v_add_f32_e32 v2, v2, v3
	v_mul_f32_e32 v3, v13, v13
	v_fmac_f32_e32 v3, v12, v12
	v_add_f32_e32 v2, v3, v2
	v_mul_f32_e32 v3, v17, v17
	v_fmac_f32_e32 v3, v16, v16
	s_or_b32 s23, s20, 48
	v_add_f32_e32 v2, v3, v2
	v_add_u32_e32 v8, s23, v203
	v_add_f32_e32 v18, v18, v2
	s_waitcnt lgkmcnt(0)
	v_ashrrev_i32_e32 v9, 31, v8
	v_mov_b32_e32 v19, v18
	s_nop 1
	v_permlane16_swap_b32_e32 v18, v19
	v_lshlrev_b64 v[10:11], 11, v[8:9]
	v_lshl_add_u64 v[10:11], s[18:19], 0, v[10:11]
	v_lshl_add_u64 v[10:11], s[48:49], 1, v[10:11]
	v_lshl_add_u64 v[2:3], v[10:11], 0, s[62:63]
	v_lshl_add_u64 v[10:11], v[2:3], 0, v[168:169]
	v_cvt_pk_bf16_f32 v2, v0, v1
	s_waitcnt lgkmcnt(0)
	v_add_f32_e32 v0, v18, v19
	v_mov_b32_e32 v1, v0
	s_nop 1
	v_permlane32_swap_b32_e32 v0, v1
	global_store_dwordx4 v[10:11], v[4:7], off
	v_cvt_pk_bf16_f32 v3, v14, v15
	s_nop 0
	v_cvt_pk_bf16_f32 v4, v12, v13
	v_cvt_pk_bf16_f32 v5, v16, v17
	global_store_dwordx4 v[10:11], v[2:5], off offset:256
	s_and_saveexec_b64 s[12:13], s[42:43]
	s_cbranch_execz .LBB0_538
	s_lshl_b32 s24, s37, 2
	s_or_b32 s24, s24, s75
	s_ashr_i32 s25, s24, 31
	s_lshl_b64 s[24:25], s[24:25], 18
	s_add_u32 s24, s73, s24
	s_addc_u32 s25, s74, s25
	s_waitcnt lgkmcnt(0)
	v_add_f32_e32 v2, v0, v1
	v_lshl_add_u64 v[0:1], v[8:9], 2, s[24:25]
	global_store_dword v[0:1], v2, off
.LBB0_538:
	s_or_b64 exec, exec, s[12:13]
	v_add_u32_e32 v92, s20, v205
	v_ashrrev_i32_e32 v93, 31, v92
	v_lshlrev_b64 v[98:99], 11, v[92:93]
	s_waitcnt lgkmcnt(0)
	v_lshl_add_u64 v[0:1], v[148:149], 0, v[98:99]
	global_load_dwordx4 v[94:97], v[0:1], off
	global_load_dwordx4 v[24:27], v[0:1], off offset:256
	v_or_b32_e32 v0, 16, v92
	v_ashrrev_i32_e32 v1, 31, v0
	v_lshlrev_b64 v[0:1], 11, v[0:1]
	v_lshl_add_u64 v[0:1], v[148:149], 0, v[0:1]
	global_load_dwordx4 v[20:23], v[0:1], off
	global_load_dwordx4 v[16:19], v[0:1], off offset:256
	v_or_b32_e32 v0, 32, v92
	v_ashrrev_i32_e32 v1, 31, v0
	v_lshlrev_b64 v[0:1], 11, v[0:1]
	v_lshl_add_u64 v[0:1], v[148:149], 0, v[0:1]
	global_load_dwordx4 v[12:15], v[0:1], off
	global_load_dwordx4 v[8:11], v[0:1], off offset:256
	v_or_b32_e32 v0, 48, v92
	v_ashrrev_i32_e32 v1, 31, v0
	v_lshlrev_b64 v[0:1], 11, v[0:1]
	v_lshl_add_u64 v[0:1], v[148:149], 0, v[0:1]
	global_load_dwordx4 v[4:7], v[0:1], off
	s_nop 0
	global_load_dwordx4 v[0:3], v[0:1], off offset:256
	v_lshl_add_u64 v[98:99], s[18:19], 0, v[98:99]
	v_lshl_add_u64 v[98:99], s[48:49], 1, v[98:99]
	v_lshl_add_u64 v[98:99], v[98:99], 0, s[62:63]
	v_lshl_add_u64 v[98:99], v[98:99], 0, v[168:169]
	s_waitcnt vmcnt(7)
	v_lshlrev_b32_e32 v100, 16, v94
	v_and_b32_e32 v101, 0xffff0000, v94
	v_lshlrev_b32_e32 v94, 16, v95
	v_and_b32_e32 v95, 0xffff0000, v95
	v_pk_add_f32 v[94:95], v[124:125], v[94:95]
	v_pk_add_f32 v[100:101], v[126:127], v[100:101]
	v_pk_add_f32 v[94:95], v[86:87], v[94:95]
	v_lshlrev_b32_e32 v86, 16, v96
	v_and_b32_e32 v87, 0xffff0000, v96
	v_lshlrev_b32_e32 v96, 16, v97
	v_and_b32_e32 v97, 0xffff0000, v97
	v_pk_add_f32 v[86:87], v[126:127], v[86:87]
	v_pk_add_f32 v[96:97], v[124:125], v[96:97]
	v_pk_add_f32 v[90:91], v[90:91], v[100:101]
	v_pk_add_f32 v[96:97], v[84:85], v[96:97]
	v_pk_add_f32 v[88:89], v[88:89], v[86:87]
	v_cvt_pk_bf16_f32 v84, v90, v91
	v_cvt_pk_bf16_f32 v85, v94, v95
	v_cvt_pk_bf16_f32 v86, v88, v89
	v_cvt_pk_bf16_f32 v87, v96, v97
	global_store_dwordx4 v[98:99], v[84:87], off
	s_nop 1
	v_mul_f32_e32 v84, v91, v91
	v_mul_f32_e32 v85, v95, v95
	v_fmac_f32_e32 v84, v90, v90
	v_fmac_f32_e32 v85, v94, v94
	v_add_f32_e32 v84, v84, v85
	v_mul_f32_e32 v85, v89, v89
	v_fmac_f32_e32 v85, v88, v88
	v_add_f32_e32 v84, v85, v84
	v_mul_f32_e32 v85, v97, v97
	v_fmac_f32_e32 v85, v96, v96
	v_add_f32_e32 v86, v85, v84
	s_waitcnt vmcnt(7)
	v_lshlrev_b32_e32 v84, 16, v24
	v_and_b32_e32 v85, 0xffff0000, v24
	v_lshlrev_b32_e32 v24, 16, v25
	v_and_b32_e32 v25, 0xffff0000, v25
	v_pk_add_f32 v[24:25], v[124:125], v[24:25]
	v_pk_add_f32 v[84:85], v[126:127], v[84:85]
	v_pk_add_f32 v[80:81], v[80:81], v[24:25]
	v_lshlrev_b32_e32 v24, 16, v26
	v_and_b32_e32 v25, 0xffff0000, v26
	v_lshlrev_b32_e32 v26, 16, v27
	v_and_b32_e32 v27, 0xffff0000, v27
	v_pk_add_f32 v[24:25], v[126:127], v[24:25]
	v_pk_add_f32 v[26:27], v[124:125], v[26:27]
	v_pk_add_f32 v[82:83], v[82:83], v[84:85]
	v_pk_add_f32 v[78:79], v[78:79], v[26:27]
	v_pk_add_f32 v[76:77], v[76:77], v[24:25]
	v_cvt_pk_bf16_f32 v24, v82, v83
	v_cvt_pk_bf16_f32 v25, v80, v81
	v_cvt_pk_bf16_f32 v26, v76, v77
	v_cvt_pk_bf16_f32 v27, v78, v79
	global_store_dwordx4 v[98:99], v[24:27], off offset:256
	s_nop 1
	v_mul_f32_e32 v24, v83, v83
	v_mul_f32_e32 v25, v81, v81
	v_fmac_f32_e32 v24, v82, v82
	v_fmac_f32_e32 v25, v80, v80
	v_add_f32_e32 v24, v24, v25
	v_mul_f32_e32 v25, v77, v77
	v_fmac_f32_e32 v25, v76, v76
	v_add_f32_e32 v24, v25, v24
	v_mul_f32_e32 v25, v79, v79
	v_fmac_f32_e32 v25, v78, v78
	v_add_f32_e32 v24, v25, v24
	v_add_f32_e32 v24, v86, v24
	v_mov_b32_e32 v25, v24
	s_nop 1
	v_permlane16_swap_b32_e32 v24, v25
	s_waitcnt lgkmcnt(0)
	v_add_f32_e32 v24, v24, v25
	v_mov_b32_e32 v25, v24
	s_nop 1
	v_permlane32_swap_b32_e32 v24, v25
	s_and_saveexec_b64 s[12:13], s[42:43]
	s_cbranch_execz .LBB0_540
; __device__ __forceinline__ float bflo(unsigned w) { return __uint_as_float(w << 16); }
;     template <int NM> __device__ __forceinline__ void round(const AccT& acc, const Unit& u, int ai, int m0, int wr, int wc, int fr, int fq) const {
;     ...
;         for (int mm = 0; mm < NM; ++mm) {
;             const int m = m0 + mm;
;             const int rl = ai * 128 + wr * 64 + m * 16 + fr; const int row = u.pm * 256 + rl;
;             const size_t off = (size_t)row * DM + u.pn * 256 + wc * 32 + 8 * fq;
;             float r = 1.f; if (MODE == 1) r = rs[((u.pm >> 3) & 3) * 256 + rl];
;             float ss = 0.f;
; #pragma unroll
;             for (int bj = 0; bj < 2; ++bj) {
;                 f32x4 d0, d1;
;                 if (MODE == 0) { d0 = acc[ai][bj][m][0] * alpha; d1 = acc[ai][bj][m][1] * alpha; }
;                 else {
;                     const u32x4 p = pv[mm][bj];
;                     const f32x4 a0 = acc[ai][bj][m][0] * r, a1 = acc[ai][bj][m][1] * r;
;                     d0 = (f32x4){fsigmoid(a0[0]) * bflo(p.x), fsigmoid(a0[1]) * bfhi(p.x), fsigmoid(a0[2]) * bflo(p.y), fsigmoid(a0[3]) * bfhi(p.y)};
;                     d1 = (f32x4){fsigmoid(a1[0]) * bflo(p.z), fsigmoid(a1[1]) * bfhi(p.z), fsigmoid(a1[2]) * bflo(p.w), fsigmoid(a1[3]) * bfhi(p.w)};
;                 }
;                 const u32x4 H = hv[mm][bj]; const u32x2 L = lv[mm][bj];
;                 const f32x4 o0 = ((f32x4){bflo(H.x), bfhi(H.x), bflo(H.y), bfhi(H.y)} + lo_unpack4(L.x)) + d0;
;                 const f32x4 o1 = ((f32x4){bflo(H.z), bfhi(H.z), bflo(H.w), bfhi(H.w)} + lo_unpack4(L.y)) + d1;
;                 u32x4 w; w.x = cvt_pk_bf16(o0[0], o0[1]); w.y = cvt_pk_bf16(o0[2], o0[3]); w.z = cvt_pk_bf16(o1[0], o1[1]); w.w = cvt_pk_bf16(o1[2], o1[3]);
;                 u32x2 wl; wl.x = lo_pack4(o0[0] - bflo(w.x), o0[1] - bfhi(w.x), o0[2] - bflo(w.y), o0[3] - bfhi(w.y));
;                 wl.y = lo_pack4(o1[0] - bflo(w.z), o1[1] - bfhi(w.z), o1[2] - bflo(w.w), o1[3] - bfhi(w.w));
;                 *GP(u32x4, hout + off + bj * 128) = w; (void)wl;
;                 ss += (o0[0] * o0[0] + o0[1] * o0[1]) + (o0[2] * o0[2] + o0[3] * o0[3]) + (o1[0] * o1[0] + o1[1] * o1[1]) + (o1[2] * o1[2] + o1[3] * o1[3]);
;             }
;             ss += __shfl_xor(ss, 16); ss += __shfl_xor(ss, 32);
;             if (fq == 0) *GP(float, ssp + (size_t)(u.pn * 4 + wc) * TT + row) = ss;
	s_lshl_b32 s20, s37, 2
	s_or_b32 s24, s20, s75
	s_ashr_i32 s25, s24, 31
	s_lshl_b64 s[24:25], s[24:25], 18
	s_add_u32 s24, s73, s24
	s_addc_u32 s25, s74, s25
	s_waitcnt lgkmcnt(0)
	v_add_f32_e32 v26, v24, v25
	v_lshl_add_u64 v[24:25], v[92:93], 2, s[24:25]
	global_store_dword v[24:25], v26, off
.LBB0_540:
	s_or_b64 exec, exec, s[12:13]
	s_waitcnt vmcnt(7)
	v_lshlrev_b32_e32 v76, 16, v20
	v_and_b32_e32 v77, 0xffff0000, v20
	v_lshlrev_b32_e32 v20, 16, v21
	v_and_b32_e32 v21, 0xffff0000, v21
	v_pk_add_f32 v[20:21], v[124:125], v[20:21]
	v_pk_add_f32 v[76:77], v[126:127], v[76:77]
	v_pk_add_f32 v[74:75], v[74:75], v[20:21]
	v_lshlrev_b32_e32 v20, 16, v22
	v_and_b32_e32 v21, 0xffff0000, v22
	v_pk_add_f32 v[72:73], v[72:73], v[76:77]
	v_pk_add_f32 v[20:21], v[126:127], v[20:21]
	v_lshlrev_b32_e32 v22, 16, v23
	v_and_b32_e32 v23, 0xffff0000, v23
	v_pk_add_f32 v[68:69], v[68:69], v[20:21]
	v_cvt_pk_bf16_f32 v20, v72, v73
	v_mul_f32_e32 v73, v73, v73
	v_pk_add_f32 v[22:23], v[124:125], v[22:23]
	v_fmac_f32_e32 v73, v72, v72
	v_mul_f32_e32 v72, v75, v75
	v_pk_add_f32 v[70:71], v[70:71], v[22:23]
	v_cvt_pk_bf16_f32 v22, v68, v69
	v_fmac_f32_e32 v72, v74, v74
	v_mul_f32_e32 v69, v69, v69
	v_add_f32_e32 v72, v73, v72
	v_fmac_f32_e32 v69, v68, v68
	v_add_f32_e32 v68, v69, v72
	v_mul_f32_e32 v69, v71, v71
	v_fmac_f32_e32 v69, v70, v70
	v_cvt_pk_bf16_f32 v23, v70, v71
	v_add_f32_e32 v70, v69, v68
	s_waitcnt vmcnt(6)
	v_lshlrev_b32_e32 v68, 16, v16
	v_and_b32_e32 v69, 0xffff0000, v16
	v_lshlrev_b32_e32 v16, 16, v17
	v_and_b32_e32 v17, 0xffff0000, v17
	v_pk_add_f32 v[68:69], v[126:127], v[68:69]
	v_pk_add_f32 v[16:17], v[124:125], v[16:17]
	v_add_u32_e32 v24, s21, v205
	v_pk_add_f32 v[66:67], v[66:67], v[16:17]
	v_pk_add_f32 v[16:17], v[64:65], v[68:69]
	v_lshlrev_b32_e32 v64, 16, v18
	v_and_b32_e32 v65, 0xffff0000, v18
	v_lshlrev_b32_e32 v18, 16, v19
	v_and_b32_e32 v19, 0xffff0000, v19
	v_pk_add_f32 v[18:19], v[124:125], v[18:19]
	v_pk_add_f32 v[64:65], v[126:127], v[64:65]
	v_pk_add_f32 v[62:63], v[62:63], v[18:19]
	v_mul_f32_e32 v18, v17, v17
	v_mul_f32_e32 v19, v67, v67
	v_pk_add_f32 v[60:61], v[60:61], v[64:65]
	v_fmac_f32_e32 v18, v16, v16
	v_fmac_f32_e32 v19, v66, v66
	v_add_f32_e32 v18, v18, v19
	v_mul_f32_e32 v19, v61, v61
	v_fmac_f32_e32 v19, v60, v60
	v_add_f32_e32 v18, v19, v18
	v_mul_f32_e32 v19, v63, v63
	v_fmac_f32_e32 v19, v62, v62
	v_add_f32_e32 v18, v19, v18
	v_add_f32_e32 v64, v70, v18
	s_waitcnt lgkmcnt(0)
	v_ashrrev_i32_e32 v25, 31, v24
	v_mov_b32_e32 v65, v64
	s_nop 1
	v_permlane16_swap_b32_e32 v64, v65
	v_lshlrev_b64 v[26:27], 11, v[24:25]
	v_lshl_add_u64 v[26:27], s[18:19], 0, v[26:27]
	v_lshl_add_u64 v[26:27], s[48:49], 1, v[26:27]
	v_lshl_add_u64 v[18:19], v[26:27], 0, s[62:63]
	v_lshl_add_u64 v[26:27], v[18:19], 0, v[168:169]
	v_cvt_pk_bf16_f32 v18, v16, v17
	s_waitcnt lgkmcnt(0)
	v_add_f32_e32 v16, v64, v65
	v_mov_b32_e32 v17, v16
	s_nop 1
	v_permlane32_swap_b32_e32 v16, v17
	v_cvt_pk_bf16_f32 v21, v74, v75
	global_store_dwordx4 v[26:27], v[20:23], off
	v_cvt_pk_bf16_f32 v19, v66, v67
	s_nop 0
	v_cvt_pk_bf16_f32 v20, v60, v61
	v_cvt_pk_bf16_f32 v21, v62, v63
	global_store_dwordx4 v[26:27], v[18:21], off offset:256
	s_and_saveexec_b64 s[12:13], s[42:43]
	s_cbranch_execz .LBB0_542
	s_lshl_b32 s20, s37, 2
	s_or_b32 s20, s20, s75
	s_ashr_i32 s21, s20, 31
	s_lshl_b64 s[20:21], s[20:21], 18
	s_add_u32 s20, s73, s20
	s_addc_u32 s21, s74, s21
	s_waitcnt lgkmcnt(0)
	v_add_f32_e32 v18, v16, v17
	v_lshl_add_u64 v[16:17], v[24:25], 2, s[20:21]
	global_store_dword v[16:17], v18, off
; __device__ __forceinline__ float bflo(unsigned w) { return __uint_as_float(w << 16); }
;     template <int NM> __device__ __forceinline__ void round(const AccT& acc, const Unit& u, int ai, int m0, int wr, int wc, int fr, int fq) const {
;     ...
;         for (int mm = 0; mm < NM; ++mm) {
;             const int m = m0 + mm;
;             const int rl = ai * 128 + wr * 64 + m * 16 + fr; const int row = u.pm * 256 + rl;
;             const size_t off = (size_t)row * DM + u.pn * 256 + wc * 32 + 8 * fq;
;             float r = 1.f; if (MODE == 1) r = rs[((u.pm >> 3) & 3) * 256 + rl];
;             float ss = 0.f;
; #pragma unroll
;             for (int bj = 0; bj < 2; ++bj) {
;                 f32x4 d0, d1;
;                 if (MODE == 0) { d0 = acc[ai][bj][m][0] * alpha; d1 = acc[ai][bj][m][1] * alpha; }
;                 else {
;                     const u32x4 p = pv[mm][bj];
;                     const f32x4 a0 = acc[ai][bj][m][0] * r, a1 = acc[ai][bj][m][1] * r;
;                     d0 = (f32x4){fsigmoid(a0[0]) * bflo(p.x), fsigmoid(a0[1]) * bfhi(p.x), fsigmoid(a0[2]) * bflo(p.y), fsigmoid(a0[3]) * bfhi(p.y)};
;                     d1 = (f32x4){fsigmoid(a1[0]) * bflo(p.z), fsigmoid(a1[1]) * bfhi(p.z), fsigmoid(a1[2]) * bflo(p.w), fsigmoid(a1[3]) * bfhi(p.w)};
;                 }
;                 const u32x4 H = hv[mm][bj]; const u32x2 L = lv[mm][bj];
;                 const f32x4 o0 = ((f32x4){bflo(H.x), bfhi(H.x), bflo(H.y), bfhi(H.y)} + lo_unpack4(L.x)) + d0;
;                 const f32x4 o1 = ((f32x4){bflo(H.z), bfhi(H.z), bflo(H.w), bfhi(H.w)} + lo_unpack4(L.y)) + d1;
;                 u32x4 w; w.x = cvt_pk_bf16(o0[0], o0[1]); w.y = cvt_pk_bf16(o0[2], o0[3]); w.z = cvt_pk_bf16(o1[0], o1[1]); w.w = cvt_pk_bf16(o1[2], o1[3]);
;                 u32x2 wl; wl.x = lo_pack4(o0[0] - bflo(w.x), o0[1] - bfhi(w.x), o0[2] - bflo(w.y), o0[3] - bfhi(w.y));
;                 wl.y = lo_pack4(o1[0] - bflo(w.z), o1[1] - bfhi(w.z), o1[2] - bflo(w.w), o1[3] - bfhi(w.w));
;                 *GP(u32x4, hout + off + bj * 128) = w; (void)wl;
;                 ss += (o0[0] * o0[0] + o0[1] * o0[1]) + (o0[2] * o0[2] + o0[3] * o0[3]) + (o1[0] * o1[0] + o1[1] * o1[1]) + (o1[2] * o1[2] + o1[3] * o1[3]);
;             }
;             ss += __shfl_xor(ss, 16); ss += __shfl_xor(ss, 32);
;             if (fq == 0) *GP(float, ssp + (size_t)(u.pn * 4 + wc) * TT + row) = ss;
.LBB0_542:
	s_or_b64 exec, exec, s[12:13]
	s_waitcnt vmcnt(7)
	v_lshlrev_b32_e32 v20, 16, v12
	v_and_b32_e32 v21, 0xffff0000, v12
	v_lshlrev_b32_e32 v12, 16, v13
	v_and_b32_e32 v13, 0xffff0000, v13
	v_pk_add_f32 v[12:13], v[124:125], v[12:13]
	v_pk_add_f32 v[20:21], v[126:127], v[20:21]
	v_pk_add_f32 v[22:23], v[58:59], v[12:13]
	v_lshlrev_b32_e32 v12, 16, v14
	v_and_b32_e32 v13, 0xffff0000, v14
	v_pk_add_f32 v[20:21], v[56:57], v[20:21]
	v_pk_add_f32 v[12:13], v[126:127], v[12:13]
	v_lshlrev_b32_e32 v14, 16, v15
	v_pk_add_f32 v[26:27], v[52:53], v[12:13]
	v_cvt_pk_bf16_f32 v12, v20, v21
	v_mul_f32_e32 v21, v21, v21
	v_fmac_f32_e32 v21, v20, v20
	v_mul_f32_e32 v20, v23, v23
	v_and_b32_e32 v15, 0xffff0000, v15
	v_fmac_f32_e32 v20, v22, v22
	v_pk_add_f32 v[14:15], v[124:125], v[14:15]
	v_add_f32_e32 v20, v21, v20
	v_mul_f32_e32 v21, v27, v27
	v_pk_add_f32 v[24:25], v[54:55], v[14:15]
	v_fmac_f32_e32 v21, v26, v26
	v_add_f32_e32 v20, v21, v20
	v_mul_f32_e32 v21, v25, v25
	v_fmac_f32_e32 v21, v24, v24
	v_cvt_pk_bf16_f32 v14, v26, v27
	v_add_f32_e32 v26, v21, v20
	s_waitcnt vmcnt(6)
	v_lshlrev_b32_e32 v20, 16, v8
	v_and_b32_e32 v21, 0xffff0000, v8
	v_lshlrev_b32_e32 v8, 16, v9
	v_and_b32_e32 v9, 0xffff0000, v9
	v_pk_add_f32 v[20:21], v[126:127], v[20:21]
	v_pk_add_f32 v[8:9], v[124:125], v[8:9]
	v_cvt_pk_bf16_f32 v13, v22, v23
	v_pk_add_f32 v[22:23], v[50:51], v[8:9]
	v_pk_add_f32 v[8:9], v[48:49], v[20:21]
	v_lshlrev_b32_e32 v20, 16, v10
	v_and_b32_e32 v21, 0xffff0000, v10
	v_lshlrev_b32_e32 v10, 16, v11
	v_and_b32_e32 v11, 0xffff0000, v11
	v_pk_add_f32 v[10:11], v[124:125], v[10:11]
	v_cvt_pk_bf16_f32 v15, v24, v25
	v_pk_add_f32 v[20:21], v[126:127], v[20:21]
	v_pk_add_f32 v[24:25], v[46:47], v[10:11]
	v_mul_f32_e32 v10, v9, v9
	v_mul_f32_e32 v11, v23, v23
	v_pk_add_f32 v[20:21], v[44:45], v[20:21]
	v_fmac_f32_e32 v10, v8, v8
	v_fmac_f32_e32 v11, v22, v22
	v_add_f32_e32 v10, v10, v11
	v_mul_f32_e32 v11, v21, v21
	v_fmac_f32_e32 v11, v20, v20
	v_add_f32_e32 v10, v11, v10
	v_mul_f32_e32 v11, v25, v25
	v_fmac_f32_e32 v11, v24, v24
	v_add_f32_e32 v10, v11, v10
	v_add_u32_e32 v16, s22, v205
	v_add_f32_e32 v26, v26, v10
	s_waitcnt lgkmcnt(0)
	v_ashrrev_i32_e32 v17, 31, v16
	v_mov_b32_e32 v27, v26
	s_nop 1
	v_permlane16_swap_b32_e32 v26, v27
	v_lshlrev_b64 v[18:19], 11, v[16:17]
	v_lshl_add_u64 v[18:19], s[18:19], 0, v[18:19]
	v_lshl_add_u64 v[18:19], s[48:49], 1, v[18:19]
	v_lshl_add_u64 v[10:11], v[18:19], 0, s[62:63]
	v_lshl_add_u64 v[18:19], v[10:11], 0, v[168:169]
	v_cvt_pk_bf16_f32 v10, v8, v9
	s_waitcnt lgkmcnt(0)
	v_add_f32_e32 v8, v26, v27
	v_mov_b32_e32 v9, v8
	s_nop 1
	v_permlane32_swap_b32_e32 v8, v9
	global_store_dwordx4 v[18:19], v[12:15], off
	v_cvt_pk_bf16_f32 v11, v22, v23
	s_nop 0
	v_cvt_pk_bf16_f32 v12, v20, v21
	v_cvt_pk_bf16_f32 v13, v24, v25
	global_store_dwordx4 v[18:19], v[10:13], off offset:256
	s_and_saveexec_b64 s[12:13], s[42:43]
	s_cbranch_execz .LBB0_544
	s_lshl_b32 s20, s37, 2
	s_or_b32 s20, s20, s75
	s_ashr_i32 s21, s20, 31
	s_lshl_b64 s[20:21], s[20:21], 18
	s_add_u32 s20, s73, s20
	s_addc_u32 s21, s74, s21
	s_waitcnt lgkmcnt(0)
	v_add_f32_e32 v10, v8, v9
	v_lshl_add_u64 v[8:9], v[16:17], 2, s[20:21]
	global_store_dword v[8:9], v10, off
.LBB0_544:
	s_or_b64 exec, exec, s[12:13]
	s_waitcnt vmcnt(7)
	v_lshlrev_b32_e32 v12, 16, v4
	v_and_b32_e32 v13, 0xffff0000, v4
	v_lshlrev_b32_e32 v4, 16, v5
	v_and_b32_e32 v5, 0xffff0000, v5
	v_pk_add_f32 v[4:5], v[124:125], v[4:5]
	v_pk_add_f32 v[12:13], v[126:127], v[12:13]
	v_pk_add_f32 v[14:15], v[42:43], v[4:5]
	v_lshlrev_b32_e32 v4, 16, v6
	v_and_b32_e32 v5, 0xffff0000, v6
	v_pk_add_f32 v[12:13], v[40:41], v[12:13]
	v_pk_add_f32 v[4:5], v[126:127], v[4:5]
	v_lshlrev_b32_e32 v6, 16, v7
	v_pk_add_f32 v[18:19], v[36:37], v[4:5]
	v_cvt_pk_bf16_f32 v4, v12, v13
	v_mul_f32_e32 v13, v13, v13
	v_fmac_f32_e32 v13, v12, v12
	v_mul_f32_e32 v12, v15, v15
	v_and_b32_e32 v7, 0xffff0000, v7
	v_fmac_f32_e32 v12, v14, v14
	v_pk_add_f32 v[6:7], v[124:125], v[6:7]
	v_add_f32_e32 v12, v13, v12
	v_mul_f32_e32 v13, v19, v19
	v_pk_add_f32 v[16:17], v[38:39], v[6:7]
	v_fmac_f32_e32 v13, v18, v18
	v_add_f32_e32 v12, v13, v12
	v_mul_f32_e32 v13, v17, v17
	v_fmac_f32_e32 v13, v16, v16
	v_cvt_pk_bf16_f32 v6, v18, v19
	v_add_f32_e32 v18, v13, v12
	s_waitcnt vmcnt(6)
	v_lshlrev_b32_e32 v12, 16, v0
	v_and_b32_e32 v13, 0xffff0000, v0
	v_lshlrev_b32_e32 v0, 16, v1
	v_and_b32_e32 v1, 0xffff0000, v1
	v_pk_add_f32 v[12:13], v[126:127], v[12:13]
	v_pk_add_f32 v[0:1], v[124:125], v[0:1]
	v_cvt_pk_bf16_f32 v5, v14, v15
	v_pk_add_f32 v[14:15], v[34:35], v[0:1]
	v_pk_add_f32 v[0:1], v[32:33], v[12:13]
	v_lshlrev_b32_e32 v12, 16, v2
	v_and_b32_e32 v13, 0xffff0000, v2
	v_lshlrev_b32_e32 v2, 16, v3
	v_and_b32_e32 v3, 0xffff0000, v3
	v_pk_add_f32 v[2:3], v[124:125], v[2:3]
	v_cvt_pk_bf16_f32 v7, v16, v17
	v_pk_add_f32 v[12:13], v[126:127], v[12:13]
	v_pk_add_f32 v[16:17], v[30:31], v[2:3]
	v_mul_f32_e32 v2, v1, v1
	v_mul_f32_e32 v3, v15, v15
	v_pk_add_f32 v[12:13], v[28:29], v[12:13]
	v_fmac_f32_e32 v2, v0, v0
	v_fmac_f32_e32 v3, v14, v14
	v_add_f32_e32 v2, v2, v3
	v_mul_f32_e32 v3, v13, v13
	v_fmac_f32_e32 v3, v12, v12
	v_add_f32_e32 v2, v3, v2
	v_mul_f32_e32 v3, v17, v17
	v_fmac_f32_e32 v3, v16, v16
	v_add_f32_e32 v2, v3, v2
	v_add_u32_e32 v8, s23, v205
	v_add_f32_e32 v18, v18, v2
	s_waitcnt lgkmcnt(0)
	v_ashrrev_i32_e32 v9, 31, v8
	v_mov_b32_e32 v19, v18
	s_nop 1
	v_permlane16_swap_b32_e32 v18, v19
	v_lshlrev_b64 v[10:11], 11, v[8:9]
	v_lshl_add_u64 v[10:11], s[18:19], 0, v[10:11]
	v_lshl_add_u64 v[10:11], s[48:49], 1, v[10:11]
	v_lshl_add_u64 v[2:3], v[10:11], 0, s[62:63]
	v_lshl_add_u64 v[10:11], v[2:3], 0, v[168:169]
	v_cvt_pk_bf16_f32 v2, v0, v1
	s_waitcnt lgkmcnt(0)
	v_add_f32_e32 v0, v18, v19
	v_mov_b32_e32 v1, v0
	s_nop 1
	v_permlane32_swap_b32_e32 v0, v1
	global_store_dwordx4 v[10:11], v[4:7], off
	v_cvt_pk_bf16_f32 v3, v14, v15
	s_nop 0
	v_cvt_pk_bf16_f32 v4, v12, v13
	v_cvt_pk_bf16_f32 v5, v16, v17
	global_store_dwordx4 v[10:11], v[2:5], off offset:256
	s_and_saveexec_b64 s[12:13], s[42:43]
	s_cbranch_execz .LBB0_515
	s_lshl_b32 s20, s37, 2
	s_or_b32 s20, s20, s75
	s_ashr_i32 s21, s20, 31
	s_lshl_b64 s[20:21], s[20:21], 18
	s_add_u32 s20, s73, s20
	s_addc_u32 s21, s74, s21
	s_waitcnt lgkmcnt(0)
	v_add_f32_e32 v2, v0, v1
	v_lshl_add_u64 v[0:1], v[8:9], 2, s[20:21]
	global_store_dword v[0:1], v2, off
	s_branch .LBB0_515

;     template <int NM> __device__ __forceinline__ void round(const AccT& acc, const Unit& u, int ai, int m0, int wr, int wc, int fr, int fq) const {
;         u32x4 hv[NM][2], pv[NM][2]; u32x2 lv[NM][2];
; #pragma unroll
;         for (int mm = 0; mm < NM; ++mm) {
;             const int rl = ai * 128 + wr * 64 + (m0 + mm) * 16 + fr;
;             const size_t off = (size_t)(u.pm * 256 + rl) * DM + u.pn * 256 + wc * 32 + 8 * fq;
; #pragma unroll
;             for (int bj = 0; bj < 2; ++bj) {
;                 hv[mm][bj] = *GP(const u32x4, hin + off + bj * 128); lv[mm][bj] = (u32x2){0u, 0u};
;                 if (MODE == 1) pv[mm][bj] = *GP(const u32x4, proj + off + bj * 128);
;             }
;         }
; #pragma unroll
;         for (int mm = 0; mm < NM; ++mm) {
;             const int m = m0 + mm;
;             const int rl = ai * 128 + wr * 64 + m * 16 + fr; const int row = u.pm * 256 + rl;
;             const size_t off = (size_t)row * DM + u.pn * 256 + wc * 32 + 8 * fq;
;             float r = 1.f; if (MODE == 1) r = rs[((u.pm >> 3) & 3) * 256 + rl];
;             float ss = 0.f;
; #pragma unroll
;             for (int bj = 0; bj < 2; ++bj) {
;                 f32x4 d0, d1;
;                 if (MODE == 0) { d0 = acc[ai][bj][m][0] * alpha; d1 = acc[ai][bj][m][1] * alpha; }
;                 else {
;                     const u32x4 p = pv[mm][bj];
;                     const f32x4 a0 = acc[ai][bj][m][0] * r, a1 = acc[ai][bj][m][1] * r;
;                     d0 = (f32x4){fsigmoid(a0[0]) * bflo(p.x), fsigmoid(a0[1]) * bfhi(p.x), fsigmoid(a0[2]) * bflo(p.y), fsigmoid(a0[3]) * bfhi(p.y)};
;                     d1 = (f32x4){fsigmoid(a1[0]) * bflo(p.z), fsigmoid(a1[1]) * bfhi(p.z), fsigmoid(a1[2]) * bflo(p.w), fsigmoid(a1[3]) * bfhi(p.w)};
;                 }
;                 const u32x4 H = hv[mm][bj]; const u32x2 L = lv[mm][bj];
;                 const f32x4 o0 = ((f32x4){bflo(H.x), bfhi(H.x), bflo(H.y), bfhi(H.y)} + lo_unpack4(L.x)) + d0;
;                 const f32x4 o1 = ((f32x4){bflo(H.z), bfhi(H.z), bflo(H.w), bfhi(H.w)} + lo_unpack4(L.y)) + d1;
;                 u32x4 w; w.x = cvt_pk_bf16(o0[0], o0[1]); w.y = cvt_pk_bf16(o0[2], o0[3]); w.z = cvt_pk_bf16(o1[0], o1[1]); w.w = cvt_pk_bf16(o1[2], o1[3]);
;                 u32x2 wl; wl.x = lo_pack4(o0[0] - bflo(w.x), o0[1] - bfhi(w.x), o0[2] - bflo(w.y), o0[3] - bfhi(w.y));
.LBB0_577:
	s_lshl_b32 s26, s81, 2
	s_add_i32 s26, s26, s25
	s_lshl_b32 s26, s26, 17
	s_mov_b32 s27, 0
	v_and_b32_e32 v176, 0xffffffc0, v162
	v_lshlrev_b32_e32 v176, 8, v176
	v_lshl_add_u32 v176, v208, 4, v176
	v_mov_b32_e32 v177, 0
	v_lshl_add_u64 v[176:177], s[26:27], 0, v[176:177]
	v_lshl_add_u64 v[176:177], s[18:19], 0, v[176:177]
	s_lshl_b32 s46, s81, 8
	v_add_u32_e32 v192, s46, v148
	s_lshl_b32 s16, s25, 8
	s_ashr_i32 s17, s16, 31
	v_ashrrev_i32_e32 v193, 31, v192
	v_mov_b32_e32 v159, s17
	v_or_b32_e32 v158, s16, v150
	v_lshlrev_b64 v[128:129], 10, v[192:193]
	v_lshl_add_u64 v[128:129], v[128:129], 0, v[158:159]
	v_lshlrev_b64 v[128:129], 1, v[128:129]
	v_mov_b64_e32 v[130:131], v[176:177]
	v_lshl_add_u64 v[128:129], s[66:67], 0, v[128:129]
	global_load_dwordx4 v[212:215], v[130:131], off
	global_load_dwordx4 v[216:219], v[128:129], off
	s_lshl_b32 s12, s81, 7
	s_and_b32 s12, s12, 0xc00
	s_add_i32 s12, s12, 0
	s_add_i32 s12, s12, 0x20000
	v_lshl_add_u32 v205, v148, 2, s12
	ds_read_b32 v224, v205
	global_load_dwordx4 v[144:147], v[128:129], off offset:256
	global_load_dwordx4 v[220:223], v[130:131], off offset:1024
	v_and_b32_e32 v132, 64, v163
	v_xor_b32_e32 v133, 16, v163
	v_add_u32_e32 v135, 64, v132
	v_or_b32_e32 v132, 16, v192
	v_cmp_lt_i32_e32 vcc, v133, v135
	v_xor_b32_e32 v134, 32, v163
	s_waitcnt lgkmcnt(0)
	v_pk_mul_f32 v[122:123], v[122:123], v[224:225] op_sel_hi:[1,0]
	v_cndmask_b32_e32 v136, v163, v133, vcc
	v_ashrrev_i32_e32 v133, 31, v132
	v_lshlrev_b64 v[132:133], 10, v[132:133]
	v_lshl_add_u64 v[132:133], v[132:133], 0, v[158:159]
	v_cmp_lt_i32_e32 vcc, v134, v135
	v_lshlrev_b64 v[132:133], 1, v[132:133]
	v_lshl_add_u64 v[128:129], s[66:67], 0, v[132:133]
	v_cndmask_b32_e32 v134, v163, v134, vcc
	s_mov_b64 s[26:27], 0x800
	v_lshl_add_u64 v[132:133], v[176:177], 0, s[26:27]
	v_lshlrev_b32_e32 v204, 2, v136
	v_lshlrev_b32_e32 v203, 2, v134
	global_load_dwordx4 v[136:139], v[128:129], off
	s_nop 0
	global_load_dwordx4 v[128:131], v[128:129], off offset:256
	s_nop 0
	global_load_dwordx4 v[140:143], v[132:133], off
	s_nop 0
	global_load_dwordx4 v[132:135], v[132:133], off offset:1024
	v_pk_mul_f32 v[120:121], v[120:121], v[224:225] op_sel_hi:[1,0]
	v_pk_mul_f32 v[126:127], v[126:127], v[224:225] op_sel_hi:[1,0]
	v_pk_mul_f32 v[124:125], v[124:125], v[224:225] op_sel_hi:[1,0]
	v_mul_f32_e32 v120, 0xbfb8aa3b, v120
	v_mul_f32_e32 v121, 0xbfb8aa3b, v121
	v_mul_f32_e32 v122, 0xbfb8aa3b, v122
	v_mul_f32_e32 v123, 0xbfb8aa3b, v123
	v_mul_f32_e32 v124, 0xbfb8aa3b, v124
	v_mul_f32_e32 v125, 0xbfb8aa3b, v125
	v_mul_f32_e32 v126, 0xbfb8aa3b, v126
	v_mul_f32_e32 v127, 0xbfb8aa3b, v127
	v_exp_f32_e32 v120, v120
	v_exp_f32_e32 v121, v121
	v_exp_f32_e32 v122, v122
	v_exp_f32_e32 v123, v123
	v_exp_f32_e32 v124, v124
	v_exp_f32_e32 v125, v125
	v_exp_f32_e32 v126, v126
	v_exp_f32_e32 v127, v127
	v_add_f32_e32 v120, 1.0, v120
	v_add_f32_e32 v121, 1.0, v121
	v_add_f32_e32 v122, 1.0, v122
	v_add_f32_e32 v123, 1.0, v123
	v_add_f32_e32 v124, 1.0, v124
	v_add_f32_e32 v125, 1.0, v125
	v_add_f32_e32 v126, 1.0, v126
	v_add_f32_e32 v127, 1.0, v127
	v_rcp_f32_e32 v226, v120
	v_rcp_f32_e32 v227, v121
	v_rcp_f32_e32 v228, v122
	v_rcp_f32_e32 v229, v123
	v_cvt_pk_f32_fp8_e32 v[120:121], 0
	v_cvt_pk_f32_fp8_sdwa v[122:123], s63 src0_sel:WORD_1
	v_rcp_f32_e32 v124, v124
	v_rcp_f32_e32 v125, v125
	v_rcp_f32_e32 v126, v126
	v_rcp_f32_e32 v127, v127
	v_pk_mul_f32 v[118:119], v[118:119], v[224:225] op_sel_hi:[1,0]
	v_pk_mul_f32 v[116:117], v[116:117], v[224:225] op_sel_hi:[1,0]
	v_mul_f32_e32 v118, 0xbfb8aa3b, v118
	v_mul_f32_e32 v119, 0xbfb8aa3b, v119
	v_mul_f32_e32 v116, 0xbfb8aa3b, v116
	v_mul_f32_e32 v117, 0xbfb8aa3b, v117
	v_pk_mul_f32 v[112:113], v[112:113], v[224:225] op_sel_hi:[1,0]
	v_exp_f32_e32 v118, v118
	v_exp_f32_e32 v119, v119
	v_exp_f32_e32 v116, v116
	v_exp_f32_e32 v117, v117
	v_mul_f32_e32 v112, 0xbfb8aa3b, v112
	v_mul_f32_e32 v113, 0xbfb8aa3b, v113
	v_exp_f32_e32 v112, v112
	v_exp_f32_e32 v113, v113
	s_waitcnt vmcnt(0)
	v_lshlrev_b32_e32 v230, 16, v212
	v_lshlrev_b32_e32 v234, 16, v216
	v_and_b32_e32 v235, 0xffff0000, v216
	v_lshlrev_b32_e32 v216, 16, v217
	v_and_b32_e32 v217, 0xffff0000, v217
	v_and_b32_e32 v231, 0xffff0000, v212
	v_lshlrev_b32_e32 v212, 16, v213
	v_and_b32_e32 v213, 0xffff0000, v213
	v_pk_fma_f32 v[234:235], v[120:121], s[34:35], v[234:235] op_sel_hi:[1,0,1]
	v_pk_fma_f32 v[216:217], v[122:123], s[34:35], v[216:217] op_sel_hi:[1,0,1]
	v_lshlrev_b32_e32 v232, 16, v214
	v_pk_fma_f32 v[212:213], v[126:127], v[212:213], v[216:217]
	v_pk_fma_f32 v[216:217], v[124:125], v[230:231], v[234:235]
	v_lshlrev_b32_e32 v124, 16, v218
	v_and_b32_e32 v125, 0xffff0000, v218
	v_and_b32_e32 v233, 0xffff0000, v214
	v_pk_fma_f32 v[124:125], v[120:121], s[34:35], v[124:125] op_sel_hi:[1,0,1]
	v_lshlrev_b32_e32 v126, 16, v219
	v_and_b32_e32 v127, 0xffff0000, v219
	v_pk_fma_f32 v[218:219], v[226:227], v[232:233], v[124:125]
	v_cvt_pk_bf16_f32 v125, v212, v213
	v_mul_f32_e32 v211, v217, v217
	v_mul_f32_e32 v213, v213, v213
	v_lshlrev_b32_e32 v214, 16, v215
	v_and_b32_e32 v215, 0xffff0000, v215
	v_pk_fma_f32 v[126:127], v[122:123], s[34:35], v[126:127] op_sel_hi:[1,0,1]
	v_fmac_f32_e32 v211, v216, v216
	v_fmac_f32_e32 v213, v212, v212
	v_mul_f32_e32 v212, v219, v219
	v_pk_mul_f32 v[114:115], v[114:115], v[224:225] op_sel_hi:[1,0]
	v_pk_fma_f32 v[214:215], v[228:229], v[214:215], v[126:127]
	v_add_f32_e32 v211, v211, v213
	v_fmac_f32_e32 v212, v218, v218
	v_add_f32_e32 v118, 1.0, v118
	v_add_f32_e32 v119, 1.0, v119
	v_mul_f32_e32 v114, 0xbfb8aa3b, v114
	v_mul_f32_e32 v115, 0xbfb8aa3b, v115
	v_add_f32_e32 v211, v212, v211
	v_mul_f32_e32 v212, v215, v215
; __device__ __forceinline__ float bflo(unsigned w) { return __uint_as_float(w << 16); }
;     template <int NM> __device__ __forceinline__ void round(const AccT& acc, const Unit& u, int ai, int m0, int wr, int wc, int fr, int fq) const {
;     ...
;         for (int mm = 0; mm < NM; ++mm) {
;             const int m = m0 + mm;
;             const int rl = ai * 128 + wr * 64 + m * 16 + fr; const int row = u.pm * 256 + rl;
;             const size_t off = (size_t)row * DM + u.pn * 256 + wc * 32 + 8 * fq;
;             float r = 1.f; if (MODE == 1) r = rs[((u.pm >> 3) & 3) * 256 + rl];
;             float ss = 0.f;
; #pragma unroll
;             for (int bj = 0; bj < 2; ++bj) {
;                 f32x4 d0, d1;
;                 if (MODE == 0) { d0 = acc[ai][bj][m][0] * alpha; d1 = acc[ai][bj][m][1] * alpha; }
;                 else {
;                     const u32x4 p = pv[mm][bj];
;                     const f32x4 a0 = acc[ai][bj][m][0] * r, a1 = acc[ai][bj][m][1] * r;
;                     d0 = (f32x4){fsigmoid(a0[0]) * bflo(p.x), fsigmoid(a0[1]) * bfhi(p.x), fsigmoid(a0[2]) * bflo(p.y), fsigmoid(a0[3]) * bfhi(p.y)};
;                     d1 = (f32x4){fsigmoid(a1[0]) * bflo(p.z), fsigmoid(a1[1]) * bfhi(p.z), fsigmoid(a1[2]) * bflo(p.w), fsigmoid(a1[3]) * bfhi(p.w)};
;                 }
;                 const u32x4 H = hv[mm][bj]; const u32x2 L = lv[mm][bj];
;                 const f32x4 o0 = ((f32x4){bflo(H.x), bfhi(H.x), bflo(H.y), bfhi(H.y)} + lo_unpack4(L.x)) + d0;
;                 const f32x4 o1 = ((f32x4){bflo(H.z), bfhi(H.z), bflo(H.w), bfhi(H.w)} + lo_unpack4(L.y)) + d1;
;                 u32x4 w; w.x = cvt_pk_bf16(o0[0], o0[1]); w.y = cvt_pk_bf16(o0[2], o0[3]); w.z = cvt_pk_bf16(o1[0], o1[1]); w.w = cvt_pk_bf16(o1[2], o1[3]);
;                 u32x2 wl; wl.x = lo_pack4(o0[0] - bflo(w.x), o0[1] - bfhi(w.x), o0[2] - bflo(w.y), o0[3] - bfhi(w.y));
;                 wl.y = lo_pack4(o1[0] - bflo(w.z), o1[1] - bfhi(w.z), o1[2] - bflo(w.w), o1[3] - bfhi(w.w));
;                 *GP(u32x4, hout + off + bj * 128) = w; (void)wl;
;                 ss += (o0[0] * o0[0] + o0[1] * o0[1]) + (o0[2] * o0[2] + o0[3] * o0[3]) + (o1[0] * o1[0] + o1[1] * o1[1]) + (o1[2] * o1[2] + o1[3] * o1[3]);
;             }
;             ss += __shfl_xor(ss, 16); ss += __shfl_xor(ss, 32);
;             if (fq == 0) *GP(float, ssp + (size_t)(u.pn * 4 + wc) * TT + row) = ss;
	v_add_f32_e32 v116, 1.0, v116
	v_add_f32_e32 v117, 1.0, v117
	v_rcp_f32_e32 v118, v118
	v_rcp_f32_e32 v119, v119
	v_exp_f32_e32 v114, v114
	v_exp_f32_e32 v115, v115
	v_fmac_f32_e32 v212, v214, v214
	v_rcp_f32_e32 v116, v116
	v_rcp_f32_e32 v117, v117
	v_add_f32_e32 v112, 1.0, v112
	v_add_f32_e32 v113, 1.0, v113
	v_cvt_pk_bf16_f32 v127, v214, v215
	v_add_f32_e32 v211, v212, v211
	v_lshlrev_b32_e32 v212, 16, v220
	v_and_b32_e32 v213, 0xffff0000, v220
	v_lshlrev_b32_e32 v214, 16, v221
	v_and_b32_e32 v215, 0xffff0000, v221
	v_rcp_f32_e32 v112, v112
	v_rcp_f32_e32 v113, v113
	v_lshlrev_b32_e32 v220, 16, v144
	v_and_b32_e32 v221, 0xffff0000, v144
	v_lshlrev_b32_e32 v144, 16, v145
	v_and_b32_e32 v145, 0xffff0000, v145
	v_pk_fma_f32 v[144:145], v[122:123], s[34:35], v[144:145] op_sel_hi:[1,0,1]
	v_add_f32_e32 v114, 1.0, v114
	v_add_f32_e32 v115, 1.0, v115
	v_pk_fma_f32 v[220:221], v[120:121], s[34:35], v[220:221] op_sel_hi:[1,0,1]
	v_pk_fma_f32 v[118:119], v[118:119], v[214:215], v[144:145]
	v_lshlrev_b32_e32 v144, 16, v146
	v_and_b32_e32 v145, 0xffff0000, v146
	v_cvt_pk_bf16_f32 v124, v216, v217
	v_lshlrev_b32_e32 v216, 16, v222
	v_and_b32_e32 v217, 0xffff0000, v222
	v_rcp_f32_e32 v114, v114
	v_rcp_f32_e32 v115, v115
	v_pk_fma_f32 v[116:117], v[116:117], v[212:213], v[220:221]
	v_pk_fma_f32 v[144:145], v[120:121], s[34:35], v[144:145] op_sel_hi:[1,0,1]
	v_lshlrev_b32_e32 v146, 16, v147
	v_pk_fma_f32 v[144:145], v[112:113], v[216:217], v[144:145]
	v_mul_f32_e32 v112, v117, v117
	v_mul_f32_e32 v113, v119, v119
	v_and_b32_e32 v147, 0xffff0000, v147
	v_fmac_f32_e32 v112, v116, v116
	v_fmac_f32_e32 v113, v118, v118
	v_cvt_pk_bf16_f32 v126, v218, v219
	v_lshlrev_b32_e32 v218, 16, v223
	v_and_b32_e32 v219, 0xffff0000, v223
	v_pk_fma_f32 v[146:147], v[122:123], s[34:35], v[146:147] op_sel_hi:[1,0,1]
	v_add_f32_e32 v112, v112, v113
	v_mul_f32_e32 v113, v145, v145
	v_pk_fma_f32 v[146:147], v[114:115], v[218:219], v[146:147]
	v_fmac_f32_e32 v113, v144, v144
	v_add_f32_e32 v112, v113, v112
	v_mul_f32_e32 v113, v147, v147
	v_fmac_f32_e32 v113, v146, v146
	v_add_f32_e32 v112, v113, v112
	v_add_f32_e32 v115, v211, v112
	v_mov_b32_e32 v211, v115
	s_nop 1
	v_permlane16_swap_b32_e32 v115, v211
	v_lshlrev_b64 v[206:207], 11, v[192:193]
	v_lshl_add_u64 v[206:207], s[14:15], 0, v[206:207]
	v_lshl_add_u64 v[206:207], s[16:17], 1, v[206:207]
	v_lshl_add_u64 v[112:113], v[206:207], 0, s[62:63]
	v_lshl_add_u64 v[206:207], v[112:113], 0, v[168:169]
	s_waitcnt lgkmcnt(0)
	v_add_f32_e32 v112, v115, v211
	v_mov_b32_e32 v113, v112
	s_nop 1
	v_permlane32_swap_b32_e32 v112, v113
	v_cvt_pk_bf16_f32 v114, v116, v117
	v_cvt_pk_bf16_f32 v115, v118, v119
	v_cvt_pk_bf16_f32 v116, v144, v145
	v_cvt_pk_bf16_f32 v117, v146, v147
	global_store_dwordx4 v[206:207], v[124:127], off
	global_store_dwordx4 v[206:207], v[114:117], off offset:256
	s_and_saveexec_b64 s[12:13], s[42:43]
	s_cbranch_execz .LBB0_579
	s_lshl_b32 s20, s25, 2
	s_or_b32 s20, s20, s71
	s_ashr_i32 s21, s20, 31
	s_lshl_b64 s[20:21], s[20:21], 18
	s_add_u32 s20, s65, s20
	s_addc_u32 s21, s70, s21
	s_waitcnt lgkmcnt(0)
	v_add_f32_e32 v114, v112, v113
	v_lshl_add_u64 v[112:113], v[192:193], 2, s[20:21]
	global_store_dword v[112:113], v114, off
.LBB0_579:
	s_or_b64 exec, exec, s[12:13]
	ds_read_b32 v112, v205 offset:64
	v_pk_mul_f32 v[146:147], v[120:121], s[34:35] op_sel_hi:[1,0]
	v_lshlrev_b32_e32 v124, 16, v136
	v_and_b32_e32 v125, 0xffff0000, v136
	v_lshlrev_b32_e32 v116, 16, v140
	s_waitcnt lgkmcnt(0)
	v_pk_mul_f32 v[108:109], v[108:109], v[112:113] op_sel_hi:[1,0]
	v_pk_mul_f32 v[110:111], v[110:111], v[112:113] op_sel_hi:[1,0]
	v_mul_f32_e32 v108, 0xbfb8aa3b, v108
	v_mul_f32_e32 v109, 0xbfb8aa3b, v109
	v_exp_f32_e32 v108, v108
	v_exp_f32_e32 v109, v109
	v_pk_mul_f32 v[104:105], v[104:105], v[112:113] op_sel_hi:[1,0]
	v_mul_f32_e32 v110, 0xbfb8aa3b, v110
	v_mul_f32_e32 v111, 0xbfb8aa3b, v111
	v_mul_f32_e32 v104, 0xbfb8aa3b, v104
	v_mul_f32_e32 v105, 0xbfb8aa3b, v105
	v_exp_f32_e32 v110, v110
	v_exp_f32_e32 v111, v111
	v_exp_f32_e32 v104, v104
	v_exp_f32_e32 v105, v105
	v_pk_mul_f32 v[106:107], v[106:107], v[112:113] op_sel_hi:[1,0]
	v_add_f32_e32 v108, 1.0, v108
	v_add_f32_e32 v109, 1.0, v109
	v_rcp_f32_e32 v108, v108
	v_rcp_f32_e32 v109, v109
	v_mul_f32_e32 v106, 0xbfb8aa3b, v106
	v_mul_f32_e32 v107, 0xbfb8aa3b, v107
	v_add_f32_e32 v110, 1.0, v110
	v_add_f32_e32 v111, 1.0, v111
	v_add_f32_e32 v104, 1.0, v104
	v_add_f32_e32 v105, 1.0, v105
	v_exp_f32_e32 v106, v106
	v_exp_f32_e32 v107, v107
	v_rcp_f32_e32 v110, v110
	v_rcp_f32_e32 v111, v111
	v_rcp_f32_e32 v104, v104
	v_rcp_f32_e32 v105, v105
	v_and_b32_e32 v117, 0xffff0000, v140
	v_pk_add_f32 v[124:125], v[146:147], v[124:125]
	v_pk_mul_f32 v[100:101], v[100:101], v[112:113] op_sel_hi:[1,0]
	v_pk_mul_f32 v[144:145], v[122:123], s[34:35] op_sel_hi:[1,0]
	v_lshlrev_b32_e32 v126, 16, v137
	v_and_b32_e32 v127, 0xffff0000, v137
	v_pk_fma_f32 v[108:109], v[108:109], v[116:117], v[124:125]
	v_lshlrev_b32_e32 v116, 16, v138
	v_and_b32_e32 v117, 0xffff0000, v138
	v_pk_mul_f32 v[102:103], v[102:103], v[112:113] op_sel_hi:[1,0]
	v_mul_f32_e32 v100, 0xbfb8aa3b, v100
	v_mul_f32_e32 v101, 0xbfb8aa3b, v101
	v_lshlrev_b32_e32 v118, 16, v141
	v_and_b32_e32 v119, 0xffff0000, v141
	v_lshlrev_b32_e32 v120, 16, v142
	v_and_b32_e32 v121, 0xffff0000, v142
	v_add_f32_e32 v106, 1.0, v106
	v_add_f32_e32 v107, 1.0, v107
	v_pk_add_f32 v[126:127], v[144:145], v[126:127]
	v_pk_add_f32 v[116:117], v[146:147], v[116:117]
	v_exp_f32_e32 v100, v100
	v_exp_f32_e32 v101, v101
	v_pk_mul_f32 v[96:97], v[96:97], v[112:113] op_sel_hi:[1,0]
	v_mul_f32_e32 v102, 0xbfb8aa3b, v102
	v_mul_f32_e32 v103, 0xbfb8aa3b, v103
; __device__ __forceinline__ unsigned cvt_pk_bf16(float lo, float hi) { const f32x2 v = {lo, hi}; return __builtin_bit_cast(unsigned, __builtin_convertvector(v, bfx2_t)); }
;     template <int NM> __device__ __forceinline__ void round(const AccT& acc, const Unit& u, int ai, int m0, int wr, int wc, int fr, int fq) const {
;     ...
;             const int rl = ai * 128 + wr * 64 + m * 16 + fr; const int row = u.pm * 256 + rl;
;             const size_t off = (size_t)row * DM + u.pn * 256 + wc * 32 + 8 * fq;
;             float r = 1.f; if (MODE == 1) r = rs[((u.pm >> 3) & 3) * 256 + rl];
;             float ss = 0.f;
; #pragma unroll
;             for (int bj = 0; bj < 2; ++bj) {
;                 f32x4 d0, d1;
;                 if (MODE == 0) { d0 = acc[ai][bj][m][0] * alpha; d1 = acc[ai][bj][m][1] * alpha; }
;                 else {
;                     const u32x4 p = pv[mm][bj];
;                     const f32x4 a0 = acc[ai][bj][m][0] * r, a1 = acc[ai][bj][m][1] * r;
;                     d0 = (f32x4){fsigmoid(a0[0]) * bflo(p.x), fsigmoid(a0[1]) * bfhi(p.x), fsigmoid(a0[2]) * bflo(p.y), fsigmoid(a0[3]) * bfhi(p.y)};
;                     d1 = (f32x4){fsigmoid(a1[0]) * bflo(p.z), fsigmoid(a1[1]) * bfhi(p.z), fsigmoid(a1[2]) * bflo(p.w), fsigmoid(a1[3]) * bfhi(p.w)};
;                 }
;                 const u32x4 H = hv[mm][bj]; const u32x2 L = lv[mm][bj];
;                 const f32x4 o0 = ((f32x4){bflo(H.x), bfhi(H.x), bflo(H.y), bfhi(H.y)} + lo_unpack4(L.x)) + d0;
;                 const f32x4 o1 = ((f32x4){bflo(H.z), bfhi(H.z), bflo(H.w), bfhi(H.w)} + lo_unpack4(L.y)) + d1;
;                 u32x4 w; w.x = cvt_pk_bf16(o0[0], o0[1]); w.y = cvt_pk_bf16(o0[2], o0[3]); w.z = cvt_pk_bf16(o1[0], o1[1]); w.w = cvt_pk_bf16(o1[2], o1[3]);
;                 u32x2 wl; wl.x = lo_pack4(o0[0] - bflo(w.x), o0[1] - bfhi(w.x), o0[2] - bflo(w.y), o0[3] - bfhi(w.y));
;                 wl.y = lo_pack4(o1[0] - bflo(w.z), o1[1] - bfhi(w.z), o1[2] - bflo(w.w), o1[3] - bfhi(w.w));
;                 *GP(u32x4, hout + off + bj * 128) = w; (void)wl;
;                 ss += (o0[0] * o0[0] + o0[1] * o0[1]) + (o0[2] * o0[2] + o0[3] * o0[3]) + (o1[0] * o1[0] + o1[1] * o1[1]) + (o1[2] * o1[2] + o1[3] * o1[3]);
;             }
;             ss += __shfl_xor(ss, 16); ss += __shfl_xor(ss, 32);
;             if (fq == 0) *GP(float, ssp + (size_t)(u.pn * 4 + wc) * TT + row) = ss;
	v_rcp_f32_e32 v106, v106
	v_rcp_f32_e32 v107, v107
	v_pk_fma_f32 v[110:111], v[110:111], v[118:119], v[126:127]
	v_pk_fma_f32 v[116:117], v[104:105], v[120:121], v[116:117]
	v_cvt_pk_bf16_f32 v104, v108, v109
	v_mul_f32_e32 v109, v109, v109
	v_exp_f32_e32 v102, v102
	v_exp_f32_e32 v103, v103
	v_mul_f32_e32 v96, 0xbfb8aa3b, v96
	v_mul_f32_e32 v97, 0xbfb8aa3b, v97
	v_fmac_f32_e32 v109, v108, v108
	v_mul_f32_e32 v108, v111, v111
	v_exp_f32_e32 v96, v96
	v_exp_f32_e32 v97, v97
	v_lshlrev_b32_e32 v118, 16, v139
	v_and_b32_e32 v119, 0xffff0000, v139
	v_fmac_f32_e32 v108, v110, v110
	v_pk_mul_f32 v[98:99], v[98:99], v[112:113] op_sel_hi:[1,0]
	v_lshlrev_b32_e32 v122, 16, v143
	v_and_b32_e32 v123, 0xffff0000, v143
	v_pk_add_f32 v[118:119], v[144:145], v[118:119]
	v_add_f32_e32 v108, v109, v108
	v_mul_f32_e32 v109, v117, v117
	v_add_f32_e32 v100, 1.0, v100
	v_add_f32_e32 v101, 1.0, v101
	v_mul_f32_e32 v98, 0xbfb8aa3b, v98
	v_mul_f32_e32 v99, 0xbfb8aa3b, v99
	v_pk_fma_f32 v[118:119], v[106:107], v[122:123], v[118:119]
	v_fmac_f32_e32 v109, v116, v116
	v_rcp_f32_e32 v100, v100
	v_rcp_f32_e32 v101, v101
	v_add_f32_e32 v102, 1.0, v102
	v_add_f32_e32 v103, 1.0, v103
	v_exp_f32_e32 v98, v98
	v_exp_f32_e32 v99, v99
	v_add_f32_e32 v108, v109, v108
	v_mul_f32_e32 v109, v119, v119
	v_rcp_f32_e32 v102, v102
	v_rcp_f32_e32 v103, v103
	v_add_f32_e32 v96, 1.0, v96
	v_add_f32_e32 v97, 1.0, v97
	v_cvt_pk_bf16_f32 v107, v118, v119
	v_fmac_f32_e32 v109, v118, v118
	v_rcp_f32_e32 v96, v96
	v_rcp_f32_e32 v97, v97
	v_lshlrev_b32_e32 v118, 16, v128
	v_and_b32_e32 v119, 0xffff0000, v128
	v_add_f32_e32 v122, v109, v108
	v_lshlrev_b32_e32 v108, 16, v132
	v_and_b32_e32 v109, 0xffff0000, v132
	v_lshlrev_b32_e32 v120, 16, v129
	v_and_b32_e32 v121, 0xffff0000, v129
	v_pk_add_f32 v[118:119], v[146:147], v[118:119]
	v_cvt_pk_bf16_f32 v105, v110, v111
	v_lshlrev_b32_e32 v110, 16, v133
	v_and_b32_e32 v111, 0xffff0000, v133
	v_add_f32_e32 v98, 1.0, v98
	v_add_f32_e32 v99, 1.0, v99
	v_pk_add_f32 v[120:121], v[144:145], v[120:121]
	v_pk_fma_f32 v[100:101], v[100:101], v[108:109], v[118:119]
	v_lshlrev_b32_e32 v108, 16, v130
	v_and_b32_e32 v109, 0xffff0000, v130
	v_lshlrev_b32_e32 v112, 16, v134
	v_and_b32_e32 v113, 0xffff0000, v134
	v_rcp_f32_e32 v98, v98
	v_rcp_f32_e32 v99, v99
	v_pk_fma_f32 v[102:103], v[102:103], v[110:111], v[120:121]
	v_pk_add_f32 v[108:109], v[146:147], v[108:109]
	v_lshlrev_b32_e32 v110, 16, v131
	v_pk_fma_f32 v[108:109], v[96:97], v[112:113], v[108:109]
	v_mul_f32_e32 v96, v101, v101
	v_mul_f32_e32 v97, v103, v103
	v_and_b32_e32 v111, 0xffff0000, v131
	v_fmac_f32_e32 v96, v100, v100
	v_fmac_f32_e32 v97, v102, v102
	v_cvt_pk_bf16_f32 v106, v116, v117
	v_lshlrev_b32_e32 v116, 16, v135
	v_and_b32_e32 v117, 0xffff0000, v135
	v_pk_add_f32 v[110:111], v[144:145], v[110:111]
	v_add_f32_e32 v96, v96, v97
	v_mul_f32_e32 v97, v109, v109
	v_pk_fma_f32 v[110:111], v[98:99], v[116:117], v[110:111]
	v_fmac_f32_e32 v97, v108, v108
	v_add_f32_e32 v96, v97, v96
	v_mul_f32_e32 v97, v111, v111
	v_fmac_f32_e32 v97, v110, v110
	v_add_f32_e32 v96, v97, v96
	v_add_u32_e32 v114, s46, v152
	v_add_f32_e32 v99, v122, v96
	v_ashrrev_i32_e32 v115, 31, v114
	v_mov_b32_e32 v116, v99
	s_nop 1
	v_permlane16_swap_b32_e32 v99, v116
	v_lshlrev_b64 v[114:115], 11, v[114:115]
	v_lshl_add_u64 v[114:115], s[14:15], 0, v[114:115]
	v_lshl_add_u64 v[114:115], s[16:17], 1, v[114:115]
	v_lshl_add_u64 v[96:97], v[114:115], 0, s[62:63]
	v_lshl_add_u64 v[112:113], v[96:97], 0, v[168:169]
	s_waitcnt lgkmcnt(0)
	v_add_f32_e32 v96, v99, v116
	v_mov_b32_e32 v97, v96
	s_nop 1
	v_permlane32_swap_b32_e32 v96, v97
	v_cvt_pk_bf16_f32 v98, v100, v101
	v_cvt_pk_bf16_f32 v99, v102, v103
	v_cvt_pk_bf16_f32 v100, v108, v109
	v_cvt_pk_bf16_f32 v101, v110, v111
	global_store_dwordx4 v[112:113], v[104:107], off
	global_store_dwordx4 v[112:113], v[98:101], off offset:256
	s_and_saveexec_b64 s[12:13], s[42:43]
	s_cbranch_execz .LBB0_581
	s_lshl_b32 s20, s25, 2
	s_or_b32 s20, s20, s71
	s_ashr_i32 s21, s20, 31
	s_lshl_b64 s[20:21], s[20:21], 18
	s_add_u32 s20, s65, s20
	s_addc_u32 s21, s70, s21
	s_ashr_i32 s47, s46, 31
	s_waitcnt lgkmcnt(0)
	v_add_f32_e32 v98, v96, v97
	v_lshl_add_u64 v[96:97], s[46:47], 0, v[148:149]
	v_lshl_add_u64 v[96:97], v[96:97], 2, s[20:21]
	global_store_dword v[96:97], v98, off offset:64
; __device__ __forceinline__ float bflo(unsigned w) { return __uint_as_float(w << 16); }
;     template <int NM> __device__ __forceinline__ void round(const AccT& acc, const Unit& u, int ai, int m0, int wr, int wc, int fr, int fq) const {
;     ...
;         for (int mm = 0; mm < NM; ++mm) {
;             const int rl = ai * 128 + wr * 64 + (m0 + mm) * 16 + fr;
;             const size_t off = (size_t)(u.pm * 256 + rl) * DM + u.pn * 256 + wc * 32 + 8 * fq;
; #pragma unroll
;             for (int bj = 0; bj < 2; ++bj) {
;                 hv[mm][bj] = *GP(const u32x4, hin + off + bj * 128); lv[mm][bj] = (u32x2){0u, 0u};
;                 if (MODE == 1) pv[mm][bj] = *GP(const u32x4, proj + off + bj * 128);
;             }
;         }
; #pragma unroll
;         for (int mm = 0; mm < NM; ++mm) {
;             const int m = m0 + mm;
;             const int rl = ai * 128 + wr * 64 + m * 16 + fr; const int row = u.pm * 256 + rl;
;             const size_t off = (size_t)row * DM + u.pn * 256 + wc * 32 + 8 * fq;
;             float r = 1.f; if (MODE == 1) r = rs[((u.pm >> 3) & 3) * 256 + rl];
;             float ss = 0.f;
; #pragma unroll
;             for (int bj = 0; bj < 2; ++bj) {
;                 f32x4 d0, d1;
;                 if (MODE == 0) { d0 = acc[ai][bj][m][0] * alpha; d1 = acc[ai][bj][m][1] * alpha; }
;                 else {
;                     const u32x4 p = pv[mm][bj];
;                     const f32x4 a0 = acc[ai][bj][m][0] * r, a1 = acc[ai][bj][m][1] * r;
;                     d0 = (f32x4){fsigmoid(a0[0]) * bflo(p.x), fsigmoid(a0[1]) * bfhi(p.x), fsigmoid(a0[2]) * bflo(p.y), fsigmoid(a0[3]) * bfhi(p.y)};
;                     d1 = (f32x4){fsigmoid(a1[0]) * bflo(p.z), fsigmoid(a1[1]) * bfhi(p.z), fsigmoid(a1[2]) * bflo(p.w), fsigmoid(a1[3]) * bfhi(p.w)};
;                 }
;                 const u32x4 H = hv[mm][bj]; const u32x2 L = lv[mm][bj];
;                 const f32x4 o0 = ((f32x4){bflo(H.x), bfhi(H.x), bflo(H.y), bfhi(H.y)} + lo_unpack4(L.x)) + d0;
;                 const f32x4 o1 = ((f32x4){bflo(H.z), bfhi(H.z), bflo(H.w), bfhi(H.w)} + lo_unpack4(L.y)) + d1;
;                 u32x4 w; w.x = cvt_pk_bf16(o0[0], o0[1]); w.y = cvt_pk_bf16(o0[2], o0[3]); w.z = cvt_pk_bf16(o1[0], o1[1]); w.w = cvt_pk_bf16(o1[2], o1[3]);
;                 u32x2 wl; wl.x = lo_pack4(o0[0] - bflo(w.x), o0[1] - bfhi(w.x), o0[2] - bflo(w.y), o0[3] - bfhi(w.y));
.LBB0_581:
	s_or_b64 exec, exec, s[12:13]
	v_or_b32_e32 v96, 32, v192
	s_waitcnt lgkmcnt(0)
	v_ashrrev_i32_e32 v97, 31, v96
	v_lshlrev_b64 v[96:97], 10, v[96:97]
	v_lshl_add_u64 v[96:97], v[96:97], 0, v[158:159]
	v_lshlrev_b64 v[96:97], 1, v[96:97]
	v_lshl_add_u64 v[98:99], s[66:67], 0, v[96:97]
	s_mov_b64 s[26:27], 0x1000
	v_lshl_add_u64 v[96:97], v[176:177], 0, s[26:27]
	global_load_dwordx4 v[120:123], v[98:99], off
	global_load_dwordx4 v[124:127], v[96:97], off
	global_load_dwordx4 v[112:115], v[98:99], off offset:256
	global_load_dwordx4 v[116:119], v[96:97], off offset:1024
	v_or_b32_e32 v96, 48, v192
	v_ashrrev_i32_e32 v97, 31, v96
	v_lshlrev_b64 v[96:97], 10, v[96:97]
	v_lshl_add_u64 v[96:97], v[96:97], 0, v[158:159]
	v_lshlrev_b64 v[96:97], 1, v[96:97]
	v_lshl_add_u64 v[98:99], s[66:67], 0, v[96:97]
	s_mov_b64 s[26:27], 0x1800
	v_lshl_add_u64 v[100:101], v[176:177], 0, s[26:27]
	global_load_dwordx4 v[104:107], v[98:99], off
	global_load_dwordx4 v[108:111], v[100:101], off
	s_nop 0
	global_load_dwordx4 v[96:99], v[98:99], off offset:256
	s_nop 0
	global_load_dwordx4 v[100:103], v[100:101], off offset:1024
	ds_read_b32 v128, v205 offset:128
	v_add_u32_e32 v130, s46, v154
	v_ashrrev_i32_e32 v131, 31, v130
	v_lshlrev_b64 v[130:131], 11, v[130:131]
	s_waitcnt lgkmcnt(0)
	v_pk_mul_f32 v[94:95], v[94:95], v[128:129] op_sel_hi:[1,0]
	v_pk_mul_f32 v[92:93], v[92:93], v[128:129] op_sel_hi:[1,0]
	v_pk_mul_f32 v[132:133], v[90:91], v[128:129] op_sel_hi:[1,0]
	v_pk_mul_f32 v[134:135], v[88:89], v[128:129] op_sel_hi:[1,0]
	v_mul_f32_e32 v88, 0xbfb8aa3b, v92
	v_mul_f32_e32 v89, 0xbfb8aa3b, v93
	v_mul_f32_e32 v92, 0xbfb8aa3b, v94
	v_mul_f32_e32 v93, 0xbfb8aa3b, v95
	v_exp_f32_e32 v88, v88
	v_exp_f32_e32 v89, v89
	v_exp_f32_e32 v92, v92
	v_exp_f32_e32 v93, v93
	v_add_f32_e32 v88, 1.0, v88
	v_add_f32_e32 v89, 1.0, v89
	v_rcp_f32_e32 v88, v88
	v_rcp_f32_e32 v89, v89
	v_add_f32_e32 v92, 1.0, v92
	v_add_f32_e32 v93, 1.0, v93
	v_rcp_f32_e32 v92, v92
	v_rcp_f32_e32 v93, v93
	v_pk_mul_f32 v[86:87], v[86:87], v[128:129] op_sel_hi:[1,0]
	v_pk_mul_f32 v[84:85], v[84:85], v[128:129] op_sel_hi:[1,0]
	v_mul_f32_e32 v86, 0xbfb8aa3b, v86
	v_mul_f32_e32 v84, 0xbfb8aa3b, v84
	v_mul_f32_e32 v85, 0xbfb8aa3b, v85
	v_mul_f32_e32 v87, 0xbfb8aa3b, v87
	v_pk_mul_f32 v[82:83], v[82:83], v[128:129] op_sel_hi:[1,0]
	v_pk_mul_f32 v[80:81], v[80:81], v[128:129] op_sel_hi:[1,0]
	v_exp_f32_e32 v84, v84
	v_exp_f32_e32 v85, v85
	v_exp_f32_e32 v86, v86
	v_exp_f32_e32 v87, v87
	v_mul_f32_e32 v80, 0xbfb8aa3b, v80
	v_mul_f32_e32 v81, 0xbfb8aa3b, v81
	v_mul_f32_e32 v82, 0xbfb8aa3b, v82
	v_mul_f32_e32 v83, 0xbfb8aa3b, v83
	v_exp_f32_e32 v80, v80
	v_exp_f32_e32 v81, v81
	v_exp_f32_e32 v82, v82
	v_exp_f32_e32 v83, v83
	v_add_f32_e32 v84, 1.0, v84
	v_add_f32_e32 v85, 1.0, v85
	v_add_f32_e32 v86, 1.0, v86
	v_add_f32_e32 v87, 1.0, v87
	v_rcp_f32_e32 v84, v84
	v_rcp_f32_e32 v85, v85
	v_rcp_f32_e32 v86, v86
	v_rcp_f32_e32 v87, v87
	v_add_f32_e32 v80, 1.0, v80
	v_add_f32_e32 v81, 1.0, v81
	v_add_f32_e32 v82, 1.0, v82
	v_add_f32_e32 v83, 1.0, v83
	v_rcp_f32_e32 v80, v80
	v_rcp_f32_e32 v81, v81
	v_rcp_f32_e32 v82, v82
	v_rcp_f32_e32 v83, v83
	s_waitcnt vmcnt(7)
	v_lshlrev_b32_e32 v136, 16, v120
	s_waitcnt vmcnt(6)
	v_lshlrev_b32_e32 v90, 16, v124
	v_and_b32_e32 v91, 0xffff0000, v124
	v_lshlrev_b32_e32 v94, 16, v125
	v_and_b32_e32 v95, 0xffff0000, v125
	v_mul_f32_e32 v124, 0xbfb8aa3b, v134
	v_mul_f32_e32 v125, 0xbfb8aa3b, v135
	v_lshlrev_b32_e32 v134, 16, v126
	v_and_b32_e32 v135, 0xffff0000, v126
	v_mul_f32_e32 v126, 0xbfb8aa3b, v132
	v_exp_f32_e32 v126, v126
	v_exp_f32_e32 v124, v124
	v_exp_f32_e32 v125, v125
	v_and_b32_e32 v137, 0xffff0000, v120
	v_add_f32_e32 v126, 1.0, v126
	v_rcp_f32_e32 v132, v126
	v_mul_f32_e32 v126, 0xbfb8aa3b, v133
	v_exp_f32_e32 v126, v126
	v_add_f32_e32 v124, 1.0, v124
	v_add_f32_e32 v125, 1.0, v125
	v_rcp_f32_e32 v124, v124
	v_add_f32_e32 v126, 1.0, v126
	v_rcp_f32_e32 v125, v125
	v_rcp_f32_e32 v133, v126
	v_pk_add_f32 v[136:137], v[146:147], v[136:137]
	v_lshlrev_b32_e32 v120, 16, v121
	v_and_b32_e32 v121, 0xffff0000, v121
	v_pk_fma_f32 v[136:137], v[88:89], v[90:91], v[136:137]
	v_lshlrev_b32_e32 v88, 16, v122
	v_and_b32_e32 v89, 0xffff0000, v122
	v_lshlrev_b32_e32 v90, 16, v123
	v_and_b32_e32 v91, 0xffff0000, v123
	v_lshl_add_u64 v[122:123], s[14:15], 0, v[130:131]
	v_lshlrev_b32_e32 v126, 16, v127
	v_and_b32_e32 v127, 0xffff0000, v127
	v_pk_add_f32 v[120:121], v[144:145], v[120:121]
	v_pk_add_f32 v[90:91], v[144:145], v[90:91]
	v_pk_add_f32 v[88:89], v[146:147], v[88:89]
	v_lshl_add_u64 v[122:123], s[16:17], 1, v[122:123]
	v_pk_fma_f32 v[92:93], v[92:93], v[94:95], v[120:121]
	v_pk_fma_f32 v[94:95], v[124:125], v[134:135], v[88:89]
	v_pk_fma_f32 v[120:121], v[132:133], v[126:127], v[90:91]
	v_lshl_add_u64 v[122:123], v[122:123], 0, s[62:63]
	v_cvt_pk_bf16_f32 v88, v136, v137
	v_cvt_pk_bf16_f32 v89, v92, v93
	v_cvt_pk_bf16_f32 v90, v94, v95
	v_cvt_pk_bf16_f32 v91, v120, v121
	v_lshl_add_u64 v[122:123], v[122:123], 0, v[168:169]
	global_store_dwordx4 v[122:123], v[88:91], off
	s_nop 1
	v_mul_f32_e32 v88, v137, v137
	v_mul_f32_e32 v89, v93, v93
	v_fmac_f32_e32 v88, v136, v136
	v_fmac_f32_e32 v89, v92, v92
	v_add_f32_e32 v88, v88, v89
	v_mul_f32_e32 v89, v95, v95
	v_fmac_f32_e32 v89, v94, v94
	v_add_f32_e32 v88, v89, v88
	v_mul_f32_e32 v89, v121, v121
	v_fmac_f32_e32 v89, v120, v120
	v_add_f32_e32 v120, v89, v88
	s_waitcnt vmcnt(5)
; __device__ __forceinline__ unsigned cvt_pk_bf16(float lo, float hi) { const f32x2 v = {lo, hi}; return __builtin_bit_cast(unsigned, __builtin_convertvector(v, bfx2_t)); }
;     template <int NM> __device__ __forceinline__ void round(const AccT& acc, const Unit& u, int ai, int m0, int wr, int wc, int fr, int fq) const {
;     ...
;             const int rl = ai * 128 + wr * 64 + m * 16 + fr; const int row = u.pm * 256 + rl;
;             const size_t off = (size_t)row * DM + u.pn * 256 + wc * 32 + 8 * fq;
;             float r = 1.f; if (MODE == 1) r = rs[((u.pm >> 3) & 3) * 256 + rl];
;             float ss = 0.f;
; #pragma unroll
;             for (int bj = 0; bj < 2; ++bj) {
;                 f32x4 d0, d1;
;                 if (MODE == 0) { d0 = acc[ai][bj][m][0] * alpha; d1 = acc[ai][bj][m][1] * alpha; }
;                 else {
;                     const u32x4 p = pv[mm][bj];
;                     const f32x4 a0 = acc[ai][bj][m][0] * r, a1 = acc[ai][bj][m][1] * r;
;                     d0 = (f32x4){fsigmoid(a0[0]) * bflo(p.x), fsigmoid(a0[1]) * bfhi(p.x), fsigmoid(a0[2]) * bflo(p.y), fsigmoid(a0[3]) * bfhi(p.y)};
;                     d1 = (f32x4){fsigmoid(a1[0]) * bflo(p.z), fsigmoid(a1[1]) * bfhi(p.z), fsigmoid(a1[2]) * bflo(p.w), fsigmoid(a1[3]) * bfhi(p.w)};
;                 }
;                 const u32x4 H = hv[mm][bj]; const u32x2 L = lv[mm][bj];
;                 const f32x4 o0 = ((f32x4){bflo(H.x), bfhi(H.x), bflo(H.y), bfhi(H.y)} + lo_unpack4(L.x)) + d0;
;                 const f32x4 o1 = ((f32x4){bflo(H.z), bfhi(H.z), bflo(H.w), bfhi(H.w)} + lo_unpack4(L.y)) + d1;
;                 u32x4 w; w.x = cvt_pk_bf16(o0[0], o0[1]); w.y = cvt_pk_bf16(o0[2], o0[3]); w.z = cvt_pk_bf16(o1[0], o1[1]); w.w = cvt_pk_bf16(o1[2], o1[3]);
;                 u32x2 wl; wl.x = lo_pack4(o0[0] - bflo(w.x), o0[1] - bfhi(w.x), o0[2] - bflo(w.y), o0[3] - bfhi(w.y));
;                 wl.y = lo_pack4(o1[0] - bflo(w.z), o1[1] - bfhi(w.z), o1[2] - bflo(w.w), o1[3] - bfhi(w.w));
;                 *GP(u32x4, hout + off + bj * 128) = w; (void)wl;
;                 ss += (o0[0] * o0[0] + o0[1] * o0[1]) + (o0[2] * o0[2] + o0[3] * o0[3]) + (o1[0] * o1[0] + o1[1] * o1[1]) + (o1[2] * o1[2] + o1[3] * o1[3]);
;             }
;             ss += __shfl_xor(ss, 16); ss += __shfl_xor(ss, 32);
;             if (fq == 0) *GP(float, ssp + (size_t)(u.pn * 4 + wc) * TT + row) = ss;
	v_lshlrev_b32_e32 v88, 16, v116
	v_and_b32_e32 v89, 0xffff0000, v116
	v_lshlrev_b32_e32 v90, 16, v117
	v_and_b32_e32 v91, 0xffff0000, v117
	v_lshlrev_b32_e32 v116, 16, v112
	v_and_b32_e32 v117, 0xffff0000, v112
	v_lshlrev_b32_e32 v112, 16, v113
	v_and_b32_e32 v113, 0xffff0000, v113
	v_pk_add_f32 v[112:113], v[144:145], v[112:113]
	v_pk_add_f32 v[116:117], v[146:147], v[116:117]
	v_pk_fma_f32 v[86:87], v[86:87], v[90:91], v[112:113]
	v_pk_fma_f32 v[84:85], v[84:85], v[88:89], v[116:117]
	v_lshlrev_b32_e32 v88, 16, v114
	v_and_b32_e32 v89, 0xffff0000, v114
	v_lshlrev_b32_e32 v90, 16, v115
	v_and_b32_e32 v91, 0xffff0000, v115
	v_lshlrev_b32_e32 v92, 16, v118
	v_and_b32_e32 v93, 0xffff0000, v118
	v_lshlrev_b32_e32 v94, 16, v119
	v_and_b32_e32 v95, 0xffff0000, v119
	v_pk_add_f32 v[90:91], v[144:145], v[90:91]
	v_pk_add_f32 v[88:89], v[146:147], v[88:89]
	v_pk_fma_f32 v[90:91], v[82:83], v[94:95], v[90:91]
	v_pk_fma_f32 v[88:89], v[80:81], v[92:93], v[88:89]
	v_cvt_pk_bf16_f32 v80, v84, v85
	v_cvt_pk_bf16_f32 v81, v86, v87
	v_cvt_pk_bf16_f32 v82, v88, v89
	v_cvt_pk_bf16_f32 v83, v90, v91
	global_store_dwordx4 v[122:123], v[80:83], off offset:256
	s_nop 1
	v_mul_f32_e32 v80, v85, v85
	v_mul_f32_e32 v81, v87, v87
	v_fmac_f32_e32 v80, v84, v84
	v_fmac_f32_e32 v81, v86, v86
	v_add_f32_e32 v80, v80, v81
	v_mul_f32_e32 v81, v89, v89
	v_fmac_f32_e32 v81, v88, v88
	v_add_f32_e32 v80, v81, v80
	v_mul_f32_e32 v81, v91, v91
	v_fmac_f32_e32 v81, v90, v90
	v_add_f32_e32 v80, v81, v80
	v_add_f32_e32 v80, v120, v80
	v_mov_b32_e32 v81, v80
	s_nop 1
	v_permlane16_swap_b32_e32 v80, v81
	s_waitcnt lgkmcnt(0)
	v_add_f32_e32 v80, v80, v81
	v_mov_b32_e32 v81, v80
	s_nop 1
	v_permlane32_swap_b32_e32 v80, v81
	s_and_saveexec_b64 s[12:13], s[42:43]
	s_cbranch_execz .LBB0_583
	s_lshl_b32 s20, s25, 2
	s_or_b32 s20, s20, s71
	s_ashr_i32 s21, s20, 31
	s_lshl_b64 s[20:21], s[20:21], 18
	s_add_u32 s20, s65, s20
	s_addc_u32 s21, s70, s21
	s_ashr_i32 s47, s46, 31
	s_waitcnt lgkmcnt(0)
	v_add_f32_e32 v82, v80, v81
	v_lshl_add_u64 v[80:81], s[46:47], 0, v[148:149]
	v_lshl_add_u64 v[80:81], v[80:81], 2, s[20:21]
	global_store_dword v[80:81], v82, off offset:128
.LBB0_583:
	s_or_b64 exec, exec, s[12:13]
	ds_read_b32 v80, v205 offset:192
	s_waitcnt vmcnt(5)
	v_lshlrev_b32_e32 v92, 16, v104
	v_and_b32_e32 v93, 0xffff0000, v104
	s_waitcnt vmcnt(4)
	v_lshlrev_b32_e32 v84, 16, v108
	v_and_b32_e32 v85, 0xffff0000, v108
	s_waitcnt lgkmcnt(0)
	v_pk_mul_f32 v[76:77], v[76:77], v[80:81] op_sel_hi:[1,0]
	v_pk_mul_f32 v[78:79], v[78:79], v[80:81] op_sel_hi:[1,0]
	v_mul_f32_e32 v76, 0xbfb8aa3b, v76
	v_mul_f32_e32 v77, 0xbfb8aa3b, v77
	v_exp_f32_e32 v76, v76
	v_exp_f32_e32 v77, v77
	v_pk_mul_f32 v[72:73], v[72:73], v[80:81] op_sel_hi:[1,0]
	v_mul_f32_e32 v78, 0xbfb8aa3b, v78
	v_mul_f32_e32 v79, 0xbfb8aa3b, v79
	v_mul_f32_e32 v72, 0xbfb8aa3b, v72
	v_mul_f32_e32 v73, 0xbfb8aa3b, v73
	v_exp_f32_e32 v78, v78
	v_exp_f32_e32 v79, v79
	v_exp_f32_e32 v72, v72
	v_exp_f32_e32 v73, v73
	v_pk_mul_f32 v[74:75], v[74:75], v[80:81] op_sel_hi:[1,0]
	v_add_f32_e32 v76, 1.0, v76
	v_add_f32_e32 v77, 1.0, v77
	v_rcp_f32_e32 v76, v76
	v_rcp_f32_e32 v77, v77
	v_mul_f32_e32 v74, 0xbfb8aa3b, v74
	v_mul_f32_e32 v75, 0xbfb8aa3b, v75
	v_add_f32_e32 v78, 1.0, v78
	v_add_f32_e32 v79, 1.0, v79
	v_add_f32_e32 v72, 1.0, v72
	v_add_f32_e32 v73, 1.0, v73
	v_exp_f32_e32 v74, v74
	v_exp_f32_e32 v75, v75
	v_rcp_f32_e32 v78, v78
	v_rcp_f32_e32 v79, v79
	v_rcp_f32_e32 v72, v72
	v_rcp_f32_e32 v73, v73
	v_pk_add_f32 v[92:93], v[146:147], v[92:93]
	v_pk_mul_f32 v[68:69], v[68:69], v[80:81] op_sel_hi:[1,0]
	v_lshlrev_b32_e32 v94, 16, v105
	v_and_b32_e32 v95, 0xffff0000, v105
	v_pk_fma_f32 v[76:77], v[76:77], v[84:85], v[92:93]
	v_lshlrev_b32_e32 v84, 16, v106
	v_and_b32_e32 v85, 0xffff0000, v106
	v_pk_mul_f32 v[70:71], v[70:71], v[80:81] op_sel_hi:[1,0]
	v_mul_f32_e32 v68, 0xbfb8aa3b, v68
	v_mul_f32_e32 v69, 0xbfb8aa3b, v69
	v_lshlrev_b32_e32 v86, 16, v109
	v_and_b32_e32 v87, 0xffff0000, v109
	v_lshlrev_b32_e32 v88, 16, v110
	v_and_b32_e32 v89, 0xffff0000, v110
	v_add_f32_e32 v74, 1.0, v74
	v_add_f32_e32 v75, 1.0, v75
	v_pk_add_f32 v[94:95], v[144:145], v[94:95]
	v_pk_add_f32 v[84:85], v[146:147], v[84:85]
	v_exp_f32_e32 v68, v68
	v_exp_f32_e32 v69, v69
	v_pk_mul_f32 v[64:65], v[64:65], v[80:81] op_sel_hi:[1,0]
	v_mul_f32_e32 v70, 0xbfb8aa3b, v70
	v_mul_f32_e32 v71, 0xbfb8aa3b, v71
	v_rcp_f32_e32 v74, v74
	v_rcp_f32_e32 v75, v75
	v_pk_fma_f32 v[78:79], v[78:79], v[86:87], v[94:95]
	v_pk_fma_f32 v[84:85], v[72:73], v[88:89], v[84:85]
	v_cvt_pk_bf16_f32 v72, v76, v77
	v_mul_f32_e32 v77, v77, v77
	v_exp_f32_e32 v70, v70
	v_exp_f32_e32 v71, v71
	v_mul_f32_e32 v64, 0xbfb8aa3b, v64
	v_mul_f32_e32 v65, 0xbfb8aa3b, v65
	v_fmac_f32_e32 v77, v76, v76
	v_mul_f32_e32 v76, v79, v79
	v_exp_f32_e32 v64, v64
	v_exp_f32_e32 v65, v65
	v_lshlrev_b32_e32 v86, 16, v107
	v_and_b32_e32 v87, 0xffff0000, v107
	v_fmac_f32_e32 v76, v78, v78
	v_pk_mul_f32 v[66:67], v[66:67], v[80:81] op_sel_hi:[1,0]
	v_lshlrev_b32_e32 v90, 16, v111
	v_and_b32_e32 v91, 0xffff0000, v111
	v_pk_add_f32 v[86:87], v[144:145], v[86:87]
	v_add_f32_e32 v76, v77, v76
	v_mul_f32_e32 v77, v85, v85
	v_add_f32_e32 v68, 1.0, v68
	v_add_f32_e32 v69, 1.0, v69
	v_mul_f32_e32 v66, 0xbfb8aa3b, v66
	v_mul_f32_e32 v67, 0xbfb8aa3b, v67
	v_pk_fma_f32 v[86:87], v[74:75], v[90:91], v[86:87]
	v_fmac_f32_e32 v77, v84, v84
	v_rcp_f32_e32 v68, v68
	v_rcp_f32_e32 v69, v69
	v_add_f32_e32 v70, 1.0, v70
	v_add_f32_e32 v71, 1.0, v71
	v_exp_f32_e32 v66, v66
	v_exp_f32_e32 v67, v67
	v_add_f32_e32 v76, v77, v76
	v_mul_f32_e32 v77, v87, v87
	v_rcp_f32_e32 v70, v70
	v_rcp_f32_e32 v71, v71
	v_add_f32_e32 v64, 1.0, v64
	v_add_f32_e32 v65, 1.0, v65
	v_cvt_pk_bf16_f32 v75, v86, v87
	v_fmac_f32_e32 v77, v86, v86
	v_rcp_f32_e32 v64, v64
	v_rcp_f32_e32 v65, v65
	s_waitcnt vmcnt(3)
; __device__ __forceinline__ float bflo(unsigned w) { return __uint_as_float(w << 16); }
;     template <int NM> __device__ __forceinline__ void round(const AccT& acc, const Unit& u, int ai, int m0, int wr, int wc, int fr, int fq) const {
;     ...
;         for (int mm = 0; mm < NM; ++mm) {
;             const int rl = ai * 128 + wr * 64 + (m0 + mm) * 16 + fr;
;             const size_t off = (size_t)(u.pm * 256 + rl) * DM + u.pn * 256 + wc * 32 + 8 * fq;
; #pragma unroll
;             for (int bj = 0; bj < 2; ++bj) {
;                 hv[mm][bj] = *GP(const u32x4, hin + off + bj * 128); lv[mm][bj] = (u32x2){0u, 0u};
;                 if (MODE == 1) pv[mm][bj] = *GP(const u32x4, proj + off + bj * 128);
;             }
;         }
; #pragma unroll
;         for (int mm = 0; mm < NM; ++mm) {
;             const int m = m0 + mm;
;             const int rl = ai * 128 + wr * 64 + m * 16 + fr; const int row = u.pm * 256 + rl;
;             const size_t off = (size_t)row * DM + u.pn * 256 + wc * 32 + 8 * fq;
;             float r = 1.f; if (MODE == 1) r = rs[((u.pm >> 3) & 3) * 256 + rl];
;             float ss = 0.f;
; #pragma unroll
;             for (int bj = 0; bj < 2; ++bj) {
;                 f32x4 d0, d1;
;                 if (MODE == 0) { d0 = acc[ai][bj][m][0] * alpha; d1 = acc[ai][bj][m][1] * alpha; }
;                 else {
;                     const u32x4 p = pv[mm][bj];
;                     const f32x4 a0 = acc[ai][bj][m][0] * r, a1 = acc[ai][bj][m][1] * r;
;                     d0 = (f32x4){fsigmoid(a0[0]) * bflo(p.x), fsigmoid(a0[1]) * bfhi(p.x), fsigmoid(a0[2]) * bflo(p.y), fsigmoid(a0[3]) * bfhi(p.y)};
;                     d1 = (f32x4){fsigmoid(a1[0]) * bflo(p.z), fsigmoid(a1[1]) * bfhi(p.z), fsigmoid(a1[2]) * bflo(p.w), fsigmoid(a1[3]) * bfhi(p.w)};
;                 }
;                 const u32x4 H = hv[mm][bj]; const u32x2 L = lv[mm][bj];
;                 const f32x4 o0 = ((f32x4){bflo(H.x), bfhi(H.x), bflo(H.y), bfhi(H.y)} + lo_unpack4(L.x)) + d0;
;                 const f32x4 o1 = ((f32x4){bflo(H.z), bfhi(H.z), bflo(H.w), bfhi(H.w)} + lo_unpack4(L.y)) + d1;
;                 u32x4 w; w.x = cvt_pk_bf16(o0[0], o0[1]); w.y = cvt_pk_bf16(o0[2], o0[3]); w.z = cvt_pk_bf16(o1[0], o1[1]); w.w = cvt_pk_bf16(o1[2], o1[3]);
;                 u32x2 wl; wl.x = lo_pack4(o0[0] - bflo(w.x), o0[1] - bfhi(w.x), o0[2] - bflo(w.y), o0[3] - bfhi(w.y));
	v_lshlrev_b32_e32 v86, 16, v96
	v_and_b32_e32 v87, 0xffff0000, v96
	v_add_f32_e32 v90, v77, v76
	s_waitcnt vmcnt(2)
	v_lshlrev_b32_e32 v76, 16, v100
	v_and_b32_e32 v77, 0xffff0000, v100
	v_lshlrev_b32_e32 v88, 16, v97
	v_and_b32_e32 v89, 0xffff0000, v97
	v_pk_add_f32 v[86:87], v[146:147], v[86:87]
	v_cvt_pk_bf16_f32 v73, v78, v79
	v_lshlrev_b32_e32 v78, 16, v101
	v_and_b32_e32 v79, 0xffff0000, v101
	v_add_f32_e32 v66, 1.0, v66
	v_add_f32_e32 v67, 1.0, v67
	v_pk_add_f32 v[88:89], v[144:145], v[88:89]
	v_pk_fma_f32 v[68:69], v[68:69], v[76:77], v[86:87]
	v_lshlrev_b32_e32 v76, 16, v98
	v_and_b32_e32 v77, 0xffff0000, v98
	v_lshlrev_b32_e32 v80, 16, v102
	v_and_b32_e32 v81, 0xffff0000, v102
	v_rcp_f32_e32 v66, v66
	v_rcp_f32_e32 v67, v67
	v_pk_fma_f32 v[70:71], v[70:71], v[78:79], v[88:89]
	v_pk_add_f32 v[76:77], v[146:147], v[76:77]
	v_lshlrev_b32_e32 v78, 16, v99
	v_pk_fma_f32 v[76:77], v[64:65], v[80:81], v[76:77]
	v_mul_f32_e32 v64, v69, v69
	v_mul_f32_e32 v65, v71, v71
	v_and_b32_e32 v79, 0xffff0000, v99
	v_fmac_f32_e32 v64, v68, v68
	v_fmac_f32_e32 v65, v70, v70
	v_cvt_pk_bf16_f32 v74, v84, v85
	v_lshlrev_b32_e32 v84, 16, v103
	v_and_b32_e32 v85, 0xffff0000, v103
	v_pk_add_f32 v[78:79], v[144:145], v[78:79]
	v_add_f32_e32 v64, v64, v65
	v_mul_f32_e32 v65, v77, v77
	v_pk_fma_f32 v[78:79], v[66:67], v[84:85], v[78:79]
	v_fmac_f32_e32 v65, v76, v76
	v_add_f32_e32 v64, v65, v64
	v_mul_f32_e32 v65, v79, v79
	v_fmac_f32_e32 v65, v78, v78
	v_add_f32_e32 v64, v65, v64
	v_add_u32_e32 v82, s46, v156
	v_add_f32_e32 v67, v90, v64
	v_ashrrev_i32_e32 v83, 31, v82
	v_mov_b32_e32 v84, v67
	s_nop 1
	v_permlane16_swap_b32_e32 v67, v84
	v_lshlrev_b64 v[82:83], 11, v[82:83]
	v_lshl_add_u64 v[82:83], s[14:15], 0, v[82:83]
	v_lshl_add_u64 v[82:83], s[16:17], 1, v[82:83]
	v_lshl_add_u64 v[64:65], v[82:83], 0, s[62:63]
	v_lshl_add_u64 v[80:81], v[64:65], 0, v[168:169]
	s_waitcnt lgkmcnt(0)
	v_add_f32_e32 v64, v67, v84
	v_mov_b32_e32 v65, v64
	s_nop 1
	v_permlane32_swap_b32_e32 v64, v65
	v_cvt_pk_bf16_f32 v66, v68, v69
	v_cvt_pk_bf16_f32 v67, v70, v71
	v_cvt_pk_bf16_f32 v68, v76, v77
	v_cvt_pk_bf16_f32 v69, v78, v79
	global_store_dwordx4 v[80:81], v[72:75], off
	global_store_dwordx4 v[80:81], v[66:69], off offset:256
	s_and_saveexec_b64 s[12:13], s[42:43]
	s_cbranch_execz .LBB0_585
	s_lshl_b32 s20, s25, 2
	s_or_b32 s20, s20, s71
	s_ashr_i32 s21, s20, 31
	s_lshl_b64 s[20:21], s[20:21], 18
	s_add_u32 s20, s65, s20
	s_addc_u32 s21, s70, s21
	s_ashr_i32 s47, s46, 31
	s_waitcnt lgkmcnt(0)
	v_add_f32_e32 v66, v64, v65
	v_lshl_add_u64 v[64:65], s[46:47], 0, v[148:149]
	v_lshl_add_u64 v[64:65], v[64:65], 2, s[20:21]
	global_store_dword v[64:65], v66, off offset:192
.LBB0_585:
	s_or_b64 exec, exec, s[12:13]
	v_add_u32_e32 v88, s46, v198
	v_ashrrev_i32_e32 v89, 31, v88
	s_waitcnt lgkmcnt(0)
	v_lshlrev_b64 v[64:65], 10, v[88:89]
	v_lshl_add_u64 v[64:65], v[64:65], 0, v[158:159]
	v_lshlrev_b64 v[64:65], 1, v[64:65]
	v_lshl_add_u64 v[66:67], s[66:67], 0, v[64:65]
	s_mov_b64 s[26:27], 0x2000
	v_lshl_add_u64 v[64:65], v[176:177], 0, s[26:27]
	global_load_dwordx4 v[92:95], v[66:67], off
	global_load_dwordx4 v[98:101], v[64:65], off
	global_load_dwordx4 v[80:83], v[66:67], off offset:256
	global_load_dwordx4 v[84:87], v[64:65], off offset:1024
	v_or_b32_e32 v64, 16, v88
	v_ashrrev_i32_e32 v65, 31, v64
	v_lshlrev_b64 v[64:65], 10, v[64:65]
	v_lshl_add_u64 v[64:65], v[64:65], 0, v[158:159]
	v_lshlrev_b64 v[64:65], 1, v[64:65]
	v_lshl_add_u64 v[66:67], s[66:67], 0, v[64:65]
	s_mov_b64 s[26:27], 0x2800
	v_lshl_add_u64 v[68:69], v[176:177], 0, s[26:27]
	global_load_dwordx4 v[72:75], v[66:67], off
	global_load_dwordx4 v[76:79], v[68:69], off
	s_nop 0
	global_load_dwordx4 v[64:67], v[66:67], off offset:256
	s_nop 0
	global_load_dwordx4 v[68:71], v[68:69], off offset:1024
	ds_read_b32 v90, v205 offset:512
	v_lshlrev_b64 v[96:97], 11, v[88:89]
	v_lshl_add_u64 v[96:97], s[14:15], 0, v[96:97]
	v_lshl_add_u64 v[96:97], s[16:17], 1, v[96:97]
	v_lshl_add_u64 v[96:97], v[96:97], 0, s[62:63]
	s_waitcnt lgkmcnt(0)
	v_pk_mul_f32 v[62:63], v[62:63], v[90:91] op_sel_hi:[1,0]
	v_pk_mul_f32 v[60:61], v[60:61], v[90:91] op_sel_hi:[1,0]
	v_mul_f32_e32 v62, 0xbfb8aa3b, v62
	v_mul_f32_e32 v60, 0xbfb8aa3b, v60
	v_mul_f32_e32 v61, 0xbfb8aa3b, v61
	v_mul_f32_e32 v63, 0xbfb8aa3b, v63
	v_pk_mul_f32 v[58:59], v[58:59], v[90:91] op_sel_hi:[1,0]
	v_pk_mul_f32 v[56:57], v[56:57], v[90:91] op_sel_hi:[1,0]
	v_exp_f32_e32 v60, v60
	v_exp_f32_e32 v61, v61
	v_exp_f32_e32 v62, v62
	v_exp_f32_e32 v63, v63
	v_mul_f32_e32 v56, 0xbfb8aa3b, v56
	v_mul_f32_e32 v57, 0xbfb8aa3b, v57
	v_mul_f32_e32 v58, 0xbfb8aa3b, v58
	v_mul_f32_e32 v59, 0xbfb8aa3b, v59
	v_exp_f32_e32 v56, v56
	v_exp_f32_e32 v57, v57
	v_exp_f32_e32 v58, v58
	v_exp_f32_e32 v59, v59
	v_add_f32_e32 v60, 1.0, v60
	v_add_f32_e32 v61, 1.0, v61
	v_add_f32_e32 v62, 1.0, v62
	v_add_f32_e32 v63, 1.0, v63
	v_rcp_f32_e32 v60, v60
	v_rcp_f32_e32 v61, v61
	v_rcp_f32_e32 v62, v62
	v_rcp_f32_e32 v63, v63
	v_add_f32_e32 v56, 1.0, v56
	v_add_f32_e32 v57, 1.0, v57
	v_add_f32_e32 v58, 1.0, v58
	v_add_f32_e32 v59, 1.0, v59
	v_rcp_f32_e32 v56, v56
	v_rcp_f32_e32 v57, v57
	v_rcp_f32_e32 v58, v58
	v_rcp_f32_e32 v59, v59
	v_lshl_add_u64 v[96:97], v[96:97], 0, v[168:169]
	s_waitcnt vmcnt(7)
	v_lshlrev_b32_e32 v106, 16, v92
	v_and_b32_e32 v107, 0xffff0000, v92
	v_lshlrev_b32_e32 v92, 16, v93
	v_and_b32_e32 v93, 0xffff0000, v93
	s_waitcnt vmcnt(6)
; __device__ __forceinline__ unsigned cvt_pk_bf16(float lo, float hi) { const f32x2 v = {lo, hi}; return __builtin_bit_cast(unsigned, __builtin_convertvector(v, bfx2_t)); }
;     template <int NM> __device__ __forceinline__ void round(const AccT& acc, const Unit& u, int ai, int m0, int wr, int wc, int fr, int fq) const {
;     ...
;             const int rl = ai * 128 + wr * 64 + m * 16 + fr; const int row = u.pm * 256 + rl;
;             const size_t off = (size_t)row * DM + u.pn * 256 + wc * 32 + 8 * fq;
;             float r = 1.f; if (MODE == 1) r = rs[((u.pm >> 3) & 3) * 256 + rl];
;             float ss = 0.f;
; #pragma unroll
;             for (int bj = 0; bj < 2; ++bj) {
;                 f32x4 d0, d1;
;                 if (MODE == 0) { d0 = acc[ai][bj][m][0] * alpha; d1 = acc[ai][bj][m][1] * alpha; }
;                 else {
;                     const u32x4 p = pv[mm][bj];
;                     const f32x4 a0 = acc[ai][bj][m][0] * r, a1 = acc[ai][bj][m][1] * r;
;                     d0 = (f32x4){fsigmoid(a0[0]) * bflo(p.x), fsigmoid(a0[1]) * bfhi(p.x), fsigmoid(a0[2]) * bflo(p.y), fsigmoid(a0[3]) * bfhi(p.y)};
;                     d1 = (f32x4){fsigmoid(a1[0]) * bflo(p.z), fsigmoid(a1[1]) * bfhi(p.z), fsigmoid(a1[2]) * bflo(p.w), fsigmoid(a1[3]) * bfhi(p.w)};
;                 }
;                 const u32x4 H = hv[mm][bj]; const u32x2 L = lv[mm][bj];
;                 const f32x4 o0 = ((f32x4){bflo(H.x), bfhi(H.x), bflo(H.y), bfhi(H.y)} + lo_unpack4(L.x)) + d0;
;                 const f32x4 o1 = ((f32x4){bflo(H.z), bfhi(H.z), bflo(H.w), bfhi(H.w)} + lo_unpack4(L.y)) + d1;
;                 u32x4 w; w.x = cvt_pk_bf16(o0[0], o0[1]); w.y = cvt_pk_bf16(o0[2], o0[3]); w.z = cvt_pk_bf16(o1[0], o1[1]); w.w = cvt_pk_bf16(o1[2], o1[3]);
;                 u32x2 wl; wl.x = lo_pack4(o0[0] - bflo(w.x), o0[1] - bfhi(w.x), o0[2] - bflo(w.y), o0[3] - bfhi(w.y));
;                 wl.y = lo_pack4(o1[0] - bflo(w.z), o1[1] - bfhi(w.z), o1[2] - bflo(w.w), o1[3] - bfhi(w.w));
;                 *GP(u32x4, hout + off + bj * 128) = w; (void)wl;
;                 ss += (o0[0] * o0[0] + o0[1] * o0[1]) + (o0[2] * o0[2] + o0[3] * o0[3]) + (o1[0] * o1[0] + o1[1] * o1[1]) + (o1[2] * o1[2] + o1[3] * o1[3]);
;             }
;             ss += __shfl_xor(ss, 16); ss += __shfl_xor(ss, 32);
;             if (fq == 0) *GP(float, ssp + (size_t)(u.pn * 4 + wc) * TT + row) = ss;
	v_lshlrev_b32_e32 v102, 16, v98
	v_and_b32_e32 v103, 0xffff0000, v98
	v_lshlrev_b32_e32 v98, 16, v99
	v_and_b32_e32 v99, 0xffff0000, v99
	v_pk_add_f32 v[108:109], v[144:145], v[92:93]
	v_pk_add_f32 v[92:93], v[146:147], v[106:107]
	v_lshlrev_b32_e32 v104, 16, v100
	v_pk_fma_f32 v[92:93], v[60:61], v[102:103], v[92:93]
	v_pk_fma_f32 v[60:61], v[62:63], v[98:99], v[108:109]
	v_lshlrev_b32_e32 v62, 16, v94
	v_and_b32_e32 v63, 0xffff0000, v94
	v_lshlrev_b32_e32 v94, 16, v95
	v_and_b32_e32 v95, 0xffff0000, v95
	v_and_b32_e32 v105, 0xffff0000, v100
	v_lshlrev_b32_e32 v100, 16, v101
	v_and_b32_e32 v101, 0xffff0000, v101
	v_pk_add_f32 v[98:99], v[144:145], v[94:95]
	v_pk_add_f32 v[62:63], v[146:147], v[62:63]
	s_nop 0
	v_pk_fma_f32 v[94:95], v[56:57], v[104:105], v[62:63]
	v_pk_fma_f32 v[62:63], v[58:59], v[100:101], v[98:99]
	v_cvt_pk_bf16_f32 v56, v92, v93
	v_cvt_pk_bf16_f32 v57, v60, v61
	v_cvt_pk_bf16_f32 v58, v94, v95
	v_cvt_pk_bf16_f32 v59, v62, v63
	global_store_dwordx4 v[96:97], v[56:59], off
	s_nop 1
	v_mul_f32_e32 v56, v93, v93
	v_mul_f32_e32 v57, v61, v61
	v_fmac_f32_e32 v56, v92, v92
	v_fmac_f32_e32 v57, v60, v60
	v_add_f32_e32 v56, v56, v57
	v_mul_f32_e32 v57, v95, v95
	v_fmac_f32_e32 v57, v94, v94
	v_add_f32_e32 v56, v57, v56
	v_mul_f32_e32 v57, v63, v63
	v_fmac_f32_e32 v57, v62, v62
	v_add_f32_e32 v91, v57, v56
	v_pk_mul_f32 v[54:55], v[54:55], v[90:91] op_sel_hi:[1,0]
	v_pk_mul_f32 v[52:53], v[52:53], v[90:91] op_sel_hi:[1,0]
	v_mul_f32_e32 v54, 0xbfb8aa3b, v54
	v_mul_f32_e32 v52, 0xbfb8aa3b, v52
	v_mul_f32_e32 v53, 0xbfb8aa3b, v53
	v_mul_f32_e32 v55, 0xbfb8aa3b, v55
	v_pk_mul_f32 v[50:51], v[50:51], v[90:91] op_sel_hi:[1,0]
	v_pk_mul_f32 v[48:49], v[48:49], v[90:91] op_sel_hi:[1,0]
	v_exp_f32_e32 v52, v52
	v_exp_f32_e32 v53, v53
	v_exp_f32_e32 v54, v54
	v_exp_f32_e32 v55, v55
	v_mul_f32_e32 v48, 0xbfb8aa3b, v48
	v_mul_f32_e32 v49, 0xbfb8aa3b, v49
	v_mul_f32_e32 v50, 0xbfb8aa3b, v50
	v_mul_f32_e32 v51, 0xbfb8aa3b, v51
	v_exp_f32_e32 v48, v48
	v_exp_f32_e32 v49, v49
	v_exp_f32_e32 v50, v50
	v_exp_f32_e32 v51, v51
	v_add_f32_e32 v52, 1.0, v52
	v_add_f32_e32 v53, 1.0, v53
	v_add_f32_e32 v54, 1.0, v54
	v_add_f32_e32 v55, 1.0, v55
	v_rcp_f32_e32 v52, v52
	v_rcp_f32_e32 v53, v53
	v_rcp_f32_e32 v54, v54
	v_rcp_f32_e32 v55, v55
	v_add_f32_e32 v48, 1.0, v48
	v_add_f32_e32 v49, 1.0, v49
	v_add_f32_e32 v50, 1.0, v50
	v_add_f32_e32 v51, 1.0, v51
	s_waitcnt vmcnt(5)
	v_lshlrev_b32_e32 v56, 16, v84
	v_and_b32_e32 v57, 0xffff0000, v84
	v_lshlrev_b32_e32 v58, 16, v85
	v_and_b32_e32 v59, 0xffff0000, v85
	v_rcp_f32_e32 v48, v48
	v_rcp_f32_e32 v49, v49
	v_rcp_f32_e32 v50, v50
	v_rcp_f32_e32 v51, v51
	v_lshlrev_b32_e32 v84, 16, v80
	v_and_b32_e32 v85, 0xffff0000, v80
	v_lshlrev_b32_e32 v80, 16, v81
	v_and_b32_e32 v81, 0xffff0000, v81
	v_pk_add_f32 v[80:81], v[144:145], v[80:81]
	v_pk_add_f32 v[84:85], v[146:147], v[84:85]
	v_pk_fma_f32 v[54:55], v[54:55], v[58:59], v[80:81]
	v_pk_fma_f32 v[52:53], v[52:53], v[56:57], v[84:85]
	v_lshlrev_b32_e32 v56, 16, v82
	v_and_b32_e32 v57, 0xffff0000, v82
	v_lshlrev_b32_e32 v58, 16, v83
	v_and_b32_e32 v59, 0xffff0000, v83
	v_lshlrev_b32_e32 v60, 16, v86
	v_and_b32_e32 v61, 0xffff0000, v86
	v_lshlrev_b32_e32 v62, 16, v87
	v_and_b32_e32 v63, 0xffff0000, v87
	v_pk_add_f32 v[58:59], v[144:145], v[58:59]
	v_pk_add_f32 v[56:57], v[146:147], v[56:57]
	v_pk_fma_f32 v[58:59], v[50:51], v[62:63], v[58:59]
	v_pk_fma_f32 v[56:57], v[48:49], v[60:61], v[56:57]
	v_cvt_pk_bf16_f32 v48, v52, v53
	v_cvt_pk_bf16_f32 v49, v54, v55
	v_cvt_pk_bf16_f32 v50, v56, v57
	v_cvt_pk_bf16_f32 v51, v58, v59
	global_store_dwordx4 v[96:97], v[48:51], off offset:256
	s_nop 1
	v_mul_f32_e32 v48, v53, v53
	v_mul_f32_e32 v49, v55, v55
	v_fmac_f32_e32 v48, v52, v52
	v_fmac_f32_e32 v49, v54, v54
	v_add_f32_e32 v48, v48, v49
	v_mul_f32_e32 v49, v57, v57
	v_fmac_f32_e32 v49, v56, v56
	v_add_f32_e32 v48, v49, v48
	v_mul_f32_e32 v49, v59, v59
	v_fmac_f32_e32 v49, v58, v58
	v_add_f32_e32 v48, v49, v48
	v_add_f32_e32 v48, v91, v48
	v_mov_b32_e32 v49, v48
	s_nop 1
	v_permlane16_swap_b32_e32 v48, v49
	s_waitcnt lgkmcnt(0)
	v_add_f32_e32 v48, v48, v49
	v_mov_b32_e32 v49, v48
	s_nop 1
	v_permlane32_swap_b32_e32 v48, v49
	s_and_saveexec_b64 s[12:13], s[42:43]
	s_cbranch_execz .LBB0_587
	s_lshl_b32 s20, s25, 2
	s_or_b32 s20, s20, s71
	s_ashr_i32 s21, s20, 31
	s_lshl_b64 s[20:21], s[20:21], 18
	s_add_u32 s20, s65, s20
	s_addc_u32 s21, s70, s21
	s_waitcnt lgkmcnt(0)
	v_add_f32_e32 v50, v48, v49
	v_lshl_add_u64 v[48:49], v[88:89], 2, s[20:21]
	global_store_dword v[48:49], v50, off
; __device__ __forceinline__ unsigned cvt_pk_bf16(float lo, float hi) { const f32x2 v = {lo, hi}; return __builtin_bit_cast(unsigned, __builtin_convertvector(v, bfx2_t)); }
;     template <int NM> __device__ __forceinline__ void round(const AccT& acc, const Unit& u, int ai, int m0, int wr, int wc, int fr, int fq) const {
;     ...
;             const int rl = ai * 128 + wr * 64 + m * 16 + fr; const int row = u.pm * 256 + rl;
;             const size_t off = (size_t)row * DM + u.pn * 256 + wc * 32 + 8 * fq;
;             float r = 1.f; if (MODE == 1) r = rs[((u.pm >> 3) & 3) * 256 + rl];
;             float ss = 0.f;
; #pragma unroll
;             for (int bj = 0; bj < 2; ++bj) {
;                 f32x4 d0, d1;
;                 if (MODE == 0) { d0 = acc[ai][bj][m][0] * alpha; d1 = acc[ai][bj][m][1] * alpha; }
;                 else {
;                     const u32x4 p = pv[mm][bj];
;                     const f32x4 a0 = acc[ai][bj][m][0] * r, a1 = acc[ai][bj][m][1] * r;
;                     d0 = (f32x4){fsigmoid(a0[0]) * bflo(p.x), fsigmoid(a0[1]) * bfhi(p.x), fsigmoid(a0[2]) * bflo(p.y), fsigmoid(a0[3]) * bfhi(p.y)};
;                     d1 = (f32x4){fsigmoid(a1[0]) * bflo(p.z), fsigmoid(a1[1]) * bfhi(p.z), fsigmoid(a1[2]) * bflo(p.w), fsigmoid(a1[3]) * bfhi(p.w)};
;                 }
;                 const u32x4 H = hv[mm][bj]; const u32x2 L = lv[mm][bj];
;                 const f32x4 o0 = ((f32x4){bflo(H.x), bfhi(H.x), bflo(H.y), bfhi(H.y)} + lo_unpack4(L.x)) + d0;
;                 const f32x4 o1 = ((f32x4){bflo(H.z), bfhi(H.z), bflo(H.w), bfhi(H.w)} + lo_unpack4(L.y)) + d1;
;                 u32x4 w; w.x = cvt_pk_bf16(o0[0], o0[1]); w.y = cvt_pk_bf16(o0[2], o0[3]); w.z = cvt_pk_bf16(o1[0], o1[1]); w.w = cvt_pk_bf16(o1[2], o1[3]);
;                 u32x2 wl; wl.x = lo_pack4(o0[0] - bflo(w.x), o0[1] - bfhi(w.x), o0[2] - bflo(w.y), o0[3] - bfhi(w.y));
;                 wl.y = lo_pack4(o1[0] - bflo(w.z), o1[1] - bfhi(w.z), o1[2] - bflo(w.w), o1[3] - bfhi(w.w));
;                 *GP(u32x4, hout + off + bj * 128) = w; (void)wl;
;                 ss += (o0[0] * o0[0] + o0[1] * o0[1]) + (o0[2] * o0[2] + o0[3] * o0[3]) + (o1[0] * o1[0] + o1[1] * o1[1]) + (o1[2] * o1[2] + o1[3] * o1[3]);
;             }
;             ss += __shfl_xor(ss, 16); ss += __shfl_xor(ss, 32);
;             if (fq == 0) *GP(float, ssp + (size_t)(u.pn * 4 + wc) * TT + row) = ss;
.LBB0_587:
	s_or_b64 exec, exec, s[12:13]
	ds_read_b32 v48, v205 offset:576
	s_waitcnt vmcnt(5)
	v_lshlrev_b32_e32 v60, 16, v72
	v_and_b32_e32 v61, 0xffff0000, v72
	s_waitcnt vmcnt(4)
	v_lshlrev_b32_e32 v52, 16, v76
	v_and_b32_e32 v53, 0xffff0000, v76
	s_waitcnt lgkmcnt(0)
	v_pk_mul_f32 v[44:45], v[44:45], v[48:49] op_sel_hi:[1,0]
	v_pk_mul_f32 v[46:47], v[46:47], v[48:49] op_sel_hi:[1,0]
	v_mul_f32_e32 v44, 0xbfb8aa3b, v44
	v_mul_f32_e32 v45, 0xbfb8aa3b, v45
	v_exp_f32_e32 v44, v44
	v_exp_f32_e32 v45, v45
	v_pk_mul_f32 v[40:41], v[40:41], v[48:49] op_sel_hi:[1,0]
	v_mul_f32_e32 v46, 0xbfb8aa3b, v46
	v_mul_f32_e32 v47, 0xbfb8aa3b, v47
	v_mul_f32_e32 v40, 0xbfb8aa3b, v40
	v_mul_f32_e32 v41, 0xbfb8aa3b, v41
	v_exp_f32_e32 v46, v46
	v_exp_f32_e32 v47, v47
	v_exp_f32_e32 v40, v40
	v_exp_f32_e32 v41, v41
	v_pk_mul_f32 v[42:43], v[42:43], v[48:49] op_sel_hi:[1,0]
	v_add_f32_e32 v44, 1.0, v44
	v_add_f32_e32 v45, 1.0, v45
	v_rcp_f32_e32 v44, v44
	v_rcp_f32_e32 v45, v45
	v_mul_f32_e32 v42, 0xbfb8aa3b, v42
	v_mul_f32_e32 v43, 0xbfb8aa3b, v43
	v_add_f32_e32 v46, 1.0, v46
	v_add_f32_e32 v47, 1.0, v47
	v_add_f32_e32 v40, 1.0, v40
	v_add_f32_e32 v41, 1.0, v41
	v_exp_f32_e32 v42, v42
	v_exp_f32_e32 v43, v43
	v_rcp_f32_e32 v46, v46
	v_rcp_f32_e32 v47, v47
	v_rcp_f32_e32 v40, v40
	v_rcp_f32_e32 v41, v41
	v_pk_add_f32 v[60:61], v[146:147], v[60:61]
	v_pk_mul_f32 v[36:37], v[36:37], v[48:49] op_sel_hi:[1,0]
	v_lshlrev_b32_e32 v62, 16, v73
	v_and_b32_e32 v63, 0xffff0000, v73
	v_pk_fma_f32 v[44:45], v[44:45], v[52:53], v[60:61]
	v_lshlrev_b32_e32 v52, 16, v74
	v_and_b32_e32 v53, 0xffff0000, v74
	v_pk_mul_f32 v[38:39], v[38:39], v[48:49] op_sel_hi:[1,0]
	v_mul_f32_e32 v36, 0xbfb8aa3b, v36
	v_mul_f32_e32 v37, 0xbfb8aa3b, v37
	v_lshlrev_b32_e32 v54, 16, v77
	v_and_b32_e32 v55, 0xffff0000, v77
	v_lshlrev_b32_e32 v56, 16, v78
	v_and_b32_e32 v57, 0xffff0000, v78
	v_add_f32_e32 v42, 1.0, v42
	v_add_f32_e32 v43, 1.0, v43
	v_pk_add_f32 v[62:63], v[144:145], v[62:63]
	v_pk_add_f32 v[52:53], v[146:147], v[52:53]
	v_exp_f32_e32 v36, v36
	v_exp_f32_e32 v37, v37
	v_pk_mul_f32 v[32:33], v[32:33], v[48:49] op_sel_hi:[1,0]
	v_mul_f32_e32 v38, 0xbfb8aa3b, v38
	v_mul_f32_e32 v39, 0xbfb8aa3b, v39
	v_rcp_f32_e32 v42, v42
	v_rcp_f32_e32 v43, v43
	v_pk_fma_f32 v[46:47], v[46:47], v[54:55], v[62:63]
	v_pk_fma_f32 v[52:53], v[40:41], v[56:57], v[52:53]
	v_cvt_pk_bf16_f32 v40, v44, v45
	v_mul_f32_e32 v45, v45, v45
	v_exp_f32_e32 v38, v38
	v_exp_f32_e32 v39, v39
	v_mul_f32_e32 v32, 0xbfb8aa3b, v32
	v_mul_f32_e32 v33, 0xbfb8aa3b, v33
	v_fmac_f32_e32 v45, v44, v44
	v_mul_f32_e32 v44, v47, v47
	v_exp_f32_e32 v32, v32
	v_exp_f32_e32 v33, v33
	v_lshlrev_b32_e32 v54, 16, v75
	v_and_b32_e32 v55, 0xffff0000, v75
	v_fmac_f32_e32 v44, v46, v46
	v_pk_mul_f32 v[34:35], v[34:35], v[48:49] op_sel_hi:[1,0]
	v_lshlrev_b32_e32 v58, 16, v79
	v_and_b32_e32 v59, 0xffff0000, v79
	v_pk_add_f32 v[54:55], v[144:145], v[54:55]
	v_add_f32_e32 v44, v45, v44
	v_mul_f32_e32 v45, v53, v53
	v_add_f32_e32 v36, 1.0, v36
	v_add_f32_e32 v37, 1.0, v37
	v_mul_f32_e32 v34, 0xbfb8aa3b, v34
	v_mul_f32_e32 v35, 0xbfb8aa3b, v35
	v_pk_fma_f32 v[54:55], v[42:43], v[58:59], v[54:55]
	v_fmac_f32_e32 v45, v52, v52
	v_rcp_f32_e32 v36, v36
	v_rcp_f32_e32 v37, v37
	v_add_f32_e32 v38, 1.0, v38
	v_add_f32_e32 v39, 1.0, v39
	v_exp_f32_e32 v34, v34
	v_exp_f32_e32 v35, v35
	v_add_f32_e32 v44, v45, v44
	v_mul_f32_e32 v45, v55, v55
	v_rcp_f32_e32 v38, v38
	v_rcp_f32_e32 v39, v39
	v_add_f32_e32 v32, 1.0, v32
	v_add_f32_e32 v33, 1.0, v33
	v_cvt_pk_bf16_f32 v43, v54, v55
	v_fmac_f32_e32 v45, v54, v54
	v_rcp_f32_e32 v32, v32
	v_rcp_f32_e32 v33, v33
	s_waitcnt vmcnt(3)
	v_lshlrev_b32_e32 v54, 16, v64
	v_and_b32_e32 v55, 0xffff0000, v64
	v_add_f32_e32 v58, v45, v44
	s_waitcnt vmcnt(2)
	v_lshlrev_b32_e32 v44, 16, v68
	v_and_b32_e32 v45, 0xffff0000, v68
	v_lshlrev_b32_e32 v56, 16, v65
	v_and_b32_e32 v57, 0xffff0000, v65
	v_pk_add_f32 v[54:55], v[146:147], v[54:55]
	v_cvt_pk_bf16_f32 v41, v46, v47
	v_lshlrev_b32_e32 v46, 16, v69
	v_and_b32_e32 v47, 0xffff0000, v69
	v_add_f32_e32 v34, 1.0, v34
	v_add_f32_e32 v35, 1.0, v35
	v_pk_add_f32 v[56:57], v[144:145], v[56:57]
	v_pk_fma_f32 v[36:37], v[36:37], v[44:45], v[54:55]
	v_lshlrev_b32_e32 v44, 16, v66
	v_and_b32_e32 v45, 0xffff0000, v66
	v_lshlrev_b32_e32 v48, 16, v70
	v_and_b32_e32 v49, 0xffff0000, v70
	v_rcp_f32_e32 v34, v34
	v_rcp_f32_e32 v35, v35
	v_pk_fma_f32 v[38:39], v[38:39], v[46:47], v[56:57]
	v_pk_add_f32 v[44:45], v[146:147], v[44:45]
	v_lshlrev_b32_e32 v46, 16, v67
	v_pk_fma_f32 v[44:45], v[32:33], v[48:49], v[44:45]
	v_mul_f32_e32 v32, v37, v37
	v_mul_f32_e32 v33, v39, v39
	v_and_b32_e32 v47, 0xffff0000, v67
	v_fmac_f32_e32 v32, v36, v36
	v_fmac_f32_e32 v33, v38, v38
	v_cvt_pk_bf16_f32 v42, v52, v53
	v_lshlrev_b32_e32 v52, 16, v71
	v_and_b32_e32 v53, 0xffff0000, v71
	v_pk_add_f32 v[46:47], v[144:145], v[46:47]
	v_add_f32_e32 v32, v32, v33
	v_mul_f32_e32 v33, v45, v45
	v_pk_fma_f32 v[46:47], v[34:35], v[52:53], v[46:47]
	v_fmac_f32_e32 v33, v44, v44
	v_add_f32_e32 v32, v33, v32
	v_mul_f32_e32 v33, v47, v47
	v_fmac_f32_e32 v33, v46, v46
	v_add_f32_e32 v32, v33, v32
	v_add_u32_e32 v50, s46, v199
	v_add_f32_e32 v35, v58, v32
	v_ashrrev_i32_e32 v51, 31, v50
	v_mov_b32_e32 v52, v35
	s_nop 1
	v_permlane16_swap_b32_e32 v35, v52
	v_lshlrev_b64 v[50:51], 11, v[50:51]
	v_lshl_add_u64 v[50:51], s[14:15], 0, v[50:51]
	v_lshl_add_u64 v[50:51], s[16:17], 1, v[50:51]
	v_lshl_add_u64 v[32:33], v[50:51], 0, s[62:63]
	v_lshl_add_u64 v[48:49], v[32:33], 0, v[168:169]
	s_waitcnt lgkmcnt(0)
	v_add_f32_e32 v32, v35, v52
	v_mov_b32_e32 v33, v32
	s_nop 1
	v_permlane32_swap_b32_e32 v32, v33
	v_cvt_pk_bf16_f32 v34, v36, v37
	v_cvt_pk_bf16_f32 v35, v38, v39
	v_cvt_pk_bf16_f32 v36, v44, v45
	v_cvt_pk_bf16_f32 v37, v46, v47
	global_store_dwordx4 v[48:49], v[40:43], off
	global_store_dwordx4 v[48:49], v[34:37], off offset:256
	s_and_saveexec_b64 s[12:13], s[42:43]
	s_cbranch_execz .LBB0_589
	s_lshl_b32 s20, s25, 2
	s_or_b32 s20, s20, s71
	s_ashr_i32 s21, s20, 31
	s_lshl_b64 s[20:21], s[20:21], 18
	s_add_u32 s20, s65, s20
	s_addc_u32 s21, s70, s21
	s_ashr_i32 s47, s46, 31
	s_waitcnt lgkmcnt(0)
	v_add_f32_e32 v34, v32, v33
	v_lshl_add_u64 v[32:33], s[46:47], 0, v[152:153]
	v_lshl_add_u64 v[32:33], v[32:33], 2, s[20:21]
	global_store_dword v[32:33], v34, off offset:512
; __device__ __forceinline__ float bflo(unsigned w) { return __uint_as_float(w << 16); }
;     template <int NM> __device__ __forceinline__ void round(const AccT& acc, const Unit& u, int ai, int m0, int wr, int wc, int fr, int fq) const {
;     ...
;         for (int mm = 0; mm < NM; ++mm) {
;             const int rl = ai * 128 + wr * 64 + (m0 + mm) * 16 + fr;
;             const size_t off = (size_t)(u.pm * 256 + rl) * DM + u.pn * 256 + wc * 32 + 8 * fq;
; #pragma unroll
;             for (int bj = 0; bj < 2; ++bj) {
;                 hv[mm][bj] = *GP(const u32x4, hin + off + bj * 128); lv[mm][bj] = (u32x2){0u, 0u};
;                 if (MODE == 1) pv[mm][bj] = *GP(const u32x4, proj + off + bj * 128);
;             }
;         }
; #pragma unroll
;         for (int mm = 0; mm < NM; ++mm) {
;             const int m = m0 + mm;
;             const int rl = ai * 128 + wr * 64 + m * 16 + fr; const int row = u.pm * 256 + rl;
;             const size_t off = (size_t)row * DM + u.pn * 256 + wc * 32 + 8 * fq;
;             float r = 1.f; if (MODE == 1) r = rs[((u.pm >> 3) & 3) * 256 + rl];
;             float ss = 0.f;
; #pragma unroll
;             for (int bj = 0; bj < 2; ++bj) {
;                 f32x4 d0, d1;
;                 if (MODE == 0) { d0 = acc[ai][bj][m][0] * alpha; d1 = acc[ai][bj][m][1] * alpha; }
;                 else {
;                     const u32x4 p = pv[mm][bj];
;                     const f32x4 a0 = acc[ai][bj][m][0] * r, a1 = acc[ai][bj][m][1] * r;
;                     d0 = (f32x4){fsigmoid(a0[0]) * bflo(p.x), fsigmoid(a0[1]) * bfhi(p.x), fsigmoid(a0[2]) * bflo(p.y), fsigmoid(a0[3]) * bfhi(p.y)};
;                     d1 = (f32x4){fsigmoid(a1[0]) * bflo(p.z), fsigmoid(a1[1]) * bfhi(p.z), fsigmoid(a1[2]) * bflo(p.w), fsigmoid(a1[3]) * bfhi(p.w)};
;                 }
;                 const u32x4 H = hv[mm][bj]; const u32x2 L = lv[mm][bj];
;                 const f32x4 o0 = ((f32x4){bflo(H.x), bfhi(H.x), bflo(H.y), bfhi(H.y)} + lo_unpack4(L.x)) + d0;
;                 const f32x4 o1 = ((f32x4){bflo(H.z), bfhi(H.z), bflo(H.w), bfhi(H.w)} + lo_unpack4(L.y)) + d1;
;                 u32x4 w; w.x = cvt_pk_bf16(o0[0], o0[1]); w.y = cvt_pk_bf16(o0[2], o0[3]); w.z = cvt_pk_bf16(o1[0], o1[1]); w.w = cvt_pk_bf16(o1[2], o1[3]);
;                 u32x2 wl; wl.x = lo_pack4(o0[0] - bflo(w.x), o0[1] - bfhi(w.x), o0[2] - bflo(w.y), o0[3] - bfhi(w.y));
.LBB0_589:
	s_or_b64 exec, exec, s[12:13]
	v_or_b32_e32 v32, 32, v88
	s_waitcnt lgkmcnt(0)
	v_ashrrev_i32_e32 v33, 31, v32
	v_lshlrev_b64 v[32:33], 10, v[32:33]
	v_lshl_add_u64 v[32:33], v[32:33], 0, v[158:159]
	v_lshlrev_b64 v[32:33], 1, v[32:33]
	v_lshl_add_u64 v[34:35], s[66:67], 0, v[32:33]
	s_mov_b64 s[26:27], 0x3000
	v_lshl_add_u64 v[32:33], v[176:177], 0, s[26:27]
	global_load_dwordx4 v[56:59], v[34:35], off
	global_load_dwordx4 v[60:63], v[32:33], off
	global_load_dwordx4 v[48:51], v[34:35], off offset:256
	global_load_dwordx4 v[52:55], v[32:33], off offset:1024
	v_or_b32_e32 v32, 48, v88
	v_ashrrev_i32_e32 v33, 31, v32
	v_lshlrev_b64 v[32:33], 10, v[32:33]
	v_lshl_add_u64 v[32:33], v[32:33], 0, v[158:159]
	v_lshlrev_b64 v[32:33], 1, v[32:33]
	v_lshl_add_u64 v[34:35], s[66:67], 0, v[32:33]
	s_mov_b64 s[26:27], 0x3800
	v_lshl_add_u64 v[36:37], v[176:177], 0, s[26:27]
	global_load_dwordx4 v[40:43], v[34:35], off
	global_load_dwordx4 v[44:47], v[36:37], off
	s_nop 0
	global_load_dwordx4 v[32:35], v[34:35], off offset:256
	s_nop 0
	global_load_dwordx4 v[36:39], v[36:37], off offset:1024
	ds_read_b32 v64, v205 offset:640
	v_add_u32_e32 v66, s46, v200
	v_ashrrev_i32_e32 v67, 31, v66
	v_lshlrev_b64 v[66:67], 11, v[66:67]
	s_waitcnt lgkmcnt(0)
	v_pk_mul_f32 v[30:31], v[30:31], v[64:65] op_sel_hi:[1,0]
	v_pk_mul_f32 v[28:29], v[28:29], v[64:65] op_sel_hi:[1,0]
	v_pk_mul_f32 v[68:69], v[26:27], v[64:65] op_sel_hi:[1,0]
	v_pk_mul_f32 v[70:71], v[24:25], v[64:65] op_sel_hi:[1,0]
	v_mul_f32_e32 v24, 0xbfb8aa3b, v28
	v_mul_f32_e32 v25, 0xbfb8aa3b, v29
	v_mul_f32_e32 v28, 0xbfb8aa3b, v30
	v_mul_f32_e32 v29, 0xbfb8aa3b, v31
	v_exp_f32_e32 v24, v24
	v_exp_f32_e32 v25, v25
	v_exp_f32_e32 v28, v28
	v_exp_f32_e32 v29, v29
	v_add_f32_e32 v24, 1.0, v24
	v_add_f32_e32 v25, 1.0, v25
	v_rcp_f32_e32 v24, v24
	v_rcp_f32_e32 v25, v25
	v_add_f32_e32 v28, 1.0, v28
	v_add_f32_e32 v29, 1.0, v29
	v_rcp_f32_e32 v28, v28
	v_rcp_f32_e32 v29, v29
	v_pk_mul_f32 v[22:23], v[22:23], v[64:65] op_sel_hi:[1,0]
	v_pk_mul_f32 v[20:21], v[20:21], v[64:65] op_sel_hi:[1,0]
	v_mul_f32_e32 v22, 0xbfb8aa3b, v22
	v_mul_f32_e32 v20, 0xbfb8aa3b, v20
	v_mul_f32_e32 v21, 0xbfb8aa3b, v21
	v_mul_f32_e32 v23, 0xbfb8aa3b, v23
	v_pk_mul_f32 v[18:19], v[18:19], v[64:65] op_sel_hi:[1,0]
	v_pk_mul_f32 v[16:17], v[16:17], v[64:65] op_sel_hi:[1,0]
	v_exp_f32_e32 v20, v20
	v_exp_f32_e32 v21, v21
	v_exp_f32_e32 v22, v22
	v_exp_f32_e32 v23, v23
	v_mul_f32_e32 v16, 0xbfb8aa3b, v16
	v_mul_f32_e32 v17, 0xbfb8aa3b, v17
	v_mul_f32_e32 v18, 0xbfb8aa3b, v18
	v_mul_f32_e32 v19, 0xbfb8aa3b, v19
	v_exp_f32_e32 v16, v16
	v_exp_f32_e32 v17, v17
	v_exp_f32_e32 v18, v18
	v_exp_f32_e32 v19, v19
	v_add_f32_e32 v20, 1.0, v20
	v_add_f32_e32 v21, 1.0, v21
	v_add_f32_e32 v22, 1.0, v22
	v_add_f32_e32 v23, 1.0, v23
	v_rcp_f32_e32 v20, v20
	v_rcp_f32_e32 v21, v21
	v_rcp_f32_e32 v22, v22
	v_rcp_f32_e32 v23, v23
	v_add_f32_e32 v16, 1.0, v16
	v_add_f32_e32 v17, 1.0, v17
	v_add_f32_e32 v18, 1.0, v18
	v_add_f32_e32 v19, 1.0, v19
	v_rcp_f32_e32 v16, v16
	v_rcp_f32_e32 v17, v17
	v_rcp_f32_e32 v18, v18
	v_rcp_f32_e32 v19, v19
	s_waitcnt vmcnt(7)
	v_lshlrev_b32_e32 v72, 16, v56
	s_waitcnt vmcnt(6)
	v_lshlrev_b32_e32 v26, 16, v60
	v_and_b32_e32 v27, 0xffff0000, v60
	v_lshlrev_b32_e32 v30, 16, v61
	v_and_b32_e32 v31, 0xffff0000, v61
	v_mul_f32_e32 v60, 0xbfb8aa3b, v70
	v_mul_f32_e32 v61, 0xbfb8aa3b, v71
	v_lshlrev_b32_e32 v70, 16, v62
	v_and_b32_e32 v71, 0xffff0000, v62
	v_mul_f32_e32 v62, 0xbfb8aa3b, v68
	v_exp_f32_e32 v62, v62
	v_exp_f32_e32 v60, v60
	v_exp_f32_e32 v61, v61
	v_and_b32_e32 v73, 0xffff0000, v56
	v_add_f32_e32 v62, 1.0, v62
	v_rcp_f32_e32 v68, v62
	v_mul_f32_e32 v62, 0xbfb8aa3b, v69
	v_exp_f32_e32 v62, v62
	v_add_f32_e32 v60, 1.0, v60
	v_add_f32_e32 v61, 1.0, v61
	v_rcp_f32_e32 v60, v60
	v_add_f32_e32 v62, 1.0, v62
	v_rcp_f32_e32 v61, v61
	v_rcp_f32_e32 v69, v62
	v_pk_add_f32 v[72:73], v[146:147], v[72:73]
	v_lshlrev_b32_e32 v56, 16, v57
	v_and_b32_e32 v57, 0xffff0000, v57
	v_pk_fma_f32 v[72:73], v[24:25], v[26:27], v[72:73]
	v_lshlrev_b32_e32 v24, 16, v58
	v_and_b32_e32 v25, 0xffff0000, v58
	v_lshlrev_b32_e32 v26, 16, v59
	v_and_b32_e32 v27, 0xffff0000, v59
	v_lshl_add_u64 v[58:59], s[14:15], 0, v[66:67]
	v_lshlrev_b32_e32 v62, 16, v63
	v_and_b32_e32 v63, 0xffff0000, v63
	v_pk_add_f32 v[56:57], v[144:145], v[56:57]
	v_pk_add_f32 v[26:27], v[144:145], v[26:27]
	v_pk_add_f32 v[24:25], v[146:147], v[24:25]
	v_lshl_add_u64 v[58:59], s[16:17], 1, v[58:59]
	v_pk_fma_f32 v[28:29], v[28:29], v[30:31], v[56:57]
	v_pk_fma_f32 v[30:31], v[60:61], v[70:71], v[24:25]
	v_pk_fma_f32 v[56:57], v[68:69], v[62:63], v[26:27]
	v_lshl_add_u64 v[58:59], v[58:59], 0, s[62:63]
	v_cvt_pk_bf16_f32 v24, v72, v73
	v_cvt_pk_bf16_f32 v25, v28, v29
	v_cvt_pk_bf16_f32 v26, v30, v31
	v_cvt_pk_bf16_f32 v27, v56, v57
	v_lshl_add_u64 v[58:59], v[58:59], 0, v[168:169]
	global_store_dwordx4 v[58:59], v[24:27], off
	s_nop 1
	v_mul_f32_e32 v24, v73, v73
	v_mul_f32_e32 v25, v29, v29
	v_fmac_f32_e32 v24, v72, v72
	v_fmac_f32_e32 v25, v28, v28
	v_add_f32_e32 v24, v24, v25
	v_mul_f32_e32 v25, v31, v31
	v_fmac_f32_e32 v25, v30, v30
	v_add_f32_e32 v24, v25, v24
	v_mul_f32_e32 v25, v57, v57
	v_fmac_f32_e32 v25, v56, v56
	v_add_f32_e32 v56, v25, v24
	s_waitcnt vmcnt(5)
	v_lshlrev_b32_e32 v24, 16, v52
	v_and_b32_e32 v25, 0xffff0000, v52
	v_lshlrev_b32_e32 v26, 16, v53
	v_and_b32_e32 v27, 0xffff0000, v53
	v_lshlrev_b32_e32 v52, 16, v48
	v_and_b32_e32 v53, 0xffff0000, v48
	v_lshlrev_b32_e32 v48, 16, v49
	v_and_b32_e32 v49, 0xffff0000, v49
	v_pk_add_f32 v[48:49], v[144:145], v[48:49]
	v_pk_add_f32 v[52:53], v[146:147], v[52:53]
	v_pk_fma_f32 v[22:23], v[22:23], v[26:27], v[48:49]
	v_pk_fma_f32 v[20:21], v[20:21], v[24:25], v[52:53]
	v_lshlrev_b32_e32 v24, 16, v50
	v_and_b32_e32 v25, 0xffff0000, v50
	v_lshlrev_b32_e32 v26, 16, v51
	v_and_b32_e32 v27, 0xffff0000, v51
	v_lshlrev_b32_e32 v28, 16, v54
	v_and_b32_e32 v29, 0xffff0000, v54
	v_lshlrev_b32_e32 v30, 16, v55
	v_and_b32_e32 v31, 0xffff0000, v55
	v_pk_add_f32 v[26:27], v[144:145], v[26:27]
	v_pk_add_f32 v[24:25], v[146:147], v[24:25]
	v_pk_fma_f32 v[26:27], v[18:19], v[30:31], v[26:27]
	v_pk_fma_f32 v[24:25], v[16:17], v[28:29], v[24:25]
	v_cvt_pk_bf16_f32 v16, v20, v21
	v_cvt_pk_bf16_f32 v17, v22, v23
	v_cvt_pk_bf16_f32 v18, v24, v25
	v_cvt_pk_bf16_f32 v19, v26, v27
	global_store_dwordx4 v[58:59], v[16:19], off offset:256
	s_nop 1
	v_mul_f32_e32 v16, v21, v21
	v_mul_f32_e32 v17, v23, v23
	v_fmac_f32_e32 v16, v20, v20
	v_fmac_f32_e32 v17, v22, v22
	v_add_f32_e32 v16, v16, v17
	v_mul_f32_e32 v17, v25, v25
	v_fmac_f32_e32 v17, v24, v24
	v_add_f32_e32 v16, v17, v16
	v_mul_f32_e32 v17, v27, v27
	v_fmac_f32_e32 v17, v26, v26
	v_add_f32_e32 v16, v17, v16
	v_add_f32_e32 v16, v56, v16
	v_mov_b32_e32 v17, v16
	s_nop 1
	v_permlane16_swap_b32_e32 v16, v17
	s_waitcnt lgkmcnt(0)
	v_add_f32_e32 v16, v16, v17
	v_mov_b32_e32 v17, v16
	s_nop 1
	v_permlane32_swap_b32_e32 v16, v17
	s_and_saveexec_b64 s[12:13], s[42:43]
	s_cbranch_execz .LBB0_591
; __device__ __forceinline__ unsigned cvt_pk_bf16(float lo, float hi) { const f32x2 v = {lo, hi}; return __builtin_bit_cast(unsigned, __builtin_convertvector(v, bfx2_t)); }
;     template <int NM> __device__ __forceinline__ void round(const AccT& acc, const Unit& u, int ai, int m0, int wr, int wc, int fr, int fq) const {
;     ...
;             const int rl = ai * 128 + wr * 64 + m * 16 + fr; const int row = u.pm * 256 + rl;
;             const size_t off = (size_t)row * DM + u.pn * 256 + wc * 32 + 8 * fq;
;             float r = 1.f; if (MODE == 1) r = rs[((u.pm >> 3) & 3) * 256 + rl];
;             float ss = 0.f;
; #pragma unroll
;             for (int bj = 0; bj < 2; ++bj) {
;                 f32x4 d0, d1;
;                 if (MODE == 0) { d0 = acc[ai][bj][m][0] * alpha; d1 = acc[ai][bj][m][1] * alpha; }
;                 else {
;                     const u32x4 p = pv[mm][bj];
;                     const f32x4 a0 = acc[ai][bj][m][0] * r, a1 = acc[ai][bj][m][1] * r;
;                     d0 = (f32x4){fsigmoid(a0[0]) * bflo(p.x), fsigmoid(a0[1]) * bfhi(p.x), fsigmoid(a0[2]) * bflo(p.y), fsigmoid(a0[3]) * bfhi(p.y)};
;                     d1 = (f32x4){fsigmoid(a1[0]) * bflo(p.z), fsigmoid(a1[1]) * bfhi(p.z), fsigmoid(a1[2]) * bflo(p.w), fsigmoid(a1[3]) * bfhi(p.w)};
;                 }
;                 const u32x4 H = hv[mm][bj]; const u32x2 L = lv[mm][bj];
;                 const f32x4 o0 = ((f32x4){bflo(H.x), bfhi(H.x), bflo(H.y), bfhi(H.y)} + lo_unpack4(L.x)) + d0;
;                 const f32x4 o1 = ((f32x4){bflo(H.z), bfhi(H.z), bflo(H.w), bfhi(H.w)} + lo_unpack4(L.y)) + d1;
;                 u32x4 w; w.x = cvt_pk_bf16(o0[0], o0[1]); w.y = cvt_pk_bf16(o0[2], o0[3]); w.z = cvt_pk_bf16(o1[0], o1[1]); w.w = cvt_pk_bf16(o1[2], o1[3]);
;                 u32x2 wl; wl.x = lo_pack4(o0[0] - bflo(w.x), o0[1] - bfhi(w.x), o0[2] - bflo(w.y), o0[3] - bfhi(w.y));
;                 wl.y = lo_pack4(o1[0] - bflo(w.z), o1[1] - bfhi(w.z), o1[2] - bflo(w.w), o1[3] - bfhi(w.w));
;                 *GP(u32x4, hout + off + bj * 128) = w; (void)wl;
;                 ss += (o0[0] * o0[0] + o0[1] * o0[1]) + (o0[2] * o0[2] + o0[3] * o0[3]) + (o1[0] * o1[0] + o1[1] * o1[1]) + (o1[2] * o1[2] + o1[3] * o1[3]);
;             }
;             ss += __shfl_xor(ss, 16); ss += __shfl_xor(ss, 32);
;             if (fq == 0) *GP(float, ssp + (size_t)(u.pn * 4 + wc) * TT + row) = ss;
	s_lshl_b32 s20, s25, 2
	s_or_b32 s20, s20, s71
	s_ashr_i32 s21, s20, 31
	s_lshl_b64 s[20:21], s[20:21], 18
	s_add_u32 s20, s65, s20
	s_addc_u32 s21, s70, s21
	s_ashr_i32 s47, s46, 31
	s_waitcnt lgkmcnt(0)
	v_add_f32_e32 v18, v16, v17
	v_lshl_add_u64 v[16:17], s[46:47], 0, v[154:155]
	v_lshl_add_u64 v[16:17], v[16:17], 2, s[20:21]
	global_store_dword v[16:17], v18, off offset:512
.LBB0_591:
	s_or_b64 exec, exec, s[12:13]
	ds_read_b32 v16, v205 offset:704
	s_waitcnt vmcnt(5)
	v_lshlrev_b32_e32 v28, 16, v40
	v_and_b32_e32 v29, 0xffff0000, v40
	s_waitcnt vmcnt(4)
	v_lshlrev_b32_e32 v20, 16, v44
	v_and_b32_e32 v21, 0xffff0000, v44
	s_waitcnt lgkmcnt(0)
	v_pk_mul_f32 v[12:13], v[12:13], v[16:17] op_sel_hi:[1,0]
	v_pk_mul_f32 v[14:15], v[14:15], v[16:17] op_sel_hi:[1,0]
	v_mul_f32_e32 v12, 0xbfb8aa3b, v12
	v_mul_f32_e32 v13, 0xbfb8aa3b, v13
	v_exp_f32_e32 v12, v12
	v_exp_f32_e32 v13, v13
	v_pk_mul_f32 v[8:9], v[8:9], v[16:17] op_sel_hi:[1,0]
	v_mul_f32_e32 v14, 0xbfb8aa3b, v14
	v_mul_f32_e32 v15, 0xbfb8aa3b, v15
	v_mul_f32_e32 v8, 0xbfb8aa3b, v8
	v_mul_f32_e32 v9, 0xbfb8aa3b, v9
	v_exp_f32_e32 v14, v14
	v_exp_f32_e32 v15, v15
	v_exp_f32_e32 v8, v8
	v_exp_f32_e32 v9, v9
	v_pk_mul_f32 v[10:11], v[10:11], v[16:17] op_sel_hi:[1,0]
	v_add_f32_e32 v12, 1.0, v12
	v_add_f32_e32 v13, 1.0, v13
	v_rcp_f32_e32 v12, v12
	v_rcp_f32_e32 v13, v13
	v_mul_f32_e32 v10, 0xbfb8aa3b, v10
	v_mul_f32_e32 v11, 0xbfb8aa3b, v11
	v_add_f32_e32 v14, 1.0, v14
	v_add_f32_e32 v15, 1.0, v15
	v_add_f32_e32 v8, 1.0, v8
	v_add_f32_e32 v9, 1.0, v9
	v_exp_f32_e32 v10, v10
	v_exp_f32_e32 v11, v11
	v_rcp_f32_e32 v14, v14
	v_rcp_f32_e32 v15, v15
	v_rcp_f32_e32 v8, v8
	v_rcp_f32_e32 v9, v9
	v_pk_add_f32 v[28:29], v[146:147], v[28:29]
	v_pk_mul_f32 v[4:5], v[4:5], v[16:17] op_sel_hi:[1,0]
	v_lshlrev_b32_e32 v30, 16, v41
	v_and_b32_e32 v31, 0xffff0000, v41
	v_pk_fma_f32 v[12:13], v[12:13], v[20:21], v[28:29]
	v_lshlrev_b32_e32 v20, 16, v42
	v_and_b32_e32 v21, 0xffff0000, v42
	v_pk_mul_f32 v[6:7], v[6:7], v[16:17] op_sel_hi:[1,0]
	v_mul_f32_e32 v4, 0xbfb8aa3b, v4
	v_mul_f32_e32 v5, 0xbfb8aa3b, v5
	v_lshlrev_b32_e32 v22, 16, v45
	v_and_b32_e32 v23, 0xffff0000, v45
	v_lshlrev_b32_e32 v24, 16, v46
	v_and_b32_e32 v25, 0xffff0000, v46
	v_add_f32_e32 v10, 1.0, v10
	v_add_f32_e32 v11, 1.0, v11
	v_pk_add_f32 v[30:31], v[144:145], v[30:31]
	v_pk_add_f32 v[20:21], v[146:147], v[20:21]
	v_exp_f32_e32 v4, v4
	v_exp_f32_e32 v5, v5
	v_pk_mul_f32 v[0:1], v[0:1], v[16:17] op_sel_hi:[1,0]
	v_mul_f32_e32 v6, 0xbfb8aa3b, v6
	v_mul_f32_e32 v7, 0xbfb8aa3b, v7
	v_rcp_f32_e32 v10, v10
	v_rcp_f32_e32 v11, v11
	v_pk_fma_f32 v[14:15], v[14:15], v[22:23], v[30:31]
	v_pk_fma_f32 v[20:21], v[8:9], v[24:25], v[20:21]
	v_cvt_pk_bf16_f32 v8, v12, v13
	v_mul_f32_e32 v13, v13, v13
	v_exp_f32_e32 v6, v6
	v_exp_f32_e32 v7, v7
	v_mul_f32_e32 v0, 0xbfb8aa3b, v0
	v_mul_f32_e32 v1, 0xbfb8aa3b, v1
	v_fmac_f32_e32 v13, v12, v12
	v_mul_f32_e32 v12, v15, v15
	v_exp_f32_e32 v0, v0
	v_exp_f32_e32 v1, v1
	v_lshlrev_b32_e32 v22, 16, v43
	v_and_b32_e32 v23, 0xffff0000, v43
	v_fmac_f32_e32 v12, v14, v14
	v_pk_mul_f32 v[2:3], v[2:3], v[16:17] op_sel_hi:[1,0]
	v_lshlrev_b32_e32 v26, 16, v47
	v_and_b32_e32 v27, 0xffff0000, v47
	v_pk_add_f32 v[22:23], v[144:145], v[22:23]
	v_add_f32_e32 v12, v13, v12
	v_mul_f32_e32 v13, v21, v21
	v_add_f32_e32 v4, 1.0, v4
	v_add_f32_e32 v5, 1.0, v5
	v_mul_f32_e32 v2, 0xbfb8aa3b, v2
	v_mul_f32_e32 v3, 0xbfb8aa3b, v3
	v_pk_fma_f32 v[22:23], v[10:11], v[26:27], v[22:23]
	v_fmac_f32_e32 v13, v20, v20
	v_rcp_f32_e32 v4, v4
	v_rcp_f32_e32 v5, v5
	v_add_f32_e32 v6, 1.0, v6
	v_add_f32_e32 v7, 1.0, v7
	v_exp_f32_e32 v2, v2
	v_exp_f32_e32 v3, v3
	v_add_f32_e32 v12, v13, v12
	v_mul_f32_e32 v13, v23, v23
	v_rcp_f32_e32 v6, v6
	v_rcp_f32_e32 v7, v7
	v_add_f32_e32 v0, 1.0, v0
	v_add_f32_e32 v1, 1.0, v1
	v_cvt_pk_bf16_f32 v11, v22, v23
	v_fmac_f32_e32 v13, v22, v22
	v_rcp_f32_e32 v0, v0
	v_rcp_f32_e32 v1, v1
	s_waitcnt vmcnt(3)
	v_lshlrev_b32_e32 v22, 16, v32
	v_and_b32_e32 v23, 0xffff0000, v32
	v_add_f32_e32 v26, v13, v12
	s_waitcnt vmcnt(2)
	v_lshlrev_b32_e32 v12, 16, v36
	v_and_b32_e32 v13, 0xffff0000, v36
	v_lshlrev_b32_e32 v24, 16, v33
	v_and_b32_e32 v25, 0xffff0000, v33
	v_pk_add_f32 v[22:23], v[146:147], v[22:23]
	v_cvt_pk_bf16_f32 v9, v14, v15
	v_lshlrev_b32_e32 v14, 16, v37
	v_and_b32_e32 v15, 0xffff0000, v37
	v_add_f32_e32 v2, 1.0, v2
	v_add_f32_e32 v3, 1.0, v3
	v_pk_add_f32 v[24:25], v[144:145], v[24:25]
	v_pk_fma_f32 v[4:5], v[4:5], v[12:13], v[22:23]
	v_lshlrev_b32_e32 v12, 16, v34
	v_and_b32_e32 v13, 0xffff0000, v34
	v_lshlrev_b32_e32 v16, 16, v38
	v_and_b32_e32 v17, 0xffff0000, v38
	v_rcp_f32_e32 v2, v2
	v_rcp_f32_e32 v3, v3
	v_pk_fma_f32 v[6:7], v[6:7], v[14:15], v[24:25]
	v_pk_add_f32 v[12:13], v[146:147], v[12:13]
	v_lshlrev_b32_e32 v14, 16, v35
	v_pk_fma_f32 v[12:13], v[0:1], v[16:17], v[12:13]
	v_mul_f32_e32 v0, v5, v5
	v_mul_f32_e32 v1, v7, v7
	v_and_b32_e32 v15, 0xffff0000, v35
	v_fmac_f32_e32 v0, v4, v4
	v_fmac_f32_e32 v1, v6, v6
	v_cvt_pk_bf16_f32 v10, v20, v21
	v_lshlrev_b32_e32 v20, 16, v39
	v_and_b32_e32 v21, 0xffff0000, v39
	v_pk_add_f32 v[14:15], v[144:145], v[14:15]
	v_add_f32_e32 v0, v0, v1
	v_mul_f32_e32 v1, v13, v13
	v_pk_fma_f32 v[14:15], v[2:3], v[20:21], v[14:15]
	v_fmac_f32_e32 v1, v12, v12
	v_add_f32_e32 v0, v1, v0
	v_mul_f32_e32 v1, v15, v15
	v_fmac_f32_e32 v1, v14, v14
	v_add_f32_e32 v0, v1, v0
	v_add_u32_e32 v18, s46, v201
	v_add_f32_e32 v3, v26, v0
	v_ashrrev_i32_e32 v19, 31, v18
	v_mov_b32_e32 v20, v3
	s_nop 1
	v_permlane16_swap_b32_e32 v3, v20
	v_lshlrev_b64 v[18:19], 11, v[18:19]
	v_lshl_add_u64 v[18:19], s[14:15], 0, v[18:19]
	v_lshl_add_u64 v[18:19], s[16:17], 1, v[18:19]
	v_lshl_add_u64 v[0:1], v[18:19], 0, s[62:63]
	v_lshl_add_u64 v[16:17], v[0:1], 0, v[168:169]
	s_waitcnt lgkmcnt(0)
	v_add_f32_e32 v0, v3, v20
	v_mov_b32_e32 v1, v0
	s_nop 1
	v_permlane32_swap_b32_e32 v0, v1
	v_cvt_pk_bf16_f32 v2, v4, v5
	v_cvt_pk_bf16_f32 v3, v6, v7
	v_cvt_pk_bf16_f32 v4, v12, v13
	v_cvt_pk_bf16_f32 v5, v14, v15
	global_store_dwordx4 v[16:17], v[8:11], off
	global_store_dwordx4 v[16:17], v[2:5], off offset:256
	s_and_saveexec_b64 s[12:13], s[42:43]
	s_cbranch_execz .LBB0_563
	s_lshl_b32 s16, s25, 2
	s_or_b32 s16, s16, s71
	s_ashr_i32 s17, s16, 31
	s_lshl_b64 s[16:17], s[16:17], 18
	s_add_u32 s16, s65, s16
	s_addc_u32 s17, s70, s17
	s_ashr_i32 s47, s46, 31
	s_waitcnt lgkmcnt(0)
	v_add_f32_e32 v2, v0, v1
	v_lshl_add_u64 v[0:1], s[46:47], 0, v[156:157]
	v_lshl_add_u64 v[0:1], v[0:1], 2, s[16:17]
	global_store_dword v[0:1], v2, off offset:512
	s_branch .LBB0_563

; __device__ __forceinline__ float bflo(unsigned w) { return __uint_as_float(w << 16); }
; __device__ __forceinline__ float bfhi(unsigned w) { return __uint_as_float(w & 0xffff0000u); }
; __device__ __forceinline__ f32x4 lo_unpack4(unsigned w) { const f32x2 a = __builtin_amdgcn_cvt_pk_f32_fp8((int)w, false), b = __builtin_amdgcn_cvt_pk_f32_fp8((int)w, true); return (f32x4){a.x, a.y, b.x, b.y} * (1.0f / 512.0f); }
; __device__ void final_norm(const Params& P, const float* ssp, const bf16_t* hi, const unsigned char* lo) {
;     ...
;     for (int row = blockIdx.x * 8 + wave; row < TT; row += G * 8) {
;         float ss = (lane < 16) ? ssp[(size_t)lane * TT + row] : 0.f;
;         u32x2 hv[4]; unsigned lv[4];
; #pragma unroll
;         for (int q = 0; q < 4; ++q) { hv[q] = *(const u32x2*)(hi + (size_t)row * DM + q * 256 + lane * 4); lv[q] = 0u; }
; #pragma unroll
;         for (int o = 32; o >= 1; o >>= 1) ss += __shfl_xor(ss, o);
;         const float r = 1.0f / sqrtf(ss * (1.0f / 1024.0f) + 1e-6f);
; #pragma unroll
;         for (int q = 0; q < 4; ++q) { const f32x4 v = (f32x4){bflo(hv[q].x), bfhi(hv[q].x), bflo(hv[q].y), bfhi(hv[q].y)} + lo_unpack4(lv[q]);
;             *(f32x4*)(out + (size_t)row * DM + q * 256 + lane * 4) = v * r * w[q]; }
;     }
.LBB0_671:
	s_or_b64 exec, exec, s[2:3]
	global_load_dwordx2 v[42:43], v[24:25], off offset:-1024
	global_load_dwordx2 v[44:45], v[24:25], off offset:-512
	global_load_dwordx2 v[46:47], v[24:25], off
	global_load_dwordx2 v[48:49], v[24:25], off offset:512
	s_waitcnt vmcnt(0)
	v_mov_b32_e32 v41, v40
	s_nop 1
	v_permlane32_swap_b32_e32 v40, v41
	v_add_u32_e32 v160, v160, v164
	v_lshl_add_u64 v[20:21], v[20:21], 0, v[22:23]
	v_lshl_add_u64 v[24:25], v[24:25], 0, v[26:27]
	s_waitcnt lgkmcnt(0)
	v_add_f32_e32 v40, v40, v41
	v_mov_b32_e32 v41, v40
	s_nop 1
	v_permlane16_swap_b32_e32 v40, v41
	s_waitcnt lgkmcnt(0)
	v_add_f32_e32 v40, v40, v41
	ds_bpermute_b32 v41, v34, v40
	s_waitcnt lgkmcnt(0)
	v_add_f32_e32 v40, v40, v41
	ds_bpermute_b32 v41, v35, v40
	s_waitcnt lgkmcnt(0)
	v_add_f32_e32 v40, v40, v41
	ds_bpermute_b32 v41, v36, v40
	s_waitcnt lgkmcnt(0)
	v_add_f32_e32 v40, v40, v41
	ds_bpermute_b32 v41, v37, v40
	s_waitcnt lgkmcnt(0)
	v_add_f32_e32 v40, v40, v41
	v_fmamk_f32 v40, v40, 0x3a800000, v38
	v_mul_f32_e32 v41, 0x4f800000, v40
	v_cmp_gt_f32_e32 vcc, s6, v40
	v_lshlrev_b32_e32 v54, 16, v46
	s_nop 0
	v_cndmask_b32_e32 v40, v40, v41, vcc
	v_sqrt_f32_e32 v41, v40
	v_and_b32_e32 v55, 0xffff0000, v46
	v_lshlrev_b32_e32 v46, 16, v47
	v_and_b32_e32 v47, 0xffff0000, v47
	v_add_u32_e32 v50, -1, v41
	v_add_u32_e32 v51, 1, v41
	v_fma_f32 v52, -v50, v41, v40
	v_fma_f32 v53, -v51, v41, v40
	v_cmp_ge_f32_e64 s[2:3], 0, v52
	v_lshlrev_b32_e32 v56, 16, v48
	v_and_b32_e32 v57, 0xffff0000, v48
	v_cndmask_b32_e64 v41, v41, v50, s[2:3]
	v_cmp_lt_f32_e64 s[2:3], 0, v53
	v_lshlrev_b32_e32 v48, 16, v49
	v_and_b32_e32 v49, 0xffff0000, v49
	v_cndmask_b32_e64 v41, v41, v51, s[2:3]
	v_mul_f32_e32 v50, 0x37800000, v41
	v_cndmask_b32_e32 v41, v41, v50, vcc
	v_cmp_class_f32_e32 vcc, v40, v39
	v_pk_add_f32 v[46:47], v[16:17], v[46:47]
	v_pk_add_f32 v[54:55], v[18:19], v[54:55]
	v_cndmask_b32_e32 v40, v41, v40, vcc
	v_div_scale_f32 v41, s[2:3], v40, v40, 1.0
	v_rcp_f32_e32 v50, v41
	v_div_scale_f32 v51, vcc, 1.0, v40, 1.0
	v_pk_add_f32 v[58:59], v[16:17], v[48:49]
	v_fma_f32 v52, -v41, v50, 1.0
	v_fmac_f32_e32 v50, v52, v50
	v_mul_f32_e32 v52, v51, v50
	v_fma_f32 v53, -v41, v52, v51
	v_fmac_f32_e32 v52, v53, v50
	v_fma_f32 v41, -v41, v52, v51
	v_div_fmas_f32 v41, v41, v50, v52
	v_div_fixup_f32 v52, v41, v40, 1.0
	v_lshlrev_b32_e32 v40, 16, v42
	v_and_b32_e32 v41, 0xffff0000, v42
	v_lshlrev_b32_e32 v42, 16, v43
	v_and_b32_e32 v43, 0xffff0000, v43
	v_lshlrev_b32_e32 v50, 16, v44
	v_and_b32_e32 v51, 0xffff0000, v44
	v_lshlrev_b32_e32 v44, 16, v45
	v_and_b32_e32 v45, 0xffff0000, v45
	v_pk_add_f32 v[42:43], v[16:17], v[42:43]
	v_pk_add_f32 v[40:41], v[18:19], v[40:41]
	v_pk_add_f32 v[44:45], v[16:17], v[44:45]
	v_pk_add_f32 v[50:51], v[18:19], v[50:51]
	v_pk_mul_f32 v[40:41], v[40:41], v[52:53] op_sel_hi:[1,0]
	v_pk_mul_f32 v[42:43], v[42:43], v[52:53] op_sel_hi:[1,0]
	v_pk_mul_f32 v[48:49], v[50:51], v[52:53] op_sel_hi:[1,0]
	v_pk_mul_f32 v[44:45], v[44:45], v[52:53] op_sel_hi:[1,0]
	v_pk_mul_f32 v[54:55], v[54:55], v[52:53] op_sel_hi:[1,0]
	v_pk_mul_f32 v[50:51], v[46:47], v[52:53] op_sel_hi:[1,0]
	v_pk_mul_f32 v[42:43], v[2:3], v[42:43]
	v_pk_mul_f32 v[40:41], v[0:1], v[40:41]
	v_pk_mul_f32 v[46:47], v[6:7], v[44:45]
	v_pk_mul_f32 v[44:45], v[4:5], v[48:49]
	v_pk_mul_f32 v[50:51], v[10:11], v[50:51]
	v_pk_mul_f32 v[48:49], v[8:9], v[54:55]
	global_store_dwordx4 v[28:29], v[40:43], off offset:-3072
	global_store_dwordx4 v[28:29], v[44:47], off offset:-2048
	global_store_dwordx4 v[28:29], v[48:51], off offset:-1024
	v_pk_add_f32 v[40:41], v[18:19], v[56:57]
	v_pk_mul_f32 v[42:43], v[58:59], v[52:53] op_sel_hi:[1,0]
	v_pk_mul_f32 v[40:41], v[40:41], v[52:53] op_sel_hi:[1,0]
	v_pk_mul_f32 v[42:43], v[14:15], v[42:43]
	v_pk_mul_f32 v[40:41], v[12:13], v[40:41]
	v_cmp_lt_i32_e32 vcc, s7, v160
	global_store_dwordx4 v[28:29], v[40:43], off
	s_or_b64 s[4:5], vcc, s[4:5]
	v_lshl_add_u64 v[28:29], v[28:29], 0, v[30:31]
	s_andn2_b64 exec, exec, s[4:5]
	s_cbranch_execz .LBB0_674
